# all attention units of the mixer phase: LDS fragment reads hoisted ahead of their MFMAs into free VGPRs (up to 8 in flight), lgkmcnt waits recounted
# baseline (speedup 1.0000x reference)
.LBB0_986:
	s_or_b64 exec, exec, s[12:13]
	s_waitcnt vmcnt(0)
	v_lshlrev_b32_e32 v12, 16, v0
	v_and_b32_e32 v13, 0xffff0000, v0
	s_mov_b32 s12, 0x3e8293ee
	v_lshlrev_b32_e32 v0, 16, v1
	v_and_b32_e32 v1, 0xffff0000, v1
	v_pk_mul_f32 v[14:15], v[0:1], s[12:13] op_sel_hi:[1,0]
	v_lshlrev_b32_e32 v0, 16, v2
	v_and_b32_e32 v1, 0xffff0000, v2
	v_pk_mul_f32 v[12:13], v[12:13], s[12:13] op_sel_hi:[1,0]
	v_pk_mul_f32 v[16:17], v[0:1], s[12:13] op_sel_hi:[1,0]
	v_lshlrev_b32_e32 v0, 16, v3
	v_and_b32_e32 v1, 0xffff0000, v3
	v_pk_mul_f32 v[18:19], v[0:1], s[12:13] op_sel_hi:[1,0]
	v_cvt_pk_bf16_f32 v0, v12, v13
	v_lshlrev_b32_e32 v12, 16, v4
	v_and_b32_e32 v13, 0xffff0000, v4
	v_lshlrev_b32_e32 v4, 16, v5
	v_and_b32_e32 v5, 0xffff0000, v5
	v_cvt_pk_bf16_f32 v1, v14, v15
	v_pk_mul_f32 v[14:15], v[4:5], s[12:13] op_sel_hi:[1,0]
	v_lshlrev_b32_e32 v4, 16, v6
	v_and_b32_e32 v5, 0xffff0000, v6
	v_lshlrev_b32_e32 v9, 4, v11
	v_add_u32_e32 v20, 0x200, v11
	v_cvt_pk_bf16_f32 v2, v16, v17
	v_pk_mul_f32 v[12:13], v[12:13], s[12:13] op_sel_hi:[1,0]
	v_pk_mul_f32 v[16:17], v[4:5], s[12:13] op_sel_hi:[1,0]
	v_lshlrev_b32_e32 v4, 16, v7
	v_and_b32_e32 v5, 0xffff0000, v7
	v_and_b32_e32 v64, 0x70, v9
	v_ashrrev_i32_e32 v9, 3, v11
	v_ashrrev_i32_e32 v45, 3, v20
	v_cvt_pk_bf16_f32 v3, v18, v19
	v_pk_mul_f32 v[18:19], v[4:5], s[12:13] op_sel_hi:[1,0]
	v_cvt_pk_bf16_f32 v4, v12, v13
	v_lshl_add_u64 v[36:37], s[10:11], 0, v[64:65]
	v_add_u32_e32 v12, s14, v9
	v_add_u32_e32 v20, s14, v45
	s_bitset1_b32 s14, 7
	v_cvt_pk_bf16_f32 v6, v16, v17
	v_mad_i64_i32 v[16:17], s[10:11], v12, s93, v[36:37]
	s_or_b32 s96, s8, 0x1200
	v_add_u32_e32 v28, s14, v9
	v_lshl_add_u64 v[12:13], v[16:17], 0, s[96:97]
	s_or_b32 s10, s8, 0x1400
	s_mov_b32 s11, s97
	v_mad_i64_i32 v[24:25], s[12:13], v20, s93, v[36:37]
	v_mad_i64_i32 v[32:33], s[12:13], v28, s93, v[36:37]
	v_cvt_pk_bf16_f32 v5, v14, v15
	global_load_dwordx4 v[12:15], v[12:13], off
	v_lshl_add_u64 v[16:17], v[16:17], 0, s[10:11]
	v_lshl_add_u64 v[20:21], v[24:25], 0, s[96:97]
	v_lshl_add_u64 v[28:29], v[32:33], 0, s[96:97]
	v_add_u32_e32 v38, s14, v45
	v_cvt_pk_bf16_f32 v7, v18, v19
	global_load_dwordx4 v[16:19], v[16:17], off
	v_lshl_add_u64 v[24:25], v[24:25], 0, s[10:11]
	global_load_dwordx4 v[20:23], v[20:21], off
	v_lshl_add_u64 v[32:33], v[32:33], 0, s[10:11]
	global_load_dwordx4 v[28:31], v[28:29], off
	v_mad_i64_i32 v[40:41], s[12:13], v38, s93, v[36:37]
	global_load_dwordx4 v[24:27], v[24:25], off
	v_lshl_add_u64 v[36:37], v[40:41], 0, s[96:97]
	global_load_dwordx4 v[32:35], v[32:33], off
	v_lshl_add_u64 v[40:41], v[40:41], 0, s[10:11]
	global_load_dwordx4 v[36:39], v[36:37], off
	v_add_u32_e32 v44, 0, v64
	global_load_dwordx4 v[40:43], v[40:41], off
	v_mad_u64_u32 v[46:47], s[10:11], v9, s94, v[44:45]
	s_barrier
	v_add_u32_e32 v54, 0, v8
	v_mad_u32_u24 v8, v10, s94, v54
	v_readlane_b32 s12, v255, 21
	v_readlane_b32 s14, v255, 23
	v_readlane_b32 s15, v255, 24
	v_readlane_b32 s13, v255, 22
	s_mov_b32 s14, s12
	s_mov_b32 s15, s12
	s_mov_b32 s13, s12
	s_mov_b32 s16, s12
	v_writelane_b32 v255, s16, 21
	s_cmp_eq_u64 exec, 0
	s_waitcnt vmcnt(7)
	ds_write_b128 v46, v[12:15]
	s_waitcnt vmcnt(6)
	ds_write_b128 v46, v[16:19] offset:18432
	v_mad_u64_u32 v[12:13], s[10:11], v45, s94, v[44:45]
	s_waitcnt vmcnt(5)
	ds_write_b128 v12, v[20:23]
	s_waitcnt vmcnt(3)
	ds_write_b128 v12, v[24:27] offset:18432
	s_waitcnt lgkmcnt(0)
	s_barrier
	ds_write_b128 v46, v[28:31] offset:36864
	s_waitcnt vmcnt(2)
	ds_write_b128 v46, v[32:35] offset:55296
	s_waitcnt vmcnt(1)
	ds_write_b128 v12, v[36:39] offset:36864
	s_waitcnt vmcnt(0)
	ds_write_b128 v12, v[40:43] offset:55296
	s_waitcnt lgkmcnt(0)
	ds_read_b128 v[56:59], v8
	ds_read_b128 v[60:63], v8 offset:64
	ds_read_b128 v[68:71], v8 offset:2304
	ds_read_b128 v[72:75], v8 offset:2368
	ds_read_b128 v[84:87], v8 offset:4608
	ds_read_b128 v[88:91], v8 offset:4672
	ds_read_b128 v[92:95], v8 offset:6976
	v_mov_b64_e32 v[30:31], s[14:15]
	v_mov_b64_e32 v[28:29], s[12:13]
	v_writelane_b32 v255, s17, 22
	v_writelane_b32 v255, s18, 23
	s_nop 0
	s_waitcnt lgkmcnt(6)
	v_mfma_f32_16x16x32_bf16 v[44:47], v[56:59], v[0:3], v[28:31]
	s_nop 0
	s_nop 0
	v_writelane_b32 v255, s19, 24
	s_nop 0
	s_waitcnt lgkmcnt(4)
	v_mfma_f32_16x16x32_bf16 v[48:51], v[68:71], v[0:3], v[28:31]
	s_nop 0
	s_nop 0
	s_nop 0
	s_waitcnt lgkmcnt(2)
	v_mfma_f32_16x16x32_bf16 v[32:35], v[84:87], v[0:3], v[28:31]
	ds_read_b128 v[12:15], v8 offset:6912
	s_nop 0
	v_mfma_f32_16x16x32_bf16 v[16:19], v[60:63], v[4:7], v[28:31]
	v_mfma_f32_16x16x32_bf16 v[20:23], v[72:75], v[4:7], v[28:31]
	s_nop 0
	s_waitcnt lgkmcnt(2)
	v_mfma_f32_16x16x32_bf16 v[24:27], v[88:91], v[4:7], v[28:31]
	s_nop 0
	s_waitcnt lgkmcnt(0)
	v_mfma_f32_16x16x32_bf16 v[36:39], v[12:15], v[0:3], v[28:31]
	v_mov_b32_e32 v12, 0
	s_nop 0
	v_mfma_f32_16x16x32_bf16 v[28:31], v[92:95], v[4:7], v[28:31]
	s_cbranch_scc1 .LBB0_988
	v_max_f32_e32 v8, v45, v45
	v_max_f32_e32 v9, v44, v44
	v_max_f32_e32 v8, v9, v8
	v_max3_f32 v8, v8, v46, v47
	v_max3_f32 v8, v8, v48, v49
	v_max3_f32 v8, v8, v50, v51
	v_max3_f32 v8, v8, v32, v33
	v_max3_f32 v8, v8, v34, v35
	v_max3_f32 v8, v8, v36, v37
	v_max3_f32 v8, v8, v38, v39
	v_mov_b32_e32 v9, v8
	s_nop 1
	v_permlane16_swap_b32_e32 v8, v9
	v_max_f32_e32 v9, v9, v9
	v_max_f32_e32 v8, v8, v8
	v_max_f32_e32 v8, v8, v9
	v_mov_b32_e32 v9, v8
	s_nop 1
	v_permlane32_swap_b32_e32 v8, v9
	v_max_f32_e32 v9, v9, v9
	v_max_f32_e32 v8, v8, v8
	v_max_f32_e32 v8, v8, v9
	v_exp_f32_e64 v9, -v8
	v_add_f32_e32 v79, 0, v8
	v_mul_f32_e32 v12, 0, v9
	v_pk_add_f32 v[44:45], v[44:45], v[8:9] op_sel_hi:[1,0] neg_lo:[0,1] neg_hi:[0,1]
	v_pk_add_f32 v[46:47], v[46:47], v[8:9] op_sel_hi:[1,0] neg_lo:[0,1] neg_hi:[0,1]
	v_pk_add_f32 v[48:49], v[48:49], v[8:9] op_sel_hi:[1,0] neg_lo:[0,1] neg_hi:[0,1]
	v_pk_add_f32 v[50:51], v[50:51], v[8:9] op_sel_hi:[1,0] neg_lo:[0,1] neg_hi:[0,1]
	v_pk_add_f32 v[32:33], v[32:33], v[8:9] op_sel_hi:[1,0] neg_lo:[0,1] neg_hi:[0,1]
	v_pk_add_f32 v[34:35], v[34:35], v[8:9] op_sel_hi:[1,0] neg_lo:[0,1] neg_hi:[0,1]
	v_pk_add_f32 v[36:37], v[36:37], v[8:9] op_sel_hi:[1,0] neg_lo:[0,1] neg_hi:[0,1]
	v_pk_add_f32 v[38:39], v[38:39], v[8:9] op_sel_hi:[1,0] neg_lo:[0,1] neg_hi:[0,1]

.LBB0_991:
	s_waitcnt lgkmcnt(0)
	v_exp_f32_e32 v40, v44
	v_exp_f32_e32 v41, v45
	v_exp_f32_e32 v46, v46
	v_exp_f32_e32 v47, v47
	v_bfe_u32 v9, v11, 4, 2
	v_add_f32_e32 v11, 0, v40
	v_exp_f32_e32 v48, v48
	v_add_f32_e32 v11, v41, v11
	v_exp_f32_e32 v49, v49
	v_add_f32_e32 v11, v46, v11
	v_exp_f32_e32 v50, v50
	v_add_f32_e32 v11, v47, v11
	v_exp_f32_e32 v51, v51
	v_add_f32_e32 v11, v48, v11
	v_exp_f32_e32 v32, v32
	v_lshlrev_b32_e32 v64, 2, v9
	v_lshrrev_b32_e32 v9, 2, v10
	v_mul_u32_u24_e32 v55, 0x90, v10
	v_add_f32_e32 v11, v49, v11
	v_exp_f32_e32 v33, v33
	v_or_b32_e32 v9, v64, v9
	v_lshlrev_b32_e32 v10, 3, v10
	v_add_f32_e32 v11, v50, v11
	v_exp_f32_e32 v34, v34
	v_and_b32_e32 v10, 24, v10
	v_mul_u32_u24_e32 v9, 0x90, v9
	v_add_f32_e32 v11, v51, v11
	v_exp_f32_e32 v35, v35
	v_add3_u32 v82, 0, v10, v9
	ds_read_b64_tr_b16 v[110:111], v82 offset:20736
	ds_read_b64_tr_b16 v[108:109], v82 offset:18432
	ds_read_b64_tr_b16 v[112:113], v82 offset:18464
	ds_read_b64_tr_b16 v[114:115], v82 offset:20768
	ds_read_b64_tr_b16 v[120:121], v82 offset:18496
	ds_read_b64_tr_b16 v[122:123], v82 offset:20800
	ds_read_b64_tr_b16 v[148:149], v82 offset:18528
	ds_read_b64_tr_b16 v[150:151], v82 offset:20832
	v_add_f32_e32 v11, v32, v11
	v_exp_f32_e32 v36, v36
	v_exp_f32_e32 v92, v24
	v_exp_f32_e32 v93, v25
	v_exp_f32_e32 v94, v26
	v_exp_f32_e32 v95, v27
	v_exp_f32_e32 v96, v28
	v_exp_f32_e32 v97, v29
	v_exp_f32_e32 v98, v30
	v_exp_f32_e32 v99, v31
	s_nop 0
	s_nop 0
	s_nop 0
	s_nop 0
	v_add_f32_e32 v11, v33, v11
	v_exp_f32_e32 v37, v37
	v_add_f32_e32 v11, v34, v11
	v_exp_f32_e32 v38, v38
	v_add_f32_e32 v11, v35, v11
	v_exp_f32_e32 v39, v39
	v_add_f32_e32 v11, v36, v11
	v_exp_f32_e32 v63, v16
	v_exp_f32_e32 v85, v17
	v_exp_f32_e32 v86, v18
	v_exp_f32_e32 v87, v19
	v_exp_f32_e32 v88, v20
	v_exp_f32_e32 v89, v21
	v_exp_f32_e32 v90, v22
	v_exp_f32_e32 v91, v23
	v_add_f32_e32 v11, v37, v11
	v_add_f32_e32 v11, v38, v11
	v_add_f32_e32 v11, v39, v11
	v_mov_b32_e32 v13, v12
	v_mov_b32_e32 v14, v12
	v_mov_b32_e32 v15, v12
	v_add_f32_e32 v62, v12, v11
	v_mov_b32_e32 v9, v8
	v_mov_b32_e32 v10, v8
	v_mov_b32_e32 v11, v8
	v_cvt_pk_bf16_f32 v16, v40, v41
	v_cvt_pk_bf16_f32 v17, v46, v47
	v_cvt_pk_bf16_f32 v18, v48, v49
	v_cvt_pk_bf16_f32 v19, v50, v51
	v_cvt_pk_bf16_f32 v20, v63, v85
	v_cvt_pk_bf16_f32 v21, v86, v87
	v_cvt_pk_bf16_f32 v22, v88, v89
	v_cvt_pk_bf16_f32 v23, v90, v91
	v_cvt_pk_bf16_f32 v48, v36, v37
	v_cvt_pk_bf16_f32 v49, v38, v39
	s_nop 0
	s_waitcnt lgkmcnt(4)
	v_mfma_f32_16x16x32_bf16 v[36:39], v[112:115], v[16:19], v[12:15]
	v_cvt_pk_bf16_f32 v46, v32, v33
	v_cvt_pk_bf16_f32 v47, v34, v35
	v_cvt_pk_bf16_f32 v50, v92, v93
	v_mfma_f32_16x16x32_bf16 v[56:59], v[112:115], v[20:23], v[8:11]
	s_nop 0
	s_nop 0
	ds_read_b64_tr_b16 v[112:113], v82 offset:23040
	ds_read_b64_tr_b16 v[114:115], v82 offset:25344
	v_cvt_pk_bf16_f32 v51, v94, v95
	v_cvt_pk_bf16_f32 v52, v96, v97
	s_nop 0
	s_waitcnt lgkmcnt(4)
	v_mfma_f32_16x16x32_bf16 v[66:69], v[120:123], v[16:19], v[12:15]
	v_cvt_pk_bf16_f32 v53, v98, v99
	v_add_u32_e32 v83, v54, v55
	v_mov_b32_e32 v43, v42
	v_mfma_f32_16x16x32_bf16 v[70:73], v[120:123], v[20:23], v[8:11]
	s_nop 0
	s_nop 0
	ds_read_b64_tr_b16 v[120:121], v82 offset:23072
	ds_read_b64_tr_b16 v[122:123], v82 offset:25376
	v_mov_b32_e32 v44, v42
	v_mov_b32_e32 v45, v42
	v_mfma_f32_16x16x32_bf16 v[32:35], v[108:111], v[16:19], v[12:15]
	s_nop 0
	s_waitcnt lgkmcnt(4)
	v_mfma_f32_16x16x32_bf16 v[12:15], v[148:151], v[16:19], v[12:15]
	s_nop 0
	s_nop 0
	v_mfma_f32_16x16x32_bf16 v[24:27], v[108:111], v[20:23], v[8:11]
	ds_read_b64_tr_b16 v[108:109], v82 offset:23104
	ds_read_b64_tr_b16 v[110:111], v82 offset:25408
	v_mfma_f32_16x16x32_bf16 v[74:77], v[148:151], v[20:23], v[8:11]
	ds_read_b64_tr_b16 v[148:149], v82 offset:23136
	ds_read_b64_tr_b16 v[150:151], v82 offset:25440
	s_nop 0
	s_waitcnt lgkmcnt(6)
	v_mfma_f32_16x16x32_bf16 v[30:33], v[112:115], v[46:49], v[32:35]
	v_mfma_f32_16x16x32_bf16 v[26:29], v[112:115], v[50:53], v[24:27]
	s_nop 0
	s_nop 0
	ds_read_b128 v[154:157], v83 offset:9216
	ds_read_b128 v[158:161], v83 offset:9280
	s_nop 0
	s_waitcnt lgkmcnt(6)
	v_mfma_f32_16x16x32_bf16 v[38:41], v[120:123], v[46:49], v[36:39]
	v_mfma_f32_16x16x32_bf16 v[34:37], v[120:123], v[50:53], v[56:59]
	s_nop 0
	s_nop 0
	ds_read_b128 v[122:125], v83 offset:11520
	ds_read_b128 v[162:165], v83 offset:11584
	s_nop 0
	s_nop 0
	s_nop 0
	s_nop 0
	s_waitcnt lgkmcnt(6)
	v_mfma_f32_16x16x32_bf16 v[22:25], v[108:111], v[46:49], v[66:69]
	v_mfma_f32_16x16x32_bf16 v[18:21], v[108:111], v[50:53], v[70:73]
	ds_read_b128 v[110:113], v83 offset:13824
	ds_read_b128 v[168:171], v83 offset:13888
	s_nop 0
	s_waitcnt lgkmcnt(6)
	v_mfma_f32_16x16x32_bf16 v[14:17], v[148:151], v[46:49], v[12:15]
	v_mfma_f32_16x16x32_bf16 v[10:13], v[148:151], v[50:53], v[74:77]
	s_nop 0
	s_nop 0
	ds_read_b128 v[148:151], v83 offset:16192
	s_nop 0
	v_xor_b32_e32 v74, 0x80000000, v79
	v_mov_b32_e32 v75, v74
	v_mov_b32_e32 v76, v74
	v_mov_b32_e32 v77, v74
	s_nop 0
	s_nop 0
	s_waitcnt lgkmcnt(6)
	v_mfma_f32_16x16x32_bf16 v[58:61], v[154:157], v[0:3], v[74:77]
	s_nop 0
	s_waitcnt lgkmcnt(5)
	v_mfma_f32_16x16x32_bf16 v[46:49], v[158:161], v[4:7], v[42:45]
	s_nop 0
	s_nop 0
	s_nop 3
	v_max3_f32 v9, v60, v58, v59
	s_nop 0
	s_waitcnt lgkmcnt(4)
	v_mfma_f32_16x16x32_bf16 v[66:69], v[122:125], v[0:3], v[74:77]
	s_nop 0
	s_waitcnt lgkmcnt(3)
	v_mfma_f32_16x16x32_bf16 v[50:53], v[162:165], v[4:7], v[42:45]
	s_nop 0
	s_nop 0
	s_nop 3
	v_max3_f32 v9, v61, v9, v66
	v_max3_f32 v9, v68, v67, v9
	s_nop 0
	s_waitcnt lgkmcnt(2)
	v_mfma_f32_16x16x32_bf16 v[70:73], v[110:113], v[0:3], v[74:77]
	s_nop 0
	s_waitcnt lgkmcnt(1)
	v_mfma_f32_16x16x32_bf16 v[54:57], v[168:171], v[4:7], v[42:45]
	ds_read_b128 v[100:103], v83 offset:16128
	s_nop 0
	s_nop 3
	v_max3_f32 v9, v70, v69, v9
	v_max3_f32 v9, v72, v71, v9
	s_nop 0
	s_waitcnt lgkmcnt(0)
	v_mfma_f32_16x16x32_bf16 v[74:77], v[100:103], v[0:3], v[74:77]
	s_nop 0
	v_mfma_f32_16x16x32_bf16 v[42:45], v[148:151], v[4:7], v[42:45]
	s_nop 5
	v_max3_f32 v9, v74, v73, v9
	v_max3_f32 v9, v76, v75, v9
	v_max_f32_e32 v100, v77, v77
	v_max_f32_e32 v9, v100, v9
	v_cmp_lt_f32_e32 vcc, s52, v9
	s_cbranch_vccz .LBB0_993
	v_max_f32_e32 v9, v59, v59
	v_max_f32_e32 v100, v58, v58
	v_max_f32_e32 v9, v100, v9
	v_max3_f32 v9, v9, v60, v61
	v_max3_f32 v9, v9, v66, v67
	v_max3_f32 v9, v9, v68, v69
	v_max3_f32 v9, v9, v70, v71
	v_max3_f32 v9, v9, v72, v73
	v_max3_f32 v9, v9, v74, v75
	v_max3_f32 v9, v9, v76, v77
	v_mov_b32_e32 v100, v9
	s_nop 1
	v_permlane16_swap_b32_e32 v9, v100
	v_max_f32_e32 v100, v100, v100
	v_max_f32_e32 v9, v9, v9
	v_max_f32_e32 v9, v9, v100
	v_mov_b32_e32 v100, v9
	s_nop 1
	v_permlane32_swap_b32_e32 v9, v100
	v_max_f32_e32 v100, v100, v100
	v_max_f32_e32 v9, v9, v9
	v_max_f32_e32 v9, v9, v100
	v_cmp_lt_f32_e32 vcc, s52, v9
	s_nop 1
	v_cndmask_b32_e32 v100, 0, v9, vcc
	v_exp_f32_e64 v102, -v100
	v_add_f32_e32 v79, v79, v100
	v_pk_add_f32 v[58:59], v[58:59], v[100:101] op_sel_hi:[1,0] neg_lo:[0,1] neg_hi:[0,1]
	v_pk_add_f32 v[60:61], v[60:61], v[100:101] op_sel_hi:[1,0] neg_lo:[0,1] neg_hi:[0,1]
	v_mul_f32_e32 v62, v62, v102
	v_pk_add_f32 v[66:67], v[66:67], v[100:101] op_sel_hi:[1,0] neg_lo:[0,1] neg_hi:[0,1]
	v_pk_add_f32 v[68:69], v[68:69], v[100:101] op_sel_hi:[1,0] neg_lo:[0,1] neg_hi:[0,1]
	v_pk_add_f32 v[70:71], v[70:71], v[100:101] op_sel_hi:[1,0] neg_lo:[0,1] neg_hi:[0,1]
	v_pk_add_f32 v[72:73], v[72:73], v[100:101] op_sel_hi:[1,0] neg_lo:[0,1] neg_hi:[0,1]
	v_pk_add_f32 v[74:75], v[74:75], v[100:101] op_sel_hi:[1,0] neg_lo:[0,1] neg_hi:[0,1]
	v_pk_add_f32 v[76:77], v[76:77], v[100:101] op_sel_hi:[1,0] neg_lo:[0,1] neg_hi:[0,1]
	v_pk_mul_f32 v[16:17], v[16:17], v[102:103] op_sel_hi:[1,0]
	v_pk_mul_f32 v[14:15], v[14:15], v[102:103] op_sel_hi:[1,0]
	v_pk_mul_f32 v[24:25], v[24:25], v[102:103] op_sel_hi:[1,0]
	v_pk_mul_f32 v[22:23], v[22:23], v[102:103] op_sel_hi:[1,0]
	v_pk_mul_f32 v[40:41], v[40:41], v[102:103] op_sel_hi:[1,0]
	v_pk_mul_f32 v[38:39], v[38:39], v[102:103] op_sel_hi:[1,0]
	v_pk_mul_f32 v[32:33], v[32:33], v[102:103] op_sel_hi:[1,0]
	v_pk_mul_f32 v[30:31], v[30:31], v[102:103] op_sel_hi:[1,0]

.LBB0_995:
	s_waitcnt lgkmcnt(0)
	ds_read_b64_tr_b16 v[106:107], v82 offset:29952
	ds_read_b64_tr_b16 v[104:105], v82 offset:27648
	ds_read_b64_tr_b16 v[110:111], v82 offset:27680
	ds_read_b64_tr_b16 v[112:113], v82 offset:29984
	ds_read_b64_tr_b16 v[122:123], v82 offset:27712
	ds_read_b64_tr_b16 v[124:125], v82 offset:30016
	ds_read_b64_tr_b16 v[150:151], v82 offset:27744
	ds_read_b64_tr_b16 v[152:153], v82 offset:30048
	v_exp_f32_e32 v8, v58
	v_exp_f32_e32 v58, v59
	v_exp_f32_e32 v59, v60
	v_exp_f32_e32 v60, v61
	v_add_f32_e32 v9, 0, v8
	v_exp_f32_e32 v61, v66
	v_add_f32_e32 v9, v58, v9
	v_exp_f32_e32 v63, v67
	v_add_f32_e32 v9, v59, v9
	v_exp_f32_e32 v66, v68
	v_add_f32_e32 v9, v60, v9
	v_exp_f32_e32 v67, v69
	v_add_f32_e32 v9, v61, v9
	v_exp_f32_e32 v68, v70
	v_add_f32_e32 v9, v63, v9
	v_exp_f32_e32 v69, v71
	v_add_f32_e32 v9, v66, v9
	v_exp_f32_e32 v70, v72
	v_add_f32_e32 v9, v67, v9
	v_exp_f32_e32 v71, v73
	v_add_f32_e32 v9, v68, v9
	v_exp_f32_e32 v72, v74
	v_add_f32_e32 v9, v69, v9
	v_exp_f32_e32 v73, v75
	v_add_f32_e32 v9, v70, v9
	v_exp_f32_e32 v74, v76
	v_add_f32_e32 v9, v71, v9
	v_exp_f32_e32 v75, v77
	v_add_f32_e32 v9, v72, v9
	v_add_f32_e32 v9, v73, v9
	v_add_f32_e32 v9, v74, v9
	v_add_f32_e32 v9, v75, v9
	v_add_f32_e32 v85, v62, v9
	v_exp_f32_e32 v89, v48
	v_exp_f32_e32 v94, v53
	v_exp_f32_e32 v95, v54
	v_exp_f32_e32 v96, v55
	v_cvt_pk_bf16_f32 v53, v59, v60
	v_cvt_pk_bf16_f32 v54, v61, v63
	v_cvt_pk_bf16_f32 v55, v66, v67
	v_cvt_pk_bf16_f32 v48, v68, v69
	s_nop 0
	s_nop 0
	s_nop 0
	s_nop 0
	v_exp_f32_e32 v87, v46
	v_exp_f32_e32 v88, v47
	v_exp_f32_e32 v90, v49
	v_exp_f32_e32 v91, v50
	v_exp_f32_e32 v92, v51
	v_exp_f32_e32 v93, v52
	v_exp_f32_e32 v97, v56
	v_exp_f32_e32 v98, v57
	v_cvt_pk_bf16_f32 v52, v8, v58
	v_cvt_pk_bf16_f32 v56, v87, v88
	v_cvt_pk_bf16_f32 v57, v89, v90
	v_cvt_pk_bf16_f32 v58, v91, v92
	v_cvt_pk_bf16_f32 v59, v93, v94
	s_nop 0
	s_waitcnt lgkmcnt(6)
	v_mfma_f32_16x16x32_bf16 v[30:33], v[104:107], v[52:55], v[30:33]
	v_exp_f32_e32 v99, v42
	v_exp_f32_e32 v100, v43
	v_exp_f32_e32 v101, v44
	v_mfma_f32_16x16x32_bf16 v[26:29], v[104:107], v[56:59], v[26:29]
	ds_read_b64_tr_b16 v[104:105], v82 offset:32256
	ds_read_b64_tr_b16 v[106:107], v82 offset:34560
	v_exp_f32_e32 v102, v45
	v_cvt_pk_bf16_f32 v49, v70, v71
	v_cvt_pk_bf16_f32 v50, v72, v73
	s_nop 0
	s_waitcnt lgkmcnt(6)
	v_mfma_f32_16x16x32_bf16 v[60:63], v[110:113], v[56:59], v[34:37]
	s_nop 2
	s_nop 0
	s_nop 0
	v_cvt_pk_bf16_f32 v51, v74, v75
	v_cvt_pk_bf16_f32 v44, v95, v96
	s_nop 0
	s_waitcnt lgkmcnt(4)
	v_mfma_f32_16x16x32_bf16 v[22:25], v[122:125], v[52:55], v[22:25]
	v_cvt_pk_bf16_f32 v45, v97, v98
	v_cvt_pk_bf16_f32 v46, v99, v100
	v_cvt_pk_bf16_f32 v47, v101, v102
	v_mfma_f32_16x16x32_bf16 v[18:21], v[122:125], v[56:59], v[18:21]
	s_nop 0
	s_nop 0
	ds_read_b64_tr_b16 v[120:121], v82 offset:32288
	ds_read_b64_tr_b16 v[122:123], v82 offset:34592
	v_mfma_f32_16x16x32_bf16 v[38:41], v[110:113], v[52:55], v[38:41]
	ds_read_b64_tr_b16 v[108:109], v82 offset:32320
	ds_read_b64_tr_b16 v[110:111], v82 offset:34624
	s_nop 0
	s_waitcnt lgkmcnt(6)
	v_mfma_f32_16x16x32_bf16 v[14:17], v[150:153], v[52:55], v[14:17]
	s_nop 0
	s_nop 0
	v_mfma_f32_16x16x32_bf16 v[8:11], v[150:153], v[56:59], v[10:13]
	s_nop 0
	s_waitcnt lgkmcnt(4)
	v_mfma_f32_16x16x32_bf16 v[32:35], v[104:107], v[48:51], v[30:33]
	v_mfma_f32_16x16x32_bf16 v[28:31], v[104:107], v[44:47], v[26:29]
	s_nop 0
	s_nop 0
	s_nop 0
	s_waitcnt lgkmcnt(2)
	v_mfma_f32_16x16x32_bf16 v[40:43], v[120:123], v[48:51], v[38:41]
	v_mfma_f32_16x16x32_bf16 v[36:39], v[120:123], v[44:47], v[60:63]
	s_nop 0
	s_nop 0
	s_nop 0
	v_xor_b32_e32 v60, 0x80000000, v79
	s_nop 0
	s_waitcnt lgkmcnt(0)
	v_mfma_f32_16x16x32_bf16 v[24:27], v[108:111], v[48:51], v[22:25]
	v_mov_b32_e32 v61, v60
	v_mov_b32_e32 v62, v60
	v_mov_b32_e32 v63, v60
	v_mfma_f32_16x16x32_bf16 v[20:23], v[108:111], v[44:47], v[18:21]
	ds_read_b64_tr_b16 v[52:53], v82 offset:32352
	ds_read_b64_tr_b16 v[54:55], v82 offset:34656
	s_nop 0
	s_waitcnt lgkmcnt(0)
	s_barrier
	s_waitcnt lgkmcnt(0)
	ds_read_b128 v[108:111], v83 offset:36864
	ds_read_b128 v[112:115], v83 offset:36928
	ds_read_b128 v[120:123], v83 offset:39168
	ds_read_b128 v[148:151], v83 offset:39232
	ds_read_b128 v[152:155], v83 offset:41472
	ds_read_b128 v[158:161], v83 offset:41536
	ds_read_b128 v[162:165], v83 offset:43776
	v_mfma_f32_16x16x32_bf16 v[12:15], v[52:55], v[48:51], v[14:17]
	v_mfma_f32_16x16x32_bf16 v[16:19], v[52:55], v[44:47], v[8:11]
	s_nop 0
	s_nop 0
	s_nop 0
	v_xor_b32_e32 v8, 0x80000000, v84
	v_mov_b32_e32 v9, v8
	v_mov_b32_e32 v10, v8
	v_mov_b32_e32 v11, v8
	s_nop 0
	s_waitcnt lgkmcnt(6)
	v_mfma_f32_16x16x32_bf16 v[56:59], v[108:111], v[0:3], v[60:63]
	s_nop 0
	s_waitcnt lgkmcnt(5)
	v_mfma_f32_16x16x32_bf16 v[44:47], v[112:115], v[4:7], v[8:11]
	s_nop 0
	s_nop 0
	s_nop 0
	s_waitcnt lgkmcnt(4)
	v_mfma_f32_16x16x32_bf16 v[66:69], v[120:123], v[0:3], v[60:63]
	s_nop 0
	s_waitcnt lgkmcnt(3)
	v_mfma_f32_16x16x32_bf16 v[48:51], v[148:151], v[4:7], v[8:11]
	s_nop 0
	s_nop 0
	s_nop 0
	s_waitcnt lgkmcnt(2)
	v_mfma_f32_16x16x32_bf16 v[70:73], v[152:155], v[0:3], v[60:63]
	s_nop 0
	s_waitcnt lgkmcnt(1)
	v_mfma_f32_16x16x32_bf16 v[52:55], v[158:161], v[4:7], v[8:11]
	s_nop 0
	ds_read_b128 v[104:107], v83 offset:43840
	s_nop 0
	s_waitcnt lgkmcnt(1)
	v_mfma_f32_16x16x32_bf16 v[74:77], v[162:165], v[0:3], v[60:63]
	s_nop 0
	s_waitcnt lgkmcnt(0)
	v_mfma_f32_16x16x32_bf16 v[60:63], v[104:107], v[4:7], v[8:11]
	s_nop 2
	v_max3_f32 v9, v58, v56, v57
	v_max3_f32 v9, v59, v9, v66
	v_max3_f32 v9, v68, v67, v9
	v_max3_f32 v9, v70, v69, v9
	v_max3_f32 v9, v72, v71, v9
	v_max3_f32 v9, v74, v73, v9
	v_max3_f32 v9, v76, v75, v9
	v_max_f32_e32 v10, v77, v77
	v_max_f32_e32 v9, v10, v9
	v_cmp_lt_f32_e32 vcc, s52, v9
	s_cbranch_vccz .LBB0_997
	v_max_f32_e32 v9, v57, v57
	v_max_f32_e32 v10, v56, v56
	v_max_f32_e32 v9, v10, v9
	v_max3_f32 v9, v9, v58, v59
	v_max3_f32 v9, v9, v66, v67
	v_max3_f32 v9, v9, v68, v69
	v_max3_f32 v9, v9, v70, v71
	v_max3_f32 v9, v9, v72, v73
	v_max3_f32 v9, v9, v74, v75
	v_max3_f32 v9, v9, v76, v77
	v_mov_b32_e32 v10, v9
	s_nop 1
	v_permlane16_swap_b32_e32 v9, v10
	v_max_f32_e32 v10, v10, v10
	v_max_f32_e32 v9, v9, v9
	v_max_f32_e32 v9, v9, v10
	v_mov_b32_e32 v10, v9
	s_nop 1
	v_permlane32_swap_b32_e32 v9, v10
	v_max_f32_e32 v10, v10, v10
	v_max_f32_e32 v9, v9, v9
	v_max_f32_e32 v9, v9, v10
	v_cmp_lt_f32_e32 vcc, s52, v9
	s_nop 1
	v_cndmask_b32_e32 v10, 0, v9, vcc
	v_exp_f32_e64 v104, -v10
	v_add_f32_e32 v79, v79, v10
	v_pk_add_f32 v[56:57], v[56:57], v[10:11] op_sel_hi:[1,0] neg_lo:[0,1] neg_hi:[0,1]
	v_pk_add_f32 v[58:59], v[58:59], v[10:11] op_sel_hi:[1,0] neg_lo:[0,1] neg_hi:[0,1]
	v_mul_f32_e32 v85, v85, v104
	v_pk_add_f32 v[66:67], v[66:67], v[10:11] op_sel_hi:[1,0] neg_lo:[0,1] neg_hi:[0,1]
	v_pk_add_f32 v[68:69], v[68:69], v[10:11] op_sel_hi:[1,0] neg_lo:[0,1] neg_hi:[0,1]
	v_pk_add_f32 v[70:71], v[70:71], v[10:11] op_sel_hi:[1,0] neg_lo:[0,1] neg_hi:[0,1]
	v_pk_add_f32 v[72:73], v[72:73], v[10:11] op_sel_hi:[1,0] neg_lo:[0,1] neg_hi:[0,1]
	v_pk_add_f32 v[74:75], v[74:75], v[10:11] op_sel_hi:[1,0] neg_lo:[0,1] neg_hi:[0,1]
	v_pk_add_f32 v[76:77], v[76:77], v[10:11] op_sel_hi:[1,0] neg_lo:[0,1] neg_hi:[0,1]
	v_pk_mul_f32 v[14:15], v[14:15], v[104:105] op_sel_hi:[1,0]
	v_pk_mul_f32 v[12:13], v[12:13], v[104:105] op_sel_hi:[1,0]
	v_pk_mul_f32 v[26:27], v[26:27], v[104:105] op_sel_hi:[1,0]
	v_pk_mul_f32 v[24:25], v[24:25], v[104:105] op_sel_hi:[1,0]
	v_pk_mul_f32 v[42:43], v[42:43], v[104:105] op_sel_hi:[1,0]
	v_pk_mul_f32 v[40:41], v[40:41], v[104:105] op_sel_hi:[1,0]
	v_pk_mul_f32 v[34:35], v[34:35], v[104:105] op_sel_hi:[1,0]
	v_pk_mul_f32 v[32:33], v[32:33], v[104:105] op_sel_hi:[1,0]

.LBB0_999:
	s_waitcnt lgkmcnt(0)
	ds_read_b64_tr_b16 v[110:111], v82 offset:57600
	ds_read_b64_tr_b16 v[108:109], v82 offset:55296
	ds_read_b64_tr_b16 v[122:123], v82 offset:55328
	ds_read_b64_tr_b16 v[124:125], v82 offset:57632
	ds_read_b64_tr_b16 v[112:113], v82 offset:55360
	ds_read_b64_tr_b16 v[114:115], v82 offset:57664
	ds_read_b64_tr_b16 v[148:149], v82 offset:55392
	ds_read_b64_tr_b16 v[150:151], v82 offset:57696
	v_exp_f32_e32 v56, v56
	v_exp_f32_e32 v57, v57
	v_exp_f32_e32 v58, v58
	v_exp_f32_e32 v59, v59
	v_add_f32_e32 v9, 0, v56
	v_exp_f32_e32 v66, v66
	v_add_f32_e32 v9, v57, v9
	v_exp_f32_e32 v67, v67
	v_add_f32_e32 v9, v58, v9
	v_exp_f32_e32 v68, v68
	v_add_f32_e32 v9, v59, v9
	v_exp_f32_e32 v69, v69
	v_add_f32_e32 v9, v66, v9
	v_exp_f32_e32 v70, v70
	v_add_f32_e32 v9, v67, v9
	v_exp_f32_e32 v71, v71
	v_add_f32_e32 v9, v68, v9
	v_exp_f32_e32 v72, v72
	v_add_f32_e32 v9, v69, v9
	v_exp_f32_e32 v73, v73
	v_add_f32_e32 v9, v70, v9
	v_exp_f32_e32 v98, v74
	v_add_f32_e32 v9, v71, v9
	v_exp_f32_e32 v99, v75
	v_add_f32_e32 v9, v72, v9
	v_exp_f32_e32 v100, v76
	v_add_f32_e32 v9, v73, v9
	v_exp_f32_e32 v101, v77
	v_add_f32_e32 v9, v98, v9
	v_add_f32_e32 v9, v99, v9
	v_add_f32_e32 v9, v100, v9
	v_add_f32_e32 v9, v101, v9
	v_add_f32_e32 v74, v85, v9
	v_exp_f32_e32 v75, v44
	v_exp_f32_e32 v76, v45
	v_exp_f32_e32 v77, v46
	v_exp_f32_e32 v84, v47
	v_exp_f32_e32 v85, v48
	v_exp_f32_e32 v87, v49
	v_exp_f32_e32 v88, v50
	v_exp_f32_e32 v89, v51
	v_exp_f32_e32 v92, v54
	v_exp_f32_e32 v94, v60
	v_exp_f32_e32 v95, v61
	v_exp_f32_e32 v96, v62
	v_exp_f32_e32 v97, v63
	v_cvt_pk_bf16_f32 v54, v66, v67
	s_nop 0
	s_nop 0
	s_nop 0
	v_exp_f32_e32 v90, v52
	v_exp_f32_e32 v91, v53
	v_exp_f32_e32 v93, v55
	v_cvt_pk_bf16_f32 v52, v56, v57
	v_cvt_pk_bf16_f32 v53, v58, v59
	v_cvt_pk_bf16_f32 v55, v68, v69
	v_cvt_pk_bf16_f32 v56, v75, v76
	v_cvt_pk_bf16_f32 v57, v77, v84
	v_cvt_pk_bf16_f32 v58, v85, v87
	v_cvt_pk_bf16_f32 v59, v88, v89
	s_nop 0
	s_waitcnt lgkmcnt(6)
	v_mfma_f32_16x16x32_bf16 v[32:35], v[108:111], v[52:55], v[32:35]
	s_nop 0
	v_cvt_pk_bf16_f32 v44, v70, v71
	v_cvt_pk_bf16_f32 v45, v72, v73
	v_mfma_f32_16x16x32_bf16 v[28:31], v[108:111], v[56:59], v[28:31]
	s_nop 0
	s_nop 0
	ds_read_b64_tr_b16 v[108:109], v82 offset:59904
	ds_read_b64_tr_b16 v[110:111], v82 offset:62208
	v_cvt_pk_bf16_f32 v46, v98, v99
	v_cvt_pk_bf16_f32 v47, v100, v101
	s_nop 0
	s_waitcnt lgkmcnt(4)
	v_mfma_f32_16x16x32_bf16 v[24:27], v[112:115], v[52:55], v[24:27]
	v_cvt_pk_bf16_f32 v48, v90, v91
	v_cvt_pk_bf16_f32 v49, v92, v93
	v_cvt_pk_bf16_f32 v50, v94, v95
	v_mfma_f32_16x16x32_bf16 v[20:23], v[112:115], v[56:59], v[20:23]
	s_nop 0
	s_nop 0
	ds_read_b64_tr_b16 v[112:113], v82 offset:59936
	ds_read_b64_tr_b16 v[114:115], v82 offset:62240
	v_cvt_pk_bf16_f32 v51, v96, v97
	v_xor_b32_e32 v70, 0x80000000, v79
	v_mfma_f32_16x16x32_bf16 v[40:43], v[122:125], v[52:55], v[40:43]
	v_mov_b32_e32 v9, v8
	v_mov_b32_e32 v10, v8
	v_mov_b32_e32 v11, v8
	s_nop 0
	s_waitcnt lgkmcnt(4)
	v_mfma_f32_16x16x32_bf16 v[12:15], v[148:151], v[52:55], v[12:15]
	v_mov_b32_e32 v71, v70
	v_mov_b32_e32 v72, v70
	v_mov_b32_e32 v73, v70
	v_mfma_f32_16x16x32_bf16 v[52:55], v[148:151], v[56:59], v[16:19]
	ds_read_b64_tr_b16 v[148:149], v82 offset:59968
	ds_read_b64_tr_b16 v[150:151], v82 offset:62272
	s_nop 2
	s_nop 0
	s_nop 0
	s_nop 0
	s_waitcnt lgkmcnt(4)
	v_mfma_f32_16x16x32_bf16 v[32:35], v[108:111], v[44:47], v[32:35]
	v_mfma_f32_16x16x32_bf16 v[28:31], v[108:111], v[48:51], v[28:31]
	s_nop 0
	s_nop 0
	ds_read_b64_tr_b16 v[108:109], v82 offset:60000
	ds_read_b64_tr_b16 v[110:111], v82 offset:62304
	v_mfma_f32_16x16x32_bf16 v[36:39], v[122:125], v[56:59], v[36:39]
	ds_read_b128 v[120:123], v83 offset:46080
	ds_read_b128 v[152:155], v83 offset:46144
	s_nop 0
	s_waitcnt lgkmcnt(6)
	v_mfma_f32_16x16x32_bf16 v[40:43], v[112:115], v[44:47], v[40:43]
	v_mfma_f32_16x16x32_bf16 v[36:39], v[112:115], v[48:51], v[36:39]
	s_nop 0
	s_nop 0
	s_nop 0
	s_nop 0
	ds_read_b128 v[112:115], v83 offset:48384
	ds_read_b128 v[156:159], v83 offset:48448
	s_nop 0
	s_waitcnt lgkmcnt(6)
	v_mfma_f32_16x16x32_bf16 v[24:27], v[148:151], v[44:47], v[24:27]
	v_mfma_f32_16x16x32_bf16 v[20:23], v[148:151], v[48:51], v[20:23]
	ds_read_b128 v[148:151], v83 offset:50688
	ds_read_b128 v[162:165], v83 offset:50752
	s_nop 0
	s_waitcnt lgkmcnt(6)
	v_mfma_f32_16x16x32_bf16 v[16:19], v[108:111], v[44:47], v[12:15]
	v_mfma_f32_16x16x32_bf16 v[12:15], v[108:111], v[48:51], v[52:55]
	s_nop 0
	s_nop 0
	ds_read_b128 v[106:109], v83 offset:52992
	ds_read_b128 v[166:169], v83 offset:53056
	s_nop 0
	s_waitcnt lgkmcnt(7)
	v_mfma_f32_16x16x32_bf16 v[56:59], v[120:123], v[0:3], v[70:73]
	s_nop 0
	s_waitcnt lgkmcnt(6)
	v_mfma_f32_16x16x32_bf16 v[44:47], v[152:155], v[4:7], v[8:11]
	s_nop 0
	s_nop 0
	s_nop 0
	s_waitcnt lgkmcnt(5)
	v_mfma_f32_16x16x32_bf16 v[60:63], v[112:115], v[0:3], v[70:73]
	s_nop 0
	s_waitcnt lgkmcnt(4)
	v_mfma_f32_16x16x32_bf16 v[48:51], v[156:159], v[4:7], v[8:11]
	s_nop 0
	s_nop 0
	s_nop 0
	s_waitcnt lgkmcnt(3)
	v_mfma_f32_16x16x32_bf16 v[66:69], v[148:151], v[0:3], v[70:73]
	s_nop 0
	s_waitcnt lgkmcnt(2)
	v_mfma_f32_16x16x32_bf16 v[52:55], v[162:165], v[4:7], v[8:11]
	s_nop 0
	s_nop 0
	s_nop 0
	s_waitcnt lgkmcnt(1)
	v_mfma_f32_16x16x32_bf16 v[70:73], v[106:109], v[0:3], v[70:73]
	s_nop 0
	s_waitcnt lgkmcnt(0)
	v_mfma_f32_16x16x32_bf16 v[0:3], v[166:169], v[4:7], v[8:11]
	v_max3_f32 v4, v58, v56, v57
	v_max3_f32 v4, v59, v4, v60
	v_max3_f32 v4, v62, v61, v4
	v_max3_f32 v4, v66, v63, v4
	v_max3_f32 v4, v68, v67, v4
	s_nop 0
	v_max3_f32 v4, v70, v69, v4
	v_max3_f32 v4, v72, v71, v4
	v_max_f32_e32 v5, v73, v73
	v_max_f32_e32 v4, v5, v4
	v_cmp_lt_f32_e32 vcc, s52, v4
	s_cbranch_vccz .LBB0_1001
	v_max_f32_e32 v4, v57, v57
	v_max_f32_e32 v5, v56, v56
	v_max_f32_e32 v4, v5, v4
	v_max3_f32 v4, v4, v58, v59
	v_max3_f32 v4, v4, v60, v61
	v_max3_f32 v4, v4, v62, v63
	v_max3_f32 v4, v4, v66, v67
	v_max3_f32 v4, v4, v68, v69
	v_max3_f32 v4, v4, v70, v71
	v_max3_f32 v4, v4, v72, v73
	v_mov_b32_e32 v5, v4
	s_nop 1
	v_permlane16_swap_b32_e32 v4, v5
	v_max_f32_e32 v5, v5, v5
	v_max_f32_e32 v4, v4, v4
	v_max_f32_e32 v4, v4, v5
	v_mov_b32_e32 v5, v4
	s_nop 1
	v_permlane32_swap_b32_e32 v4, v5
	v_max_f32_e32 v5, v5, v5
	v_max_f32_e32 v4, v4, v4
	v_max_f32_e32 v4, v4, v5
	v_cmp_lt_f32_e32 vcc, s52, v4
	s_nop 1
	v_cndmask_b32_e32 v4, 0, v4, vcc
	v_exp_f32_e64 v6, -v4
	v_pk_add_f32 v[56:57], v[56:57], v[4:5] op_sel_hi:[1,0] neg_lo:[0,1] neg_hi:[0,1]
	v_pk_add_f32 v[58:59], v[58:59], v[4:5] op_sel_hi:[1,0] neg_lo:[0,1] neg_hi:[0,1]
	v_pk_add_f32 v[60:61], v[60:61], v[4:5] op_sel_hi:[1,0] neg_lo:[0,1] neg_hi:[0,1]
	v_mul_f32_e32 v74, v74, v6
	v_pk_add_f32 v[62:63], v[62:63], v[4:5] op_sel_hi:[1,0] neg_lo:[0,1] neg_hi:[0,1]
	v_pk_add_f32 v[66:67], v[66:67], v[4:5] op_sel_hi:[1,0] neg_lo:[0,1] neg_hi:[0,1]
	v_pk_add_f32 v[68:69], v[68:69], v[4:5] op_sel_hi:[1,0] neg_lo:[0,1] neg_hi:[0,1]
	v_pk_add_f32 v[70:71], v[70:71], v[4:5] op_sel_hi:[1,0] neg_lo:[0,1] neg_hi:[0,1]
	v_pk_add_f32 v[72:73], v[72:73], v[4:5] op_sel_hi:[1,0] neg_lo:[0,1] neg_hi:[0,1]
	v_pk_mul_f32 v[18:19], v[18:19], v[6:7] op_sel_hi:[1,0]
	v_pk_mul_f32 v[16:17], v[16:17], v[6:7] op_sel_hi:[1,0]
	v_pk_mul_f32 v[26:27], v[26:27], v[6:7] op_sel_hi:[1,0]
	v_pk_mul_f32 v[24:25], v[24:25], v[6:7] op_sel_hi:[1,0]
	v_pk_mul_f32 v[42:43], v[42:43], v[6:7] op_sel_hi:[1,0]
	v_pk_mul_f32 v[40:41], v[40:41], v[6:7] op_sel_hi:[1,0]
	v_pk_mul_f32 v[34:35], v[34:35], v[6:7] op_sel_hi:[1,0]
	v_pk_mul_f32 v[32:33], v[32:33], v[6:7] op_sel_hi:[1,0]

.LBB0_1003:
	s_waitcnt lgkmcnt(0)
	v_exp_f32_e32 v5, v56
	v_exp_f32_e32 v7, v57
	v_exp_f32_e32 v9, v58
	v_exp_f32_e32 v10, v59
	v_add_f32_e32 v6, 0, v5
	v_exp_f32_e32 v11, v60
	v_add_f32_e32 v6, v7, v6
	v_exp_f32_e32 v58, v61
	v_add_f32_e32 v6, v9, v6
	v_exp_f32_e32 v59, v62
	v_add_f32_e32 v6, v10, v6
	v_exp_f32_e32 v60, v63
	v_add_f32_e32 v6, v11, v6
	v_exp_f32_e32 v61, v66
	v_add_f32_e32 v6, v58, v6
	v_exp_f32_e32 v62, v67
	v_add_f32_e32 v6, v59, v6
	v_exp_f32_e32 v63, v68
	v_add_f32_e32 v6, v60, v6
	v_exp_f32_e32 v66, v69
	v_add_f32_e32 v6, v61, v6
	v_exp_f32_e32 v67, v70
	v_add_f32_e32 v6, v62, v6
	v_exp_f32_e32 v68, v71
	v_add_f32_e32 v6, v63, v6
	v_exp_f32_e32 v69, v72
	v_add_f32_e32 v6, v66, v6
	v_exp_f32_e32 v70, v73
	v_add_f32_e32 v6, v67, v6
	v_add_f32_e32 v6, v68, v6
	v_add_f32_e32 v6, v69, v6
	v_add_f32_e32 v6, v70, v6
	v_add_f32_e32 v56, v74, v6
	v_exp_f32_e32 v6, v44
	v_exp_f32_e32 v44, v45
	v_exp_f32_e32 v45, v46
	v_exp_f32_e32 v46, v47
	v_add_f32_e32 v8, 0, v6
	v_exp_f32_e32 v47, v48
	v_add_f32_e32 v8, v44, v8
	v_exp_f32_e32 v49, v49
	v_add_f32_e32 v8, v45, v8
	v_exp_f32_e32 v50, v50
	v_add_f32_e32 v8, v46, v8
	v_exp_f32_e32 v51, v51
	v_add_f32_e32 v8, v47, v8
	v_exp_f32_e32 v52, v52
	v_add_f32_e32 v8, v49, v8
	v_exp_f32_e32 v53, v53
	v_add_f32_e32 v8, v50, v8
	v_exp_f32_e32 v54, v54
	v_add_f32_e32 v8, v51, v8
	v_exp_f32_e32 v55, v55
	v_add_f32_e32 v8, v52, v8
	v_exp_f32_e32 v71, v0
	v_add_f32_e32 v8, v53, v8
	v_exp_f32_e32 v72, v1
	v_add_f32_e32 v8, v54, v8
	v_exp_f32_e32 v73, v2
	v_add_f32_e32 v8, v55, v8
	v_exp_f32_e32 v3, v3
	v_add_f32_e32 v0, v71, v8
	v_add_f32_e32 v0, v72, v0
	v_add_f32_e32 v0, v73, v0
	v_add_u32_e32 v57, 0xd800, v82
	ds_read_b64_tr_b16 v[92:93], v57 offset:11520
	ds_read_b64_tr_b16 v[96:97], v57 offset:11552
	ds_read_b64_tr_b16 v[90:91], v82 offset:64512
	ds_read_b64_tr_b16 v[94:95], v82 offset:64544
	ds_read_b64_tr_b16 v[98:99], v82 offset:64576
	ds_read_b64_tr_b16 v[100:101], v57 offset:11584
	ds_read_b64_tr_b16 v[104:105], v82 offset:64608
	ds_read_b64_tr_b16 v[106:107], v57 offset:11616
	v_add_f32_e32 v0, v3, v0
	v_add_f32_e32 v48, v4, v0
	v_cvt_pk_bf16_f32 v9, v9, v10
	v_cvt_pk_bf16_f32 v10, v11, v58
	v_cvt_pk_bf16_f32 v11, v59, v60
	v_cvt_pk_bf16_f32 v45, v45, v46
	v_cvt_pk_bf16_f32 v46, v47, v49
	v_cvt_pk_bf16_f32 v47, v50, v51
	v_cvt_pk_bf16_f32 v4, v61, v62
	v_cvt_pk_bf16_f32 v0, v52, v53
	s_nop 0
	s_nop 0
	s_nop 0
	s_nop 0
	v_cvt_pk_bf16_f32 v8, v5, v7
	v_cvt_pk_bf16_f32 v44, v6, v44
	v_cvt_pk_bf16_f32 v5, v63, v66
	s_nop 0
	s_waitcnt lgkmcnt(5)
	v_mfma_f32_16x16x32_bf16 v[32:35], v[90:93], v[8:11], v[32:35]
	v_cvt_pk_bf16_f32 v6, v67, v68
	v_cvt_pk_bf16_f32 v7, v69, v70
	v_cvt_pk_bf16_f32 v1, v54, v55
	v_mfma_f32_16x16x32_bf16 v[28:31], v[90:93], v[44:47], v[28:31]
	s_nop 0
	s_nop 0
	ds_read_b64_tr_b16 v[88:89], v57 offset:13824
	ds_read_b64_tr_b16 v[90:91], v57 offset:16128
	v_cvt_pk_bf16_f32 v2, v71, v72
	v_cvt_pk_bf16_f32 v3, v73, v3
	s_nop 0
	s_waitcnt lgkmcnt(6)
	v_mfma_f32_16x16x32_bf16 v[40:43], v[94:97], v[8:11], v[40:43]
	s_lshl_b32 s12, s45, 6
	s_ashr_i32 s13, s12, 31
	s_lshl_b64 s[12:13], s[12:13], 2
	v_mfma_f32_16x16x32_bf16 v[36:39], v[94:97], v[44:47], v[36:39]
	v_ashrrev_i32_e32 v79, 31, v78
	s_mov_b32 s9, s97
	s_nop 0
	s_waitcnt lgkmcnt(4)
	v_mfma_f32_16x16x32_bf16 v[58:61], v[98:101], v[8:11], v[24:27]
	v_mfma_f32_16x16x32_bf16 v[50:53], v[98:101], v[44:47], v[20:23]
	s_nop 2
	s_nop 0
	s_nop 0
	s_nop 0
	s_waitcnt lgkmcnt(2)
	v_mfma_f32_16x16x32_bf16 v[66:69], v[104:107], v[8:11], v[16:19]
	s_nop 0
	s_nop 0
	v_mfma_f32_16x16x32_bf16 v[44:47], v[104:107], v[44:47], v[12:15]
	s_nop 2
	ds_read_b64_tr_b16 v[12:13], v57 offset:13856
	ds_read_b64_tr_b16 v[14:15], v57 offset:16160
	s_nop 0
	s_waitcnt lgkmcnt(2)
	v_mfma_f32_16x16x32_bf16 v[16:19], v[88:91], v[4:7], v[32:35]
	v_mfma_f32_16x16x32_bf16 v[24:27], v[88:91], v[0:3], v[28:31]
	s_nop 2
	ds_read_b64_tr_b16 v[28:29], v57 offset:13888
	ds_read_b64_tr_b16 v[30:31], v57 offset:16192
	ds_read_b64_tr_b16 v[32:33], v57 offset:13920
	ds_read_b64_tr_b16 v[34:35], v57 offset:16224
	s_nop 0
	s_waitcnt lgkmcnt(4)
	v_mfma_f32_16x16x32_bf16 v[8:11], v[12:15], v[4:7], v[40:43]
	s_waitcnt lgkmcnt(0)
	s_barrier
	s_load_dwordx2 s[10:11], s[0:1], 0xc8
	v_mfma_f32_16x16x32_bf16 v[12:15], v[12:15], v[0:3], v[36:39]
	s_waitcnt lgkmcnt(0)
	s_add_u32 s10, s10, s12
	v_mfma_f32_16x16x32_bf16 v[20:23], v[28:31], v[4:7], v[58:61]
	s_addc_u32 s11, s11, s13
	v_mfma_f32_16x16x32_bf16 v[28:31], v[28:31], v[0:3], v[50:53]
	v_mfma_f32_16x16x32_bf16 v[4:7], v[32:35], v[4:7], v[66:69]
	s_nop 1
	v_lshlrev_b64 v[52:53], 11, v[78:79]
	v_lshl_add_u64 v[52:53], s[6:7], 0, v[52:53]
	v_lshl_add_u64 v[52:53], v[52:53], 0, s[8:9]
	v_mfma_f32_16x16x32_bf16 v[0:3], v[32:35], v[0:3], v[44:47]
	v_mov_b32_e32 v32, v56
	s_nop 1
	v_permlane16_swap_b32_e32 v56, v32
	v_add_f32_e32 v32, v56, v32
	v_mov_b32_e32 v33, v32
	s_nop 1
	v_permlane32_swap_b32_e32 v32, v33
	v_add_f32_e32 v34, v32, v33
	v_mov_b32_e32 v32, v48
	s_nop 1
	v_permlane16_swap_b32_e32 v48, v32
	v_add_f32_e32 v32, v48, v32
	v_mov_b32_e32 v33, v32
	s_nop 1
	v_permlane32_swap_b32_e32 v32, v33
	v_add_f32_e32 v35, v32, v33
	s_nop 0
	v_add_f32_dpp v32, v81, v81 quad_perm:[1,0,3,2] row_mask:0xf bank_mask:0xf bound_ctrl:1
	v_rcp_f32_e32 v48, v34
	v_rcp_f32_e32 v34, v35
	v_add_f32_dpp v32, v32, v32 quad_perm:[2,3,0,1] row_mask:0xf bank_mask:0xf bound_ctrl:1
	v_lshlrev_b32_e32 v44, 2, v64
	v_lshlrev_b32_e32 v64, 1, v64
	v_add_f32_dpp v32, v32, v32 row_half_mirror row_mask:0xf bank_mask:0xf bound_ctrl:1
	s_mov_b64 s[6:7], 0xf000600
	s_nop 0
	v_add_f32_dpp v32, v32, v32 row_mirror row_mask:0xf bank_mask:0xf bound_ctrl:1
	v_mov_b32_e32 v33, v32
	s_nop 1
	v_permlane16_swap_b32_e32 v32, v33
	v_add_f32_e32 v32, v32, v33
	v_mov_b32_e32 v33, v32
	s_nop 1
	v_permlane32_swap_b32_e32 v32, v33
	v_add_f32_e32 v33, v32, v33
	s_nop 0
	v_add_f32_dpp v32, v80, v80 quad_perm:[1,0,3,2] row_mask:0xf bank_mask:0xf bound_ctrl:1
	v_mul_f32_e32 v33, 0x3fb8aa3b, v33
	v_exp_f32_e32 v191, v33
	v_add_f32_dpp v32, v32, v32 quad_perm:[2,3,0,1] row_mask:0xf bank_mask:0xf bound_ctrl:1
	s_nop 1
	v_add_f32_dpp v32, v32, v32 row_half_mirror row_mask:0xf bank_mask:0xf bound_ctrl:1
	s_nop 1
	v_add_f32_dpp v32, v32, v32 row_mirror row_mask:0xf bank_mask:0xf bound_ctrl:1
	v_mov_b32_e32 v36, v32
	s_nop 1
	v_permlane16_swap_b32_e32 v32, v36
	v_add_f32_e32 v32, v32, v36
	v_mov_b32_e32 v36, v32
	s_nop 1
	v_permlane32_swap_b32_e32 v32, v36
	v_add_f32_e32 v36, v32, v36
	v_cvt_f32_i32_e32 v32, s45
	v_mul_f32_e32 v33, 0x3fb8aa3b, v36
	v_exp_f32_e32 v33, v33
	v_mul_f32_e32 v32, 0xbe99999a, v32
	v_mul_f32_e32 v32, 0x3fb8aa3b, v32
	v_exp_f32_e32 v32, v32
	s_nop 0
	v_mul_f32_e32 v32, 0x3f19999a, v32
	v_pk_add_f32 v[32:33], v[190:191], v[32:33] neg_lo:[0,1] neg_hi:[0,1]
	s_nop 0
	v_add_f32_e32 v33, v32, v33
	v_mul_f32_e32 v50, v34, v33
	v_sub_f32_e32 v49, 1.0, v32
	global_load_dwordx4 v[32:35], v44, s[10:11]
	global_load_dwordx4 v[36:39], v44, s[10:11] offset:64
	global_load_dwordx4 v[40:43], v44, s[10:11] offset:128
	s_nop 0
	global_load_dwordx4 v[44:47], v44, s[10:11] offset:192
	v_pk_mul_f32 v[24:25], v[24:25], v[50:51] op_sel_hi:[1,0]
	v_pk_mul_f32 v[26:27], v[26:27], v[50:51] op_sel_hi:[1,0]
	v_pk_fma_f32 v[16:17], v[16:17], v[48:49], v[24:25] op_sel_hi:[1,0,1] neg_lo:[0,0,1] neg_hi:[0,0,1]
	v_pk_fma_f32 v[18:19], v[18:19], v[48:49], v[26:27] op_sel_hi:[1,0,1] neg_lo:[0,0,1] neg_hi:[0,0,1]
	v_mul_f32_e32 v24, v17, v17
	v_pk_fma_f32 v[24:25], v[16:17], v[16:17], v[24:25] op_sel_hi:[1,1,0]
	v_mul_f32_e32 v26, v19, v19
	v_pk_fma_f32 v[24:25], v[18:19], v[18:19], v[24:25]
	v_pk_mul_f32 v[12:13], v[12:13], v[50:51] op_sel_hi:[1,0]
	v_pk_add_f32 v[24:25], v[26:27], v[24:25] op_sel_hi:[0,1]
	v_pk_mul_f32 v[14:15], v[14:15], v[50:51] op_sel_hi:[1,0]
	v_pk_fma_f32 v[8:9], v[8:9], v[48:49], v[12:13] op_sel_hi:[1,0,1] neg_lo:[0,0,1] neg_hi:[0,0,1]
	v_pk_fma_f32 v[10:11], v[10:11], v[48:49], v[14:15] op_sel_hi:[1,0,1] neg_lo:[0,0,1] neg_hi:[0,0,1]
	v_pk_fma_f32 v[12:13], v[8:9], v[8:9], v[24:25]
	v_mul_f32_e32 v14, v9, v9
	v_pk_add_f32 v[12:13], v[14:15], v[12:13] op_sel_hi:[0,1]
	v_pk_fma_f32 v[12:13], v[10:11], v[10:11], v[12:13]
	v_mul_f32_e32 v14, v11, v11
	v_pk_add_f32 v[12:13], v[14:15], v[12:13] op_sel_hi:[0,1]
	v_pk_mul_f32 v[14:15], v[30:31], v[50:51] op_sel_hi:[1,0]
	v_pk_mul_f32 v[0:1], v[0:1], v[50:51] op_sel_hi:[1,0]
	v_pk_fma_f32 v[14:15], v[22:23], v[48:49], v[14:15] op_sel_hi:[1,0,1] neg_lo:[0,0,1] neg_hi:[0,0,1]
	v_pk_mul_f32 v[22:23], v[28:29], v[50:51] op_sel_hi:[1,0]
	v_pk_mul_f32 v[2:3], v[2:3], v[50:51] op_sel_hi:[1,0]
	v_pk_fma_f32 v[20:21], v[20:21], v[48:49], v[22:23] op_sel_hi:[1,0,1] neg_lo:[0,0,1] neg_hi:[0,0,1]
	v_pk_fma_f32 v[0:1], v[4:5], v[48:49], v[0:1] op_sel_hi:[1,0,1] neg_lo:[0,0,1] neg_hi:[0,0,1]
	v_pk_fma_f32 v[12:13], v[20:21], v[20:21], v[12:13]
	v_mul_f32_e32 v22, v21, v21
	v_pk_add_f32 v[12:13], v[22:23], v[12:13] op_sel_hi:[0,1]
	v_pk_fma_f32 v[12:13], v[14:15], v[14:15], v[12:13]
	v_mul_f32_e32 v22, v15, v15
	v_pk_add_f32 v[12:13], v[22:23], v[12:13] op_sel_hi:[0,1]
	v_pk_fma_f32 v[2:3], v[6:7], v[48:49], v[2:3] op_sel_hi:[1,0,1] neg_lo:[0,0,1] neg_hi:[0,0,1]
	v_pk_fma_f32 v[4:5], v[0:1], v[0:1], v[12:13]
	v_mul_f32_e32 v6, v1, v1
	v_pk_add_f32 v[4:5], v[6:7], v[4:5] op_sel_hi:[0,1]
	v_pk_fma_f32 v[4:5], v[2:3], v[2:3], v[4:5]
	v_mul_f32_e32 v6, v3, v3
	v_pk_add_f32 v[4:5], v[6:7], v[4:5] op_sel_hi:[0,1]
	v_mov_b32_e32 v5, v4
	s_nop 1
	v_permlane16_swap_b32_e32 v4, v5
	v_add_f32_e32 v4, v4, v5
	v_mov_b32_e32 v5, v4
	s_nop 1
	v_permlane32_swap_b32_e32 v4, v5
	v_add_f32_e32 v4, v4, v5
	v_fmamk_f32 v4, v4, 0x3c800000, v229
	v_cmp_gt_f32_e32 vcc, s55, v4
	v_mul_f32_e32 v5, 0x4b800000, v4
	v_lshl_add_u64 v[26:27], v[52:53], 0, v[64:65]
	v_cndmask_b32_e32 v4, v4, v5, vcc
	v_rsq_f32_e32 v4, v4
	v_lshl_add_u64 v[52:53], v[26:27], 0, s[6:7]
	s_mov_b32 s6, 0xf000000
	v_mul_f32_e32 v5, 0x45800000, v4
	v_cndmask_b32_e32 v4, v4, v5, vcc
	v_mul_f32_e32 v4, v49, v4
	v_pk_mul_f32 v[6:7], v[16:17], v[4:5] op_sel_hi:[1,0]
	v_pk_mul_f32 v[12:13], v[18:19], v[4:5] op_sel_hi:[1,0]
	v_pk_mul_f32 v[0:1], v[0:1], v[4:5] op_sel_hi:[1,0]
	v_pk_mul_f32 v[2:3], v[2:3], v[4:5] op_sel_hi:[1,0]
	s_waitcnt vmcnt(3)
	v_pk_mul_f32 v[6:7], v[32:33], v[6:7]
	v_pk_mul_f32 v[12:13], v[34:35], v[12:13]
	v_cvt_pk_bf16_f32 v6, v6, v7
	v_cvt_pk_bf16_f32 v7, v12, v13
	v_add_co_u32_e32 v12, vcc, s6, v26
	s_waitcnt vmcnt(0)
	v_pk_mul_f32 v[0:1], v[44:45], v[0:1]
	v_addc_co_u32_e32 v13, vcc, 0, v27, vcc
	global_store_dwordx2 v[12:13], v[6:7], off offset:1536
	v_pk_mul_f32 v[6:7], v[8:9], v[4:5] op_sel_hi:[1,0]
	v_pk_mul_f32 v[8:9], v[10:11], v[4:5] op_sel_hi:[1,0]
	v_pk_mul_f32 v[6:7], v[36:37], v[6:7]
	v_pk_mul_f32 v[8:9], v[38:39], v[8:9]
	v_cvt_pk_bf16_f32 v6, v6, v7
	v_cvt_pk_bf16_f32 v7, v8, v9
	global_store_dwordx2 v[52:53], v[6:7], off offset:32
	v_pk_mul_f32 v[6:7], v[20:21], v[4:5] op_sel_hi:[1,0]
	v_pk_mul_f32 v[8:9], v[14:15], v[4:5] op_sel_hi:[1,0]
	v_pk_mul_f32 v[6:7], v[40:41], v[6:7]
	v_pk_mul_f32 v[8:9], v[42:43], v[8:9]
	v_pk_mul_f32 v[2:3], v[46:47], v[2:3]
	v_cvt_pk_bf16_f32 v6, v6, v7
	v_cvt_pk_bf16_f32 v7, v8, v9
	v_cvt_pk_bf16_f32 v0, v0, v1
	v_cvt_pk_bf16_f32 v1, v2, v3
	global_store_dwordx2 v[52:53], v[6:7], off offset:64
	global_store_dwordx2 v[52:53], v[0:1], off offset:96
	s_mov_b64 s[6:7], 0

.LBB0_1043:
	s_waitcnt lgkmcnt(0)
	s_add_i32 s7, s6, 0
	v_add_u32_e32 v26, 0, v33
	ds_read_u16 v64, v26
	s_add_i32 s8, s7, 0x10000
	s_nop 0
	v_mov_b32_e32 v17, s8
	ds_read_b64 v[66:67], v17
	s_add_i32 s7, s7, 0x10400
	s_nop 0
	v_mov_b32_e32 v17, s7
	ds_read_b64 v[88:89], v17
	s_nop 0
	s_waitcnt lgkmcnt(2)
	v_lshlrev_b32_e32 v16, 16, v64
	s_add_i32 s6, s6, 8
	s_nop 0
	s_waitcnt lgkmcnt(1)
	v_mul_f32_e32 v20, v66, v16
	v_add_u32_e32 v28, 0, v32
	ds_read_b128 v[92:95], v28
	ds_read_u16 v64, v26 offset:128
	ds_read_b128 v[96:99], v28 offset:128
	s_nop 0
	s_waitcnt lgkmcnt(3)
	v_mul_f32_e32 v24, v88, v16
	s_nop 0
	v_add_u32_e32 v32, 0x100, v32
	v_add_u32_e32 v33, 0x100, v33
	s_cmpk_lg_i32 s6, 0x400
	s_nop 0
	s_waitcnt lgkmcnt(2)
	v_lshlrev_b32_e32 v36, 16, v94
	v_and_b32_e32 v37, 0xffff0000, v94
	v_pk_fma_f32 v[4:5], v[20:21], v[36:37], v[4:5] op_sel_hi:[0,1,1]
	v_pk_fma_f32 v[36:37], v[24:25], v[36:37], v[0:1] op_sel_hi:[0,1,1]
	s_nop 0
	v_lshlrev_b32_e32 v34, 16, v92
	v_and_b32_e32 v35, 0xffff0000, v92
	v_lshlrev_b32_e32 v22, 16, v93
	v_and_b32_e32 v23, 0xffff0000, v93
	v_lshlrev_b32_e32 v38, 16, v95
	v_and_b32_e32 v39, 0xffff0000, v95
	s_nop 0
	s_waitcnt lgkmcnt(1)
	v_lshlrev_b32_e32 v0, 16, v64
	v_pk_fma_f32 v[6:7], v[20:21], v[38:39], v[6:7] op_sel_hi:[0,1,1]
	v_pk_fma_f32 v[18:19], v[20:21], v[22:23], v[10:11] op_sel_hi:[0,1,1]
	v_pk_fma_f32 v[16:17], v[20:21], v[34:35], v[8:9] op_sel_hi:[0,1,1]
	v_pk_fma_f32 v[38:39], v[24:25], v[38:39], v[2:3] op_sel_hi:[0,1,1]
	v_pk_fma_f32 v[22:23], v[24:25], v[22:23], v[14:15] op_sel_hi:[0,1,1]
	v_pk_fma_f32 v[20:21], v[24:25], v[34:35], v[12:13] op_sel_hi:[0,1,1]
	v_mul_f32_e32 v24, v67, v0
	v_mul_f32_e32 v26, v89, v0
	s_nop 0
	s_nop 0
	s_waitcnt lgkmcnt(0)
	v_lshlrev_b32_e32 v28, 16, v96
	v_and_b32_e32 v29, 0xffff0000, v96
	v_lshlrev_b32_e32 v30, 16, v97
	v_and_b32_e32 v31, 0xffff0000, v97
	v_lshlrev_b32_e32 v0, 16, v98
	v_and_b32_e32 v1, 0xffff0000, v98
	v_lshlrev_b32_e32 v2, 16, v99
	v_and_b32_e32 v3, 0xffff0000, v99
	v_pk_fma_f32 v[6:7], v[24:25], v[2:3], v[6:7] op_sel_hi:[0,1,1]
	v_pk_fma_f32 v[4:5], v[24:25], v[0:1], v[4:5] op_sel_hi:[0,1,1]
	v_pk_fma_f32 v[10:11], v[24:25], v[30:31], v[18:19] op_sel_hi:[0,1,1]
	v_pk_fma_f32 v[8:9], v[24:25], v[28:29], v[16:17] op_sel_hi:[0,1,1]
	v_pk_fma_f32 v[2:3], v[26:27], v[2:3], v[38:39] op_sel_hi:[0,1,1]
	v_pk_fma_f32 v[0:1], v[26:27], v[0:1], v[36:37] op_sel_hi:[0,1,1]
	v_pk_fma_f32 v[14:15], v[26:27], v[30:31], v[22:23] op_sel_hi:[0,1,1]
	v_pk_fma_f32 v[12:13], v[26:27], v[28:29], v[20:21] op_sel_hi:[0,1,1]
	s_cbranch_scc1 .LBB0_1043
	s_load_dwordx2 s[6:7], s[0:1], 0xf8
	v_pk_fma_f32 v[8:9], v[24:25], v[28:29], v[16:17] op_sel_hi:[0,1,1]
	v_lshlrev_b32_e32 v16, 6, v27
	v_ashrrev_i32_e32 v17, 31, v16
	v_pk_fma_f32 v[12:13], v[26:27], v[28:29], v[20:21] op_sel_hi:[0,1,1]
	s_waitcnt lgkmcnt(0)
	s_add_u32 s10, s6, 0x3000000
	s_addc_u32 s11, s7, 0
	s_lshl_b32 s6, s17, 3
	s_lshl_b32 s7, s45, 1
	s_add_i32 s6, s7, s6
	s_ashr_i32 s7, s6, 31
	s_lshl_b64 s[8:9], s[6:7], 16
	s_add_u32 s7, s10, s8
	s_addc_u32 s9, s11, s9
	s_lshl_b32 s12, s16, 14
	s_add_u32 s8, s7, s12
	s_addc_u32 s9, s9, 0
	s_or_b32 s6, s6, 1
	s_ashr_i32 s7, s6, 31
	s_lshl_b64 s[6:7], s[6:7], 16
	s_add_u32 s6, s10, s6
	s_addc_u32 s7, s11, s7
	v_lshlrev_b64 v[16:17], 2, v[16:17]
	v_lshlrev_b32_e32 v20, 5, v25
	s_add_u32 s6, s6, s12
	v_pk_fma_f32 v[10:11], v[24:25], v[30:31], v[18:19] op_sel_hi:[0,1,1]
	v_lshl_add_u64 v[18:19], s[8:9], 0, v[16:17]
	v_and_b32_e32 v64, 0xe0, v20
	s_addc_u32 s7, s7, 0
	v_lshl_add_u64 v[18:19], v[18:19], 0, v[64:65]
	v_lshl_add_u64 v[16:17], s[6:7], 0, v[16:17]
	v_pk_fma_f32 v[14:15], v[26:27], v[30:31], v[22:23] op_sel_hi:[0,1,1]
	v_lshl_add_u64 v[16:17], v[16:17], 0, v[64:65]
	global_store_dwordx4 v[18:19], v[8:11], off
	global_store_dwordx4 v[18:19], v[4:7], off offset:16
	global_store_dwordx4 v[16:17], v[12:15], off
	global_store_dwordx4 v[16:17], v[0:3], off offset:16

.LBB0_1046:
	s_andn2_b64 vcc, exec, s[6:7]
	s_cbranch_vccnz .LBB0_1052
	v_mov_b32_e32 v12, v228
	s_load_dwordx2 s[6:7], s[0:1], 0x100
	s_load_dwordx2 s[8:9], s[0:1], 0xb8
	s_lshl_b32 s11, s86, 5
	s_and_b32 s16, s11, 0xff00
	s_bfe_u32 s10, s86, 0x20001
	s_add_i32 s17, s16, 0xffff5e00
	s_waitcnt lgkmcnt(0)
	s_add_u32 s12, s6, 0xae00000
	s_addc_u32 s13, s7, 0
	s_lshl_b32 s14, s86, 7
	s_and_b32 s18, s14, 0x80
	s_lshl_b32 s14, s45, 2
	s_or_b32 s14, s14, s10
	s_ashr_i32 s15, s14, 31
	s_lshl_b64 s[14:15], s[14:15], 2
	s_add_u32 s8, s8, s14
	v_and_b32_e32 v14, 15, v12
	v_ashrrev_i32_e32 v0, 2, v12
	s_addc_u32 s9, s9, s15
	s_or_b32 s14, s18, s17
	v_and_b32_e32 v0, -16, v0
	v_or_b32_e32 v1, s14, v14
	v_bfe_u32 v13, v12, 4, 2
	v_add_u32_e32 v56, v1, v0
	v_mov_b64_e32 v[0:1], s[12:13]
	v_ashrrev_i32_e32 v15, 3, v12
	v_lshlrev_b32_e32 v8, 4, v12
	v_add_u32_e32 v12, 0x200, v12
	v_mad_i64_i32 v[0:1], s[14:15], v56, s93, v[0:1]
	s_lshl_b32 s96, s10, 7
	v_and_b32_e32 v44, 0x70, v8
	v_mov_b32_e32 v45, v65
	v_ashrrev_i32_e32 v57, 3, v12
	v_lshl_add_u64 v[0:1], v[0:1], 0, s[96:97]
	v_lshlrev_b32_e32 v64, 4, v13
	v_lshl_add_u64 v[36:37], s[12:13], 0, v[44:45]
	v_add_u32_e32 v12, s17, v57
	s_add_i32 s16, s16, 0xffff5e80
	v_lshl_add_u64 v[4:5], v[0:1], 0, v[64:65]
	v_add_u32_e32 v8, s17, v15
	v_mad_i64_i32 v[20:21], s[12:13], v12, s93, v[36:37]
	v_add_u32_e32 v12, s16, v15
	global_load_dwordx4 v[0:3], v[4:5], off offset:3072
	s_nop 0
	global_load_dwordx4 v[4:7], v[4:5], off offset:3136
	v_mad_i64_i32 v[8:9], s[12:13], v8, s93, v[36:37]
	s_and_b32 s96, s11, 0x80
	v_mad_i64_i32 v[28:29], s[12:13], v12, s93, v[36:37]
	v_add_u32_e32 v12, s16, v57
	v_lshl_add_u64 v[16:17], v[8:9], 0, s[96:97]
	v_lshl_add_u64 v[24:25], v[20:21], 0, s[96:97]
	v_lshl_add_u64 v[32:33], v[28:29], 0, s[96:97]
	v_mad_i64_i32 v[36:37], s[12:13], v12, s93, v[36:37]
	global_load_dwordx4 v[8:11], v[16:17], off offset:3584
	s_nop 0
	global_load_dwordx4 v[16:19], v[16:17], off offset:3840
	s_nop 0
	global_load_dwordx4 v[20:23], v[24:25], off offset:3584
	s_nop 0
	global_load_dwordx4 v[24:27], v[24:25], off offset:3840
	s_nop 0
	global_load_dwordx4 v[28:31], v[32:33], off offset:3584
	s_nop 0
	global_load_dwordx4 v[32:35], v[32:33], off offset:3840
	v_lshl_add_u64 v[40:41], v[36:37], 0, s[96:97]
	global_load_dwordx4 v[36:39], v[40:41], off offset:3584
	s_nop 0
	global_load_dwordx4 v[40:43], v[40:41], off offset:3840
	s_nop 0
	global_load_dword v66, v65, s[8:9]
	v_add_u32_e32 v12, 0, v44
	s_mov_b32 s8, 0x3e38aa3b
	s_barrier
	v_cmp_eq_u32_e32 vcc, 0, v13
	s_waitcnt vmcnt(0)
	v_lshlrev_b32_e32 v44, 16, v0
	v_and_b32_e32 v45, 0xffff0000, v0
	v_lshlrev_b32_e32 v0, 16, v1
	v_and_b32_e32 v1, 0xffff0000, v1
	v_lshlrev_b32_e32 v46, 16, v2
	v_and_b32_e32 v47, 0xffff0000, v2
	v_lshlrev_b32_e32 v2, 16, v3
	v_and_b32_e32 v3, 0xffff0000, v3
	v_lshlrev_b32_e32 v48, 16, v4
	v_and_b32_e32 v49, 0xffff0000, v4
	v_lshlrev_b32_e32 v4, 16, v5
	v_and_b32_e32 v5, 0xffff0000, v5
	v_lshlrev_b32_e32 v50, 16, v6
	v_and_b32_e32 v51, 0xffff0000, v6
	v_lshlrev_b32_e32 v6, 16, v7
	v_and_b32_e32 v7, 0xffff0000, v7
	v_pk_mul_f32 v[44:45], v[44:45], s[8:9] op_sel_hi:[1,0]
	v_pk_mul_f32 v[52:53], v[0:1], s[8:9] op_sel_hi:[1,0]
	v_pk_mul_f32 v[46:47], v[46:47], s[8:9] op_sel_hi:[1,0]
	v_pk_mul_f32 v[54:55], v[2:3], s[8:9] op_sel_hi:[1,0]
	v_pk_mul_f32 v[58:59], v[48:49], s[8:9] op_sel_hi:[1,0]
	v_pk_mul_f32 v[60:61], v[4:5], s[8:9] op_sel_hi:[1,0]
	v_pk_mul_f32 v[50:51], v[50:51], s[8:9] op_sel_hi:[1,0]
	v_pk_mul_f32 v[62:63], v[6:7], s[8:9] op_sel_hi:[1,0]
	v_mad_u64_u32 v[4:5], s[8:9], v15, s94, v[12:13]
	v_mad_u64_u32 v[6:7], s[8:9], v57, s94, v[12:13]
	v_add_u32_e32 v48, 0, v64
	ds_write_b128 v4, v[8:11]
	ds_write_b128 v4, v[16:19] offset:18432
	ds_write_b128 v6, v[20:23]
	ds_write_b128 v6, v[24:27] offset:18432
	s_waitcnt lgkmcnt(0)
	s_barrier
	v_mad_u32_u24 v12, v14, s94, v48
	ds_write_b128 v4, v[28:31] offset:36864
	ds_write_b128 v4, v[32:35] offset:55296
	ds_write_b128 v6, v[36:39] offset:36864
	ds_write_b128 v6, v[40:43] offset:55296
	s_waitcnt lgkmcnt(0)
	ds_read_b128 v[68:71], v12
	ds_read_b128 v[88:91], v12 offset:64
	ds_read_b128 v[92:95], v12 offset:2304
	ds_read_b128 v[98:101], v12 offset:13824
	ds_read_b128 v[104:107], v12 offset:2368
	ds_read_b128 v[108:111], v12 offset:4608
	ds_read_b128 v[112:115], v12 offset:4672
	ds_read_b128 v[120:123], v12 offset:6912
	v_mul_f32_e32 v15, 0x3fb8aa3b, v66
	v_xor_b32_e32 v8, 0x80000000, v15
	v_cvt_pk_bf16_f32 v0, v44, v45
	v_cvt_pk_bf16_f32 v1, v52, v53
	v_cvt_pk_bf16_f32 v2, v46, v47
	v_cvt_pk_bf16_f32 v3, v54, v55
	v_mov_b32_e32 v9, v8
	v_mov_b32_e32 v10, v8
	v_mov_b32_e32 v11, v8
	s_nop 0
	v_cvt_pk_bf16_f32 v4, v58, v59
	s_nop 0
	s_waitcnt lgkmcnt(7)
	v_mfma_f32_16x16x32_bf16 v[16:19], v[68:71], v[0:3], v[8:11]
	ds_read_b128 v[68:71], v12 offset:6976
	v_cvt_pk_bf16_f32 v5, v60, v61
	v_cvt_pk_bf16_f32 v6, v50, v51
	v_cvt_pk_bf16_f32 v7, v62, v63
	s_nop 0
	s_nop 0
	s_waitcnt lgkmcnt(7)
	v_mfma_f32_16x16x32_bf16 v[44:47], v[88:91], v[4:7], v[16:19]
	ds_read_b128 v[88:91], v12 offset:9216
	s_nop 2
	s_nop 0
	s_nop 0
	s_waitcnt lgkmcnt(7)
	v_mfma_f32_16x16x32_bf16 v[20:23], v[92:95], v[0:3], v[8:11]
	s_nop 0
	ds_read_b128 v[92:95], v12 offset:9280
	s_nop 0
	s_waitcnt lgkmcnt(6)
	v_mfma_f32_16x16x32_bf16 v[40:43], v[104:107], v[4:7], v[20:23]
	s_nop 0
	ds_read_b128 v[104:107], v12 offset:11520
	s_nop 0
	s_waitcnt lgkmcnt(6)
	v_mfma_f32_16x16x32_bf16 v[20:23], v[108:111], v[0:3], v[8:11]
	s_nop 0
	ds_read_b128 v[108:111], v12 offset:11584
	s_nop 0
	s_waitcnt lgkmcnt(6)
	v_mfma_f32_16x16x32_bf16 v[36:39], v[112:115], v[4:7], v[20:23]
	s_nop 0
	ds_read_b128 v[112:115], v12 offset:13888
	s_nop 0
	s_waitcnt lgkmcnt(6)
	v_mfma_f32_16x16x32_bf16 v[20:23], v[120:123], v[0:3], v[8:11]
	s_nop 0
	ds_read_b128 v[122:125], v12 offset:16128
	s_nop 0
	s_waitcnt lgkmcnt(6)
	v_mfma_f32_16x16x32_bf16 v[32:35], v[68:71], v[4:7], v[20:23]
	s_nop 0
	ds_read_b128 v[68:71], v12 offset:16192
	s_nop 0
	s_waitcnt lgkmcnt(6)
	v_mfma_f32_16x16x32_bf16 v[20:23], v[88:91], v[0:3], v[8:11]
	s_nop 0
	s_nop 0
	s_waitcnt lgkmcnt(5)
	v_mfma_f32_16x16x32_bf16 v[28:31], v[92:95], v[4:7], v[20:23]
	s_nop 0
	s_nop 0
	s_waitcnt lgkmcnt(4)
	v_mfma_f32_16x16x32_bf16 v[20:23], v[104:107], v[0:3], v[8:11]
	s_nop 0
	s_waitcnt lgkmcnt(3)
	v_mfma_f32_16x16x32_bf16 v[24:27], v[108:111], v[4:7], v[20:23]
	s_nop 0
	v_mfma_f32_16x16x32_bf16 v[20:23], v[98:101], v[0:3], v[8:11]
	s_nop 0
	s_nop 0
	s_waitcnt lgkmcnt(2)
	v_mfma_f32_16x16x32_bf16 v[20:23], v[112:115], v[4:7], v[20:23]
	s_nop 0
	v_mov_b32_e32 v12, 0
	s_nop 0
	s_waitcnt lgkmcnt(1)
	v_mfma_f32_16x16x32_bf16 v[52:55], v[122:125], v[0:3], v[8:11]
	v_cndmask_b32_e64 v50, 0, 1.0, vcc
	s_nop 1
	v_max3_f32 v9, v46, v44, v45
	v_max3_f32 v9, v47, v9, v40
	v_max3_f32 v9, v42, v41, v9
	v_max3_f32 v9, v36, v43, v9
	v_max3_f32 v9, v38, v37, v9
	v_max3_f32 v9, v32, v39, v9
	v_max3_f32 v9, v34, v33, v9
	v_max3_f32 v9, v28, v35, v9
	v_max3_f32 v9, v30, v29, v9
	s_nop 0
	s_waitcnt lgkmcnt(0)
	v_mfma_f32_16x16x32_bf16 v[16:19], v[68:71], v[4:7], v[52:55]
	v_max3_f32 v9, v24, v31, v9
	v_max3_f32 v9, v26, v25, v9
	v_max3_f32 v9, v20, v27, v9
	v_max3_f32 v9, v22, v21, v9
	s_nop 3
	v_max3_f32 v9, v16, v23, v9
	v_max3_f32 v9, v18, v17, v9
	v_max_f32_e32 v10, v19, v19
	v_max_f32_e32 v9, v10, v9
	v_cmp_lt_f32_e32 vcc, s52, v9
	s_cbranch_vccz .LBB0_1049
	v_max_f32_e32 v8, v45, v45
	v_max_f32_e32 v9, v44, v44
	v_max_f32_e32 v8, v9, v8
	v_max3_f32 v8, v8, v46, v47
	v_max3_f32 v8, v8, v40, v41
	v_max3_f32 v8, v8, v42, v43
	v_max3_f32 v8, v8, v36, v37
	v_max3_f32 v8, v8, v38, v39
	v_max3_f32 v8, v8, v32, v33
	v_max3_f32 v8, v8, v34, v35
	v_max3_f32 v8, v8, v28, v29
	v_max3_f32 v8, v8, v30, v31
	v_max3_f32 v8, v8, v24, v25
	v_max3_f32 v8, v8, v26, v27
	v_max3_f32 v8, v8, v20, v21
	v_max3_f32 v8, v8, v22, v23
	v_max3_f32 v8, v8, v16, v17
	v_max3_f32 v8, v8, v18, v19
	v_mov_b32_e32 v9, v8
	s_nop 1
	v_permlane16_swap_b32_e32 v8, v9
	v_max_f32_e32 v9, v9, v9
	v_max_f32_e32 v8, v8, v8
	v_max_f32_e32 v8, v8, v9
	v_mov_b32_e32 v9, v8
	s_nop 1
	v_permlane32_swap_b32_e32 v8, v9
	v_max_f32_e32 v9, v9, v9
	v_max_f32_e32 v8, v8, v8
	v_max_f32_e32 v8, v8, v9
	v_cmp_lt_f32_e32 vcc, s52, v8
	s_nop 1
	v_cndmask_b32_e32 v8, 0, v8, vcc
	v_exp_f32_e64 v9, -v8
	v_add_f32_e32 v10, v15, v8
	v_mul_f32_e32 v50, v50, v9
	v_pk_add_f32 v[44:45], v[44:45], v[8:9] op_sel_hi:[1,0] neg_lo:[0,1] neg_hi:[0,1]
	v_pk_add_f32 v[46:47], v[46:47], v[8:9] op_sel_hi:[1,0] neg_lo:[0,1] neg_hi:[0,1]
	v_pk_add_f32 v[40:41], v[40:41], v[8:9] op_sel_hi:[1,0] neg_lo:[0,1] neg_hi:[0,1]
	v_pk_add_f32 v[42:43], v[42:43], v[8:9] op_sel_hi:[1,0] neg_lo:[0,1] neg_hi:[0,1]
	v_pk_add_f32 v[36:37], v[36:37], v[8:9] op_sel_hi:[1,0] neg_lo:[0,1] neg_hi:[0,1]
	v_pk_add_f32 v[38:39], v[38:39], v[8:9] op_sel_hi:[1,0] neg_lo:[0,1] neg_hi:[0,1]
	v_pk_add_f32 v[32:33], v[32:33], v[8:9] op_sel_hi:[1,0] neg_lo:[0,1] neg_hi:[0,1]
	v_pk_add_f32 v[34:35], v[34:35], v[8:9] op_sel_hi:[1,0] neg_lo:[0,1] neg_hi:[0,1]
	v_pk_add_f32 v[28:29], v[28:29], v[8:9] op_sel_hi:[1,0] neg_lo:[0,1] neg_hi:[0,1]
	v_pk_add_f32 v[30:31], v[30:31], v[8:9] op_sel_hi:[1,0] neg_lo:[0,1] neg_hi:[0,1]
	v_pk_add_f32 v[24:25], v[24:25], v[8:9] op_sel_hi:[1,0] neg_lo:[0,1] neg_hi:[0,1]
	v_pk_add_f32 v[26:27], v[26:27], v[8:9] op_sel_hi:[1,0] neg_lo:[0,1] neg_hi:[0,1]
	v_pk_add_f32 v[20:21], v[20:21], v[8:9] op_sel_hi:[1,0] neg_lo:[0,1] neg_hi:[0,1]
	v_pk_add_f32 v[22:23], v[22:23], v[8:9] op_sel_hi:[1,0] neg_lo:[0,1] neg_hi:[0,1]
	v_pk_add_f32 v[16:17], v[16:17], v[8:9] op_sel_hi:[1,0] neg_lo:[0,1] neg_hi:[0,1]
	v_pk_add_f32 v[18:19], v[18:19], v[8:9] op_sel_hi:[1,0] neg_lo:[0,1] neg_hi:[0,1]
	v_mul_f32_e32 v12, 0, v9
	v_xor_b32_e32 v8, 0x80000000, v10
.LBB0_1049:
	s_waitcnt lgkmcnt(0)
	v_exp_f32_e32 v44, v44
	v_exp_f32_e32 v45, v45
	v_exp_f32_e32 v46, v46
	v_exp_f32_e32 v47, v47
	v_add_f32_e32 v51, 0, v44
	v_exp_f32_e32 v40, v40
	v_add_f32_e32 v51, v45, v51
	v_exp_f32_e32 v41, v41
	v_add_f32_e32 v51, v46, v51
	v_exp_f32_e32 v42, v42
	v_add_f32_e32 v51, v47, v51
	v_exp_f32_e32 v43, v43
	v_add_f32_e32 v51, v40, v51
	v_exp_f32_e32 v36, v36
	v_add_f32_e32 v51, v41, v51
	v_exp_f32_e32 v37, v37
	v_add_f32_e32 v51, v42, v51
	v_exp_f32_e32 v38, v38
	v_add_f32_e32 v51, v43, v51
	v_exp_f32_e32 v39, v39
	v_add_f32_e32 v51, v51, v36
	v_exp_f32_e32 v32, v32
	v_add_f32_e32 v51, v37, v51
	v_exp_f32_e32 v33, v33
	v_add_f32_e32 v51, v38, v51
	v_exp_f32_e32 v34, v34
	v_add_f32_e32 v51, v39, v51
	v_exp_f32_e32 v35, v35
	v_add_f32_e32 v51, v32, v51
	v_exp_f32_e32 v28, v28
	v_add_f32_e32 v51, v33, v51
	v_exp_f32_e32 v29, v29
	v_add_f32_e32 v51, v34, v51
	v_exp_f32_e32 v30, v30
	v_add_f32_e32 v51, v35, v51
	v_exp_f32_e32 v31, v31
	v_add_f32_e32 v51, v28, v51
	v_exp_f32_e32 v52, v24
	v_add_f32_e32 v51, v29, v51
	v_add_f32_e32 v51, v30, v51
	v_add_f32_e32 v51, v31, v51
	v_add_f32_e32 v24, v52, v51
	v_exp_f32_e32 v51, v25
	v_exp_f32_e32 v53, v26
	v_exp_f32_e32 v54, v27
	v_exp_f32_e32 v55, v20
	v_add_f32_e32 v24, v51, v24
	v_exp_f32_e32 v57, v21
	v_add_f32_e32 v24, v53, v24
	v_exp_f32_e32 v61, v22
	v_add_f32_e32 v24, v54, v24
	v_exp_f32_e32 v62, v23
	v_lshlrev_b32_e32 v58, 2, v13
	v_lshrrev_b32_e32 v10, 2, v14
	v_add_f32_e32 v20, v55, v24
	v_exp_f32_e32 v63, v16
	v_lshlrev_b32_e32 v9, 3, v14
	v_or_b32_e32 v10, v58, v10
	v_add_f32_e32 v20, v57, v20
	v_and_b32_e32 v9, 24, v9
	v_mul_u32_u24_e32 v10, 0x90, v10
	v_add_f32_e32 v20, v61, v20
	v_add3_u32 v59, 0, v9, v10
	ds_read_b64_tr_b16 v[70:71], v59 offset:20736
	ds_read_b64_tr_b16 v[68:69], v59 offset:18432
	ds_read_b64_tr_b16 v[88:89], v59 offset:18464
	ds_read_b64_tr_b16 v[90:91], v59 offset:20768
	ds_read_b64_tr_b16 v[92:93], v59 offset:18496
	ds_read_b64_tr_b16 v[94:95], v59 offset:20800
	ds_read_b64_tr_b16 v[96:97], v59 offset:18528
	ds_read_b64_tr_b16 v[98:99], v59 offset:20832
	v_add_f32_e32 v20, v62, v20
	v_add_f32_e32 v16, v63, v20
	v_cvt_pk_bf16_f32 v20, v36, v37
	v_cvt_pk_bf16_f32 v21, v38, v39
	v_cvt_pk_bf16_f32 v22, v32, v33
	v_cvt_pk_bf16_f32 v23, v34, v35
	s_nop 0
	s_nop 0
	s_nop 0
	s_nop 0
	v_cvt_pk_bf16_f32 v24, v44, v45
	v_cvt_pk_bf16_f32 v25, v46, v47
	v_cvt_pk_bf16_f32 v26, v40, v41
	v_cvt_pk_bf16_f32 v27, v42, v43
	s_nop 0
	s_nop 0
	s_nop 0
	s_nop 0
	v_mul_u32_u24_e32 v49, 0x90, v14
	v_mov_b32_e32 v13, v12
	v_mov_b32_e32 v14, v12
	v_mov_b32_e32 v15, v12
	v_exp_f32_e32 v64, v17
	v_exp_f32_e32 v66, v18
	s_nop 0
	s_waitcnt lgkmcnt(6)
	v_mfma_f32_16x16x32_bf16 v[32:35], v[68:71], v[24:27], v[12:15]
	ds_read_b64_tr_b16 v[68:69], v59 offset:23040
	ds_read_b64_tr_b16 v[70:71], v59 offset:25344
	v_exp_f32_e32 v67, v19
	v_add_f32_e32 v16, v64, v16
	v_add_f32_e32 v16, v66, v16
	s_nop 0
	s_waitcnt lgkmcnt(6)
	v_mfma_f32_16x16x32_bf16 v[36:39], v[88:91], v[24:27], v[12:15]
	ds_read_b64_tr_b16 v[88:89], v59 offset:23072
	ds_read_b64_tr_b16 v[90:91], v59 offset:25376
	v_add_f32_e32 v16, v67, v16
	v_add_f32_e32 v60, v50, v16
	v_cvt_pk_bf16_f32 v16, v28, v29
	s_nop 0
	s_waitcnt lgkmcnt(6)
	v_mfma_f32_16x16x32_bf16 v[40:43], v[92:95], v[24:27], v[12:15]
	ds_read_b64_tr_b16 v[92:93], v59 offset:23104
	ds_read_b64_tr_b16 v[94:95], v59 offset:25408
	v_cvt_pk_bf16_f32 v17, v30, v31
	v_cvt_pk_bf16_f32 v18, v52, v51
	v_cvt_pk_bf16_f32 v19, v53, v54
	s_nop 0
	s_waitcnt lgkmcnt(6)
	v_mfma_f32_16x16x32_bf16 v[12:15], v[96:99], v[24:27], v[12:15]
	s_nop 0
	s_nop 0
	ds_read_b64_tr_b16 v[96:97], v59 offset:23136
	ds_read_b64_tr_b16 v[98:99], v59 offset:25440
	v_cvt_pk_bf16_f32 v28, v55, v57
	v_cvt_pk_bf16_f32 v29, v61, v62
	s_nop 0
	s_waitcnt lgkmcnt(6)
	v_mfma_f32_16x16x32_bf16 v[24:27], v[68:71], v[20:23], v[32:35]
	ds_read_b64_tr_b16 v[68:69], v59 offset:27648
	ds_read_b64_tr_b16 v[70:71], v59 offset:29952
	s_nop 2
	s_nop 0
	s_nop 0
	v_cvt_pk_bf16_f32 v30, v63, v64
	v_cvt_pk_bf16_f32 v31, v66, v67
	s_nop 0
	s_waitcnt lgkmcnt(6)
	v_mfma_f32_16x16x32_bf16 v[32:35], v[88:91], v[20:23], v[36:39]
	ds_read_b64_tr_b16 v[88:89], v59 offset:27680
	ds_read_b64_tr_b16 v[90:91], v59 offset:29984
	s_nop 2
	s_nop 0
	s_nop 0
	v_add_u32_e32 v57, v48, v49
	v_mov_b32_e32 v9, v8
	s_nop 0
	s_waitcnt lgkmcnt(6)
	v_mfma_f32_16x16x32_bf16 v[36:39], v[92:95], v[20:23], v[40:43]
	ds_read_b64_tr_b16 v[92:93], v59 offset:27712
	ds_read_b64_tr_b16 v[94:95], v59 offset:30016
	s_nop 2
	s_nop 0
	s_nop 0
	v_mov_b32_e32 v10, v8
	v_mov_b32_e32 v11, v8
	s_nop 0
	s_waitcnt lgkmcnt(6)
	v_mfma_f32_16x16x32_bf16 v[12:15], v[96:99], v[20:23], v[12:15]
	s_nop 0
	s_nop 0
	ds_read_b64_tr_b16 v[96:97], v59 offset:27744
	ds_read_b64_tr_b16 v[98:99], v59 offset:30048
	s_nop 0
	s_waitcnt lgkmcnt(6)
	v_mfma_f32_16x16x32_bf16 v[20:23], v[68:71], v[16:19], v[24:27]
	ds_read_b64_tr_b16 v[68:69], v59 offset:32256
	ds_read_b64_tr_b16 v[70:71], v59 offset:34560
	s_nop 2
	s_nop 0
	s_nop 0
	s_nop 0
	s_waitcnt lgkmcnt(6)
	v_mfma_f32_16x16x32_bf16 v[32:35], v[88:91], v[16:19], v[32:35]
	s_nop 0
	s_nop 0
	ds_read_b64_tr_b16 v[88:89], v59 offset:32288
	ds_read_b64_tr_b16 v[90:91], v59 offset:34592
	s_nop 0
	s_waitcnt lgkmcnt(6)
	v_mfma_f32_16x16x32_bf16 v[36:39], v[92:95], v[16:19], v[36:39]
	s_nop 0
	s_nop 0
	ds_read_b64_tr_b16 v[92:93], v59 offset:32320
	ds_read_b64_tr_b16 v[94:95], v59 offset:34624
	s_nop 0
	s_waitcnt lgkmcnt(6)
	v_mfma_f32_16x16x32_bf16 v[12:15], v[96:99], v[16:19], v[12:15]
	s_nop 0
	s_nop 0
	s_nop 0
	s_waitcnt lgkmcnt(4)
	v_mfma_f32_16x16x32_bf16 v[24:27], v[68:71], v[28:31], v[20:23]
	s_nop 0
	s_nop 0
	s_nop 0
	s_waitcnt lgkmcnt(2)
	v_mfma_f32_16x16x32_bf16 v[20:23], v[88:91], v[28:31], v[32:35]
	s_nop 0
	s_nop 0
	s_nop 0
	ds_read_b64_tr_b16 v[32:33], v59 offset:32352
	ds_read_b64_tr_b16 v[34:35], v59 offset:34656
	s_nop 0
	s_waitcnt lgkmcnt(2)
	v_mfma_f32_16x16x32_bf16 v[16:19], v[92:95], v[28:31], v[36:39]
	s_waitcnt lgkmcnt(0)
	s_barrier
	s_waitcnt lgkmcnt(0)
	ds_read_b128 v[88:91], v57 offset:36864
	ds_read_b128 v[92:95], v57 offset:36928
	ds_read_b128 v[96:99], v57 offset:39168
	ds_read_b128 v[100:103], v57 offset:39232
	ds_read_b128 v[104:107], v57 offset:41472
	ds_read_b128 v[108:111], v57 offset:41536
	ds_read_b128 v[112:115], v57 offset:43776
	ds_read_b128 v[120:123], v57 offset:43840
	v_mfma_f32_16x16x32_bf16 v[12:15], v[32:35], v[28:31], v[12:15]
	s_nop 0
	s_nop 0
	s_nop 0
	s_waitcnt lgkmcnt(7)
	v_mfma_f32_16x16x32_bf16 v[28:31], v[88:91], v[0:3], v[8:11]
	ds_read_b128 v[88:91], v57 offset:46080
	s_nop 0
	s_waitcnt lgkmcnt(7)
	v_mfma_f32_16x16x32_bf16 v[28:31], v[92:95], v[4:7], v[28:31]
	s_nop 0
	s_nop 0
	ds_read_b128 v[92:95], v57 offset:46144
	s_nop 0
	s_waitcnt lgkmcnt(7)
	v_mfma_f32_16x16x32_bf16 v[32:35], v[96:99], v[0:3], v[8:11]
	ds_read_b128 v[96:99], v57 offset:48384
	s_nop 0
	s_waitcnt lgkmcnt(7)
	v_mfma_f32_16x16x32_bf16 v[32:35], v[100:103], v[4:7], v[32:35]
	s_nop 0
	s_nop 0
	ds_read_b128 v[100:103], v57 offset:48448
	s_nop 0
	s_waitcnt lgkmcnt(7)
	v_mfma_f32_16x16x32_bf16 v[36:39], v[104:107], v[0:3], v[8:11]
	ds_read_b128 v[104:107], v57 offset:50688
	s_nop 0
	s_waitcnt lgkmcnt(7)
	v_mfma_f32_16x16x32_bf16 v[36:39], v[108:111], v[4:7], v[36:39]
	s_nop 0
	s_nop 0
	ds_read_b128 v[150:153], v57 offset:50752
	s_nop 0
	s_waitcnt lgkmcnt(7)
	v_mfma_f32_16x16x32_bf16 v[40:43], v[112:115], v[0:3], v[8:11]
	s_nop 0
	s_waitcnt lgkmcnt(6)
	v_mfma_f32_16x16x32_bf16 v[40:43], v[120:123], v[4:7], v[40:43]
	s_nop 0
	s_nop 0
	s_nop 0
	s_waitcnt lgkmcnt(5)
	v_mfma_f32_16x16x32_bf16 v[44:47], v[88:91], v[0:3], v[8:11]
	s_nop 0
	s_waitcnt lgkmcnt(4)
	v_mfma_f32_16x16x32_bf16 v[44:47], v[92:95], v[4:7], v[44:47]
	s_nop 0
	s_nop 0
	s_nop 0
	s_waitcnt lgkmcnt(3)
	v_mfma_f32_16x16x32_bf16 v[48:51], v[96:99], v[0:3], v[8:11]
	s_nop 0
	s_waitcnt lgkmcnt(2)
	v_mfma_f32_16x16x32_bf16 v[48:51], v[100:103], v[4:7], v[48:51]
	s_nop 0
	s_nop 0
	s_nop 0
	s_waitcnt lgkmcnt(1)
	v_mfma_f32_16x16x32_bf16 v[52:55], v[104:107], v[0:3], v[8:11]
	s_nop 0
	s_waitcnt lgkmcnt(0)
	v_mfma_f32_16x16x32_bf16 v[52:55], v[150:153], v[4:7], v[52:55]
	ds_read_b128 v[66:69], v57 offset:52992
	ds_read_b128 v[70:73], v57 offset:53056
	s_nop 0
	s_waitcnt lgkmcnt(1)
	v_mfma_f32_16x16x32_bf16 v[0:3], v[66:69], v[0:3], v[8:11]
	s_nop 0
	s_waitcnt lgkmcnt(0)
	v_mfma_f32_16x16x32_bf16 v[0:3], v[70:73], v[4:7], v[0:3]
	v_max3_f32 v4, v30, v28, v29
	v_max3_f32 v4, v31, v4, v32
	v_max3_f32 v4, v34, v33, v4
	v_max3_f32 v4, v36, v35, v4
	v_max3_f32 v4, v38, v37, v4
	v_max3_f32 v4, v40, v39, v4
	v_max3_f32 v4, v42, v41, v4
	v_max3_f32 v4, v44, v43, v4
	v_max3_f32 v4, v46, v45, v4
	v_max3_f32 v4, v48, v47, v4
	v_max3_f32 v4, v50, v49, v4
	v_max3_f32 v4, v52, v51, v4
	v_max3_f32 v4, v54, v53, v4
	v_max3_f32 v4, v0, v55, v4
	v_max3_f32 v4, v2, v1, v4
	v_max_f32_e32 v5, v3, v3
	v_max_f32_e32 v4, v5, v4
	v_cmp_lt_f32_e32 vcc, s52, v4
	s_cbranch_vccz .LBB0_1051
	v_max_f32_e32 v4, v29, v29
	v_max_f32_e32 v5, v28, v28
	v_max_f32_e32 v4, v5, v4
	v_max3_f32 v4, v4, v30, v31
	v_max3_f32 v4, v4, v32, v33
	v_max3_f32 v4, v4, v34, v35
	v_max3_f32 v4, v4, v36, v37
	v_max3_f32 v4, v4, v38, v39
	v_max3_f32 v4, v4, v40, v41
	v_max3_f32 v4, v4, v42, v43
	v_max3_f32 v4, v4, v44, v45
	v_max3_f32 v4, v4, v46, v47
	v_max3_f32 v4, v4, v48, v49
	v_max3_f32 v4, v4, v50, v51
	v_max3_f32 v4, v4, v52, v53
	v_max3_f32 v4, v4, v54, v55
	v_max3_f32 v4, v4, v0, v1
	v_max3_f32 v4, v4, v2, v3
	v_mov_b32_e32 v5, v4
	s_nop 1
	v_permlane16_swap_b32_e32 v4, v5
	v_max_f32_e32 v5, v5, v5
	v_max_f32_e32 v4, v4, v4
	v_max_f32_e32 v4, v4, v5
	v_mov_b32_e32 v5, v4
	s_nop 1
	v_permlane32_swap_b32_e32 v4, v5
	v_max_f32_e32 v5, v5, v5
	v_max_f32_e32 v4, v4, v4
	v_max_f32_e32 v4, v4, v5
	v_cmp_lt_f32_e32 vcc, s52, v4
	s_nop 1
	v_cndmask_b32_e32 v4, 0, v4, vcc
	v_exp_f32_e64 v6, -v4
	v_pk_add_f32 v[28:29], v[28:29], v[4:5] op_sel_hi:[1,0] neg_lo:[0,1] neg_hi:[0,1]
	v_pk_add_f32 v[30:31], v[30:31], v[4:5] op_sel_hi:[1,0] neg_lo:[0,1] neg_hi:[0,1]
	v_pk_add_f32 v[32:33], v[32:33], v[4:5] op_sel_hi:[1,0] neg_lo:[0,1] neg_hi:[0,1]
	v_mul_f32_e32 v60, v60, v6
	v_pk_add_f32 v[34:35], v[34:35], v[4:5] op_sel_hi:[1,0] neg_lo:[0,1] neg_hi:[0,1]
	v_pk_add_f32 v[36:37], v[36:37], v[4:5] op_sel_hi:[1,0] neg_lo:[0,1] neg_hi:[0,1]
	v_pk_add_f32 v[38:39], v[38:39], v[4:5] op_sel_hi:[1,0] neg_lo:[0,1] neg_hi:[0,1]
	v_pk_add_f32 v[40:41], v[40:41], v[4:5] op_sel_hi:[1,0] neg_lo:[0,1] neg_hi:[0,1]
	v_pk_add_f32 v[42:43], v[42:43], v[4:5] op_sel_hi:[1,0] neg_lo:[0,1] neg_hi:[0,1]
	v_pk_add_f32 v[44:45], v[44:45], v[4:5] op_sel_hi:[1,0] neg_lo:[0,1] neg_hi:[0,1]
	v_pk_add_f32 v[46:47], v[46:47], v[4:5] op_sel_hi:[1,0] neg_lo:[0,1] neg_hi:[0,1]
	v_pk_add_f32 v[48:49], v[48:49], v[4:5] op_sel_hi:[1,0] neg_lo:[0,1] neg_hi:[0,1]
	v_pk_add_f32 v[50:51], v[50:51], v[4:5] op_sel_hi:[1,0] neg_lo:[0,1] neg_hi:[0,1]
	v_pk_add_f32 v[52:53], v[52:53], v[4:5] op_sel_hi:[1,0] neg_lo:[0,1] neg_hi:[0,1]
	v_pk_add_f32 v[54:55], v[54:55], v[4:5] op_sel_hi:[1,0] neg_lo:[0,1] neg_hi:[0,1]
	v_pk_add_f32 v[0:1], v[0:1], v[4:5] op_sel_hi:[1,0] neg_lo:[0,1] neg_hi:[0,1]
	v_pk_add_f32 v[2:3], v[2:3], v[4:5] op_sel_hi:[1,0] neg_lo:[0,1] neg_hi:[0,1]
	v_pk_mul_f32 v[14:15], v[14:15], v[6:7] op_sel_hi:[1,0]
	v_pk_mul_f32 v[12:13], v[12:13], v[6:7] op_sel_hi:[1,0]
	v_pk_mul_f32 v[18:19], v[18:19], v[6:7] op_sel_hi:[1,0]
	v_pk_mul_f32 v[16:17], v[16:17], v[6:7] op_sel_hi:[1,0]
	v_pk_mul_f32 v[22:23], v[22:23], v[6:7] op_sel_hi:[1,0]
	v_pk_mul_f32 v[20:21], v[20:21], v[6:7] op_sel_hi:[1,0]
	v_pk_mul_f32 v[26:27], v[26:27], v[6:7] op_sel_hi:[1,0]
	v_pk_mul_f32 v[24:25], v[24:25], v[6:7] op_sel_hi:[1,0]
.LBB0_1051:
	s_waitcnt lgkmcnt(0)
	ds_read_b64_tr_b16 v[92:93], v59 offset:57600
	ds_read_b64_tr_b16 v[90:91], v59 offset:55296
	ds_read_b64_tr_b16 v[94:95], v59 offset:55360
	ds_read_b64_tr_b16 v[96:97], v59 offset:57664
	ds_read_b64_tr_b16 v[98:99], v59 offset:59904
	ds_read_b64_tr_b16 v[100:101], v59 offset:62208
	ds_read_b64_tr_b16 v[102:103], v59 offset:59936
	ds_read_b64_tr_b16 v[104:105], v59 offset:62240
	v_exp_f32_e32 v4, v28
	v_exp_f32_e32 v6, v29
	v_exp_f32_e32 v7, v30
	v_exp_f32_e32 v8, v31
	v_add_f32_e32 v5, 0, v4
	v_exp_f32_e32 v9, v32
	v_add_f32_e32 v5, v6, v5
	v_exp_f32_e32 v10, v33
	v_add_f32_e32 v5, v7, v5
	v_exp_f32_e32 v11, v34
	v_add_f32_e32 v5, v8, v5
	v_exp_f32_e32 v29, v35
	v_add_f32_e32 v5, v9, v5
	v_exp_f32_e32 v34, v36
	v_add_f32_e32 v5, v10, v5
	v_exp_f32_e32 v35, v37
	v_add_f32_e32 v5, v11, v5
	v_exp_f32_e32 v36, v38
	v_add_f32_e32 v5, v29, v5
	v_exp_f32_e32 v37, v39
	v_add_f32_e32 v5, v5, v34
	v_exp_f32_e32 v38, v40
	v_add_f32_e32 v5, v35, v5
	v_exp_f32_e32 v39, v41
	v_add_f32_e32 v5, v36, v5
	v_add_f32_e32 v5, v37, v5
	v_add_f32_e32 v5, v38, v5
	v_exp_f32_e32 v40, v42
	v_add_f32_e32 v5, v39, v5
	v_exp_f32_e32 v41, v43
	v_cvt_pk_bf16_f32 v31, v7, v8
	v_cvt_pk_bf16_f32 v32, v9, v10
	v_cvt_pk_bf16_f32 v8, v34, v35
	v_cvt_pk_bf16_f32 v9, v36, v37
	v_cvt_pk_bf16_f32 v10, v38, v39
	s_nop 0
	s_nop 0
	ds_read_b64_tr_b16 v[38:39], v59 offset:55328
	v_add_f32_e32 v5, v40, v5
	v_cvt_pk_bf16_f32 v30, v4, v6
	v_cvt_pk_bf16_f32 v33, v11, v29
	v_add_f32_e32 v5, v41, v5
	v_cvt_pk_bf16_f32 v11, v40, v41
	s_nop 0
	s_waitcnt lgkmcnt(7)
	v_mfma_f32_16x16x32_bf16 v[24:27], v[90:93], v[30:33], v[24:27]
	ds_read_b64_tr_b16 v[90:91], v59 offset:59968
	ds_read_b64_tr_b16 v[92:93], v59 offset:62272
	ds_read_b64_tr_b16 v[40:41], v59 offset:57632
	s_nop 0
	s_nop 0
	v_exp_f32_e32 v42, v44
	s_nop 0
	s_waitcnt lgkmcnt(8)
	v_mfma_f32_16x16x32_bf16 v[16:19], v[94:97], v[30:33], v[16:19]
	ds_read_b64_tr_b16 v[94:95], v59 offset:60000
	ds_read_b64_tr_b16 v[96:97], v59 offset:62304
	ds_read_b64_tr_b16 v[34:35], v59 offset:55392
	ds_read_b64_tr_b16 v[36:37], v59 offset:57696
	v_exp_f32_e32 v43, v45
	v_exp_f32_e32 v44, v46
	s_waitcnt lgkmcnt(4)
	v_mfma_f32_16x16x32_bf16 v[20:23], v[38:41], v[30:33], v[20:23]
	v_exp_f32_e32 v45, v47
	v_add_f32_e32 v5, v42, v5
	v_exp_f32_e32 v46, v48
	s_nop 0
	s_waitcnt lgkmcnt(0)
	v_mfma_f32_16x16x32_bf16 v[12:15], v[34:37], v[30:33], v[12:15]
	s_nop 0
	s_nop 0
	v_add_f32_e32 v5, v43, v5
	v_exp_f32_e32 v47, v49
	s_nop 0
	v_mfma_f32_16x16x32_bf16 v[24:27], v[98:101], v[8:11], v[24:27]
	s_nop 0
	s_nop 0
	ds_read_b64_tr_b16 v[108:109], v59 offset:64512
	v_add_f32_e32 v5, v44, v5
	v_exp_f32_e32 v48, v50
	s_nop 0
	v_mfma_f32_16x16x32_bf16 v[20:23], v[102:105], v[8:11], v[20:23]
	s_nop 0
	s_nop 0
	v_add_f32_e32 v5, v45, v5
	v_exp_f32_e32 v49, v51
	v_add_f32_e32 v5, v46, v5
	v_exp_f32_e32 v50, v52
	s_nop 0
	v_mfma_f32_16x16x32_bf16 v[16:19], v[90:93], v[8:11], v[16:19]
	s_nop 0
	s_nop 0
	v_add_f32_e32 v5, v47, v5
	v_exp_f32_e32 v51, v53
	v_add_f32_e32 v5, v48, v5
	v_exp_f32_e32 v52, v54
	v_add_f32_e32 v5, v49, v5
	v_exp_f32_e32 v53, v55
	v_add_f32_e32 v5, v50, v5
	v_exp_f32_e32 v54, v0
	v_add_u32_e32 v61, 0xd800, v59
	ds_read_b64_tr_b16 v[110:111], v61 offset:11520
	ds_read_b64_tr_b16 v[88:89], v59 offset:64576
	ds_read_b64_tr_b16 v[90:91], v61 offset:11584
	ds_read_b64_tr_b16 v[100:101], v61 offset:13824
	ds_read_b64_tr_b16 v[102:103], v61 offset:16128
	v_add_f32_e32 v5, v51, v5
	s_nop 0
	v_mfma_f32_16x16x32_bf16 v[8:11], v[94:97], v[8:11], v[12:15]
	ds_read_b64_tr_b16 v[92:93], v61 offset:13856
	ds_read_b64_tr_b16 v[94:95], v61 offset:16160
	s_nop 2
	s_nop 0
	s_nop 0
	ds_read_b64_tr_b16 v[32:33], v61 offset:11552
	v_add_f32_e32 v5, v52, v5
	v_add_f32_e32 v5, v53, v5
	v_add_f32_e32 v0, v54, v5
	v_cvt_pk_bf16_f32 v4, v42, v43
	v_cvt_pk_bf16_f32 v5, v44, v45
	v_cvt_pk_bf16_f32 v6, v46, v47
	v_cvt_pk_bf16_f32 v7, v48, v49
	ds_read_b64_tr_b16 v[30:31], v59 offset:64544
	v_exp_f32_e32 v55, v1
	s_nop 0
	s_waitcnt lgkmcnt(8)
	v_mfma_f32_16x16x32_bf16 v[12:15], v[108:111], v[4:7], v[24:27]
	ds_read_b64_tr_b16 v[96:97], v61 offset:13888
	ds_read_b64_tr_b16 v[98:99], v61 offset:16192
	s_nop 2
	s_nop 0
	s_nop 0
	v_exp_f32_e32 v62, v2
	v_exp_f32_e32 v3, v3
	s_nop 0
	s_waitcnt lgkmcnt(8)
	v_mfma_f32_16x16x32_bf16 v[16:19], v[88:91], v[4:7], v[16:19]
	ds_read_b64_tr_b16 v[24:25], v59 offset:64608
	ds_read_b64_tr_b16 v[26:27], v61 offset:11616
	v_add_f32_e32 v0, v55, v0
	v_add_f32_e32 v0, v62, v0
	s_waitcnt lgkmcnt(4)
	v_mfma_f32_16x16x32_bf16 v[20:23], v[30:33], v[4:7], v[20:23]
	v_add_f32_e32 v0, v3, v0
	v_add_f32_e32 v28, v60, v0
	v_cvt_pk_bf16_f32 v0, v50, v51
	s_nop 0
	s_waitcnt lgkmcnt(0)
	v_mfma_f32_16x16x32_bf16 v[4:7], v[24:27], v[4:7], v[8:11]
	s_nop 2
	s_nop 0
	s_nop 0
	v_cvt_pk_bf16_f32 v1, v52, v53
	v_cvt_pk_bf16_f32 v2, v54, v55
	v_cvt_pk_bf16_f32 v3, v62, v3
	v_ashrrev_i32_e32 v57, 31, v56
	s_lshl_b32 s8, s10, 6
	s_nop 0
	v_mfma_f32_16x16x32_bf16 v[8:11], v[100:103], v[0:3], v[12:15]
	s_nop 2
	s_nop 0
	s_nop 0
	s_lshl_b32 s96, s8, 1
	v_lshlrev_b32_e32 v64, 1, v58
	s_nop 0
	v_mfma_f32_16x16x32_bf16 v[12:15], v[92:95], v[0:3], v[20:23]
	s_nop 2
	s_nop 0
	s_nop 0
	s_nop 0
	v_mfma_f32_16x16x32_bf16 v[16:19], v[96:99], v[0:3], v[16:19]
	ds_read_b64_tr_b16 v[20:21], v61 offset:13920
	ds_read_b64_tr_b16 v[22:23], v61 offset:16224
	s_nop 0
	s_waitcnt lgkmcnt(0)
	s_barrier
	v_mfma_f32_16x16x32_bf16 v[0:3], v[20:23], v[0:3], v[4:7]
	s_nop 2
	v_mov_b32_e32 v4, v28
	s_nop 1
	v_permlane16_swap_b32_e32 v28, v4
	v_add_f32_e32 v4, v28, v4
	v_mov_b32_e32 v5, v4
	s_nop 1
	v_permlane32_swap_b32_e32 v4, v5
	v_add_f32_e32 v4, v4, v5
	v_lshlrev_b64 v[6:7], 11, v[56:57]
	v_rcp_f32_e32 v4, v4
	v_lshl_add_u64 v[6:7], s[6:7], 0, v[6:7]
	v_lshl_add_u64 v[6:7], v[6:7], 0, s[96:97]
	v_lshl_add_u64 v[6:7], v[6:7], 0, v[64:65]
	s_mov_b64 s[6:7], 0xf000400
	v_lshl_add_u64 v[20:21], v[6:7], 0, s[6:7]
	s_mov_b32 s6, 0xf000000
	v_pk_mul_f32 v[8:9], v[8:9], v[4:5] op_sel_hi:[1,0]
	v_pk_mul_f32 v[10:11], v[10:11], v[4:5] op_sel_hi:[1,0]
	v_add_co_u32_e32 v6, vcc, s6, v6
	v_cvt_pk_bf16_f32 v8, v8, v9
	v_cvt_pk_bf16_f32 v9, v10, v11
	v_addc_co_u32_e32 v7, vcc, 0, v7, vcc
	global_store_dwordx2 v[6:7], v[8:9], off offset:1024
	v_pk_mul_f32 v[6:7], v[12:13], v[4:5] op_sel_hi:[1,0]
	v_pk_mul_f32 v[8:9], v[14:15], v[4:5] op_sel_hi:[1,0]
	v_cvt_pk_bf16_f32 v6, v6, v7
	v_cvt_pk_bf16_f32 v7, v8, v9
	global_store_dwordx2 v[20:21], v[6:7], off offset:32
	v_pk_mul_f32 v[6:7], v[16:17], v[4:5] op_sel_hi:[1,0]
	v_pk_mul_f32 v[8:9], v[18:19], v[4:5] op_sel_hi:[1,0]
	v_pk_mul_f32 v[0:1], v[0:1], v[4:5] op_sel_hi:[1,0]
	v_pk_mul_f32 v[2:3], v[2:3], v[4:5] op_sel_hi:[1,0]
	v_cvt_pk_bf16_f32 v6, v6, v7
	v_cvt_pk_bf16_f32 v7, v8, v9
	v_cvt_pk_bf16_f32 v0, v0, v1
	v_cvt_pk_bf16_f32 v1, v2, v3
	global_store_dwordx2 v[20:21], v[6:7], off offset:64
	global_store_dwordx2 v[20:21], v[0:1], off offset:96

.LBB0_1060:
	s_or_b64 exec, exec, s[8:9]
	v_add_u32_e32 v40, 0, v40
	v_mad_u64_u32 v[46:47], s[8:9], v41, s94, v[40:41]
	ds_write_b128 v46, v[0:3]
	ds_write_b128 v46, v[4:7] offset:18432
	v_mad_u64_u32 v[0:1], s[8:9], v44, s94, v[40:41]
	v_add_u32_e32 v94, 0, v64
	ds_write_b128 v0, v[8:11]
	ds_write_b128 v0, v[12:15] offset:18432
	s_waitcnt lgkmcnt(0)
	s_barrier
	v_mad_u32_u24 v66, v75, s94, v94
	ds_write_b128 v46, v[16:19] offset:36864
	ds_write_b128 v46, v[20:23] offset:55296
	ds_write_b128 v0, v[24:27] offset:36864
	ds_write_b128 v0, v[28:31] offset:55296
	s_waitcnt lgkmcnt(0)
	ds_read_b128 v[112:115], v66
	ds_read_b128 v[120:123], v66 offset:64
	ds_read_b128 v[148:151], v66 offset:2304
	ds_read_b128 v[152:155], v66 offset:2368
	ds_read_b128 v[156:159], v66 offset:4608
	ds_read_b128 v[160:163], v66 offset:4672
	ds_read_b128 v[164:167], v66 offset:6912
	ds_read_b128 v[168:171], v66 offset:6976
	s_nop 0
	s_waitcnt lgkmcnt(7)
	v_mfma_f32_16x16x32_bf16 v[0:3], v[112:115], v[32:35], 0
	ds_read_b128 v[112:115], v66 offset:9216
	v_lshlrev_b32_e32 v91, 2, v42
	v_or_b32_e32 v78, 32, v91
	s_add_i32 s8, 0, 0x12000
	s_nop 0
	s_waitcnt lgkmcnt(7)
	v_mfma_f32_16x16x32_bf16 v[40:43], v[120:123], v[36:39], v[0:3]
	ds_read_b128 v[120:123], v66 offset:9280
	v_readlane_b32 s9, v255, 19
	v_or_b32_e32 v79, 48, v91
	v_or_b32_e32 v80, 64, v91
	s_nop 0
	s_nop 0
	s_waitcnt lgkmcnt(7)
	v_mfma_f32_16x16x32_bf16 v[4:7], v[148:151], v[32:35], 0
	s_nop 0
	ds_read_b128 v[148:151], v66 offset:11520
	v_or_b32_e32 v81, 0x50, v91
	v_or_b32_e32 v82, 0x60, v91
	s_nop 0
	s_waitcnt lgkmcnt(7)
	v_mfma_f32_16x16x32_bf16 v[44:47], v[152:155], v[36:39], v[4:7]
	ds_read_b128 v[152:155], v66 offset:11584
	v_lshlrev_b32_e32 v12, 2, v78
	v_add_u32_e32 v100, s8, v12
	v_add_u32_e32 v97, s9, v12
	s_nop 0
	s_nop 0
	s_nop 0
	s_waitcnt lgkmcnt(7)
	v_mfma_f32_16x16x32_bf16 v[0:3], v[156:159], v[32:35], 0
	ds_read_b128 v[156:159], v66 offset:13824
	v_add_u32_e32 v95, s8, v64
	v_or_b32_e32 v77, 16, v91
	v_or_b32_e32 v83, 0x70, v91
	s_nop 0
	s_waitcnt lgkmcnt(7)
	v_mfma_f32_16x16x32_bf16 v[48:51], v[160:163], v[36:39], v[0:3]
	v_lshlrev_b32_e32 v8, 2, v79
	v_add_u32_e32 v102, s8, v8
	v_add_u32_e32 v99, s9, v8
	s_nop 0
	s_nop 0
	s_nop 0
	s_waitcnt lgkmcnt(6)
	v_mfma_f32_16x16x32_bf16 v[4:7], v[164:167], v[32:35], 0
	s_lshl_b32 s10, s12, 6
	v_lshlrev_b32_e32 v16, 2, v77
	v_readfirstlane_b32 s11, v92
	s_nop 0
	s_waitcnt lgkmcnt(5)
	v_mfma_f32_16x16x32_bf16 v[52:55], v[168:171], v[36:39], v[4:7]
	v_lshlrev_b32_e32 v12, 2, v80
	v_add_u32_e32 v104, s8, v12
	v_add_u32_e32 v101, s9, v12
	s_nop 0
	s_nop 0
	s_nop 0
	s_waitcnt lgkmcnt(4)
	v_mfma_f32_16x16x32_bf16 v[0:3], v[112:115], v[32:35], 0
	v_ashrrev_i32_e32 v87, 31, v86
	v_add_u32_e32 v98, s8, v16
	v_add_u32_e32 v96, s9, v16
	s_nop 0
	s_waitcnt lgkmcnt(3)
	v_mfma_f32_16x16x32_bf16 v[56:59], v[120:123], v[36:39], v[0:3]
	v_lshlrev_b32_e32 v8, 2, v81
	v_add_u32_e32 v106, s8, v8
	v_add_u32_e32 v103, s9, v8
	s_nop 0
	ds_read_b128 v[8:11], v66 offset:13888
	s_nop 0
	s_waitcnt lgkmcnt(3)
	v_mfma_f32_16x16x32_bf16 v[4:7], v[148:151], v[32:35], 0
	s_cmpk_lt_i32 s11, 0x80
	s_nop 0
	s_waitcnt lgkmcnt(2)
	v_mfma_f32_16x16x32_bf16 v[60:63], v[152:155], v[36:39], v[4:7]
	v_lshlrev_b32_e32 v12, 2, v82
	v_add_u32_e32 v107, s8, v12
	v_add_u32_e32 v105, s9, v12
	s_nop 1
	ds_read_b128 v[4:7], v66 offset:16128
	ds_read_b128 v[12:15], v66 offset:16192
	s_nop 0
	s_waitcnt lgkmcnt(3)
	v_mfma_f32_16x16x32_bf16 v[0:3], v[156:159], v[32:35], 0
	s_nop 0
	s_waitcnt lgkmcnt(2)
	v_mfma_f32_16x16x32_bf16 v[66:69], v[8:11], v[36:39], v[0:3]
	v_cvt_f32_i32_e32 v9, v90
	v_lshlrev_b32_e32 v8, 2, v83
	v_add_u32_e32 v108, s8, v8
	s_nop 0
	s_waitcnt lgkmcnt(1)
	v_mfma_f32_16x16x32_bf16 v[0:3], v[4:7], v[32:35], 0
	v_mul_f32_e32 v4, v76, v9
	v_exp_f32_e32 v64, v4
	v_add_u32_e32 v109, s9, v8
	s_nop 0
	s_waitcnt lgkmcnt(0)
	v_mfma_f32_16x16x32_bf16 v[70:73], v[12:15], v[36:39], v[0:3]
	s_mov_b64 s[8:9], -1
	s_cbranch_scc0 .LBB0_1066
	s_nop 0
	v_sub_u32_e32 v0, 0, v90
	v_cvt_f32_i32_e32 v0, v0
	s_cmp_lt_i32 s11, -15
	v_mul_f32_e32 v0, v93, v0
	v_exp_f32_e32 v74, v0
	s_cbranch_scc1 .LBB0_1063
	s_waitcnt lgkmcnt(0)
	ds_read_b128 v[168:171], v95
	ds_read_b128 v[172:175], v98
	ds_read_b128 v[176:179], v96
	ds_read_b128 v[184:187], v100
	ds_read_b128 v[200:203], v97
	ds_read_b128 v[204:207], v102
	ds_read_b128 v[216:219], v99
	ds_read_b128 v[220:223], v104
	v_add_u32_e32 v84, 0x12200, v94
	s_nop 0
	s_nop 0
	s_nop 0
	s_nop 0
	s_nop 0
	s_nop 0
	s_nop 0
	s_nop 0
	ds_read_b128 v[242:245], v101
	ds_read_b128 v[246:249], v106
	ds_read_b128 v[250:253], v103
	ds_read_b128 v[122:125], v107
	ds_read_b128 v[126:129], v105
	ds_read_b128 v[130:133], v108
	ds_read_b128 v[134:137], v84
	ds_read_b128 v[138:141], v109
	v_or_b32_e32 v165, 0x72, v91
	v_or_b32_e32 v164, 0x73, v91
	s_nop 0
	s_waitcnt lgkmcnt(2)
	v_pk_mul_f32 v[84:85], v[64:65], v[132:133] op_sel_hi:[0,1]
	s_nop 0
	s_waitcnt lgkmcnt(1)
	v_pk_mul_f32 v[132:133], v[74:75], v[134:135] op_sel_hi:[0,1]
	v_pk_mul_f32 v[134:135], v[74:75], v[136:137] op_sel_hi:[0,1]
	s_nop 0
	s_waitcnt lgkmcnt(0)
	v_pk_mul_f32 v[136:137], v[74:75], v[140:141] op_sel_hi:[0,1]
	v_cmp_ne_u32_e32 vcc, v90, v165
	v_or_b32_e32 v162, 0x62, v91
	v_or_b32_e32 v161, 0x63, v91
	v_cndmask_b32_e32 v136, v237, v136, vcc
	v_cmp_ne_u32_e32 vcc, v90, v164
	v_pk_mul_f32 v[128:129], v[74:75], v[128:129] op_sel_hi:[0,1]
	v_or_b32_e32 v159, 0x52, v91
	v_cndmask_b32_e32 v137, v237, v137, vcc
	v_cmp_ne_u32_e32 vcc, v90, v162
	v_or_b32_e32 v158, 0x53, v91
	v_pk_mul_f32 v[120:121], v[74:75], v[252:253] op_sel_hi:[0,1]
	v_cndmask_b32_e32 v128, v237, v128, vcc
	v_cmp_ne_u32_e32 vcc, v90, v161
	v_or_b32_e32 v156, 0x42, v91
	v_or_b32_e32 v155, 0x43, v91
	v_cndmask_b32_e32 v129, v237, v129, vcc
	v_cmp_ne_u32_e32 vcc, v90, v159
	v_pk_mul_f32 v[112:113], v[74:75], v[244:245] op_sel_hi:[0,1]
	v_or_b32_e32 v153, 50, v91
	v_cndmask_b32_e32 v120, v237, v120, vcc
	v_cmp_ne_u32_e32 vcc, v90, v158
	v_or_b32_e32 v152, 51, v91
	v_pk_mul_f32 v[26:27], v[74:75], v[218:219] op_sel_hi:[0,1]
	v_cndmask_b32_e32 v121, v237, v121, vcc
	v_cmp_ne_u32_e32 vcc, v90, v156
	v_or_b32_e32 v150, 34, v91
	v_or_b32_e32 v149, 35, v91
	v_cndmask_b32_e32 v112, v237, v112, vcc
	v_cmp_ne_u32_e32 vcc, v90, v155
	v_pk_mul_f32 v[18:19], v[74:75], v[202:203] op_sel_hi:[0,1]
	v_or_b32_e32 v147, 18, v91
	v_cndmask_b32_e32 v113, v237, v113, vcc
	v_cmp_ne_u32_e32 vcc, v90, v153
	v_or_b32_e32 v146, 19, v91
	v_pk_mul_f32 v[10:11], v[74:75], v[178:179] op_sel_hi:[0,1]
	v_cndmask_b32_e32 v26, v237, v26, vcc
	v_cmp_ne_u32_e32 vcc, v90, v152
	v_or_b32_e32 v144, 2, v91
	v_or_b32_e32 v143, 3, v91
	v_cndmask_b32_e32 v27, v237, v27, vcc
	v_cmp_ne_u32_e32 vcc, v90, v150
	v_or_b32_e32 v163, 0x71, v91
	v_pk_mul_f32 v[138:139], v[74:75], v[138:139] op_sel_hi:[0,1]
	v_cndmask_b32_e32 v18, v237, v18, vcc
	v_cmp_ne_u32_e32 vcc, v90, v149
	v_or_b32_e32 v160, 0x61, v91
	v_pk_mul_f32 v[126:127], v[74:75], v[126:127] op_sel_hi:[0,1]
	v_cndmask_b32_e32 v19, v237, v19, vcc
	v_cmp_ne_u32_e32 vcc, v90, v147
	v_or_b32_e32 v157, 0x51, v91
	v_pk_mul_f32 v[118:119], v[74:75], v[250:251] op_sel_hi:[0,1]
	v_cndmask_b32_e32 v10, v237, v10, vcc
	v_cmp_ne_u32_e32 vcc, v90, v146
	v_or_b32_e32 v154, 0x41, v91
	v_pk_mul_f32 v[110:111], v[74:75], v[242:243] op_sel_hi:[0,1]
	v_cndmask_b32_e32 v11, v237, v11, vcc
	v_cmp_ne_u32_e32 vcc, v90, v144
	v_or_b32_e32 v151, 49, v91
	v_pk_mul_f32 v[24:25], v[74:75], v[216:217] op_sel_hi:[0,1]
	v_cndmask_b32_e32 v134, v237, v134, vcc
	v_cmp_ne_u32_e32 vcc, v90, v143
	v_or_b32_e32 v148, 33, v91
	v_pk_mul_f32 v[16:17], v[74:75], v[200:201] op_sel_hi:[0,1]
	v_cndmask_b32_e32 v135, v237, v135, vcc
	v_cmp_ne_u32_e32 vcc, v90, v83
	v_or_b32_e32 v145, 17, v91
	v_pk_mul_f32 v[8:9], v[74:75], v[176:177] op_sel_hi:[0,1]
	v_cndmask_b32_e32 v138, v237, v138, vcc
	v_cmp_ne_u32_e32 vcc, v90, v163
	v_or_b32_e32 v142, 1, v91
	v_pk_mul_f32 v[2:3], v[64:65], v[170:171] op_sel_hi:[0,1]
	v_cndmask_b32_e32 v139, v237, v139, vcc
	v_cmp_ne_u32_e32 vcc, v90, v82
	v_pk_mul_f32 v[6:7], v[64:65], v[174:175] op_sel_hi:[0,1]
	v_pk_mul_f32 v[14:15], v[64:65], v[186:187] op_sel_hi:[0,1]
	v_cndmask_b32_e32 v126, v237, v126, vcc
	v_cmp_ne_u32_e32 vcc, v90, v160
	v_pk_mul_f32 v[22:23], v[64:65], v[206:207] op_sel_hi:[0,1]
	v_pk_mul_f32 v[30:31], v[64:65], v[222:223] op_sel_hi:[0,1]
	v_cndmask_b32_e32 v127, v237, v127, vcc
	v_cmp_ne_u32_e32 vcc, v90, v81
	v_pk_mul_f32 v[116:117], v[64:65], v[248:249] op_sel_hi:[0,1]
	v_pk_mul_f32 v[124:125], v[64:65], v[124:125] op_sel_hi:[0,1]
	v_cndmask_b32_e32 v118, v237, v118, vcc
	v_cmp_ne_u32_e32 vcc, v90, v157
	v_pk_mul_f32 v[0:1], v[64:65], v[168:169] op_sel_hi:[0,1]
	v_pk_mul_f32 v[4:5], v[64:65], v[172:173] op_sel_hi:[0,1]
	v_cndmask_b32_e32 v119, v237, v119, vcc
	v_cmp_ne_u32_e32 vcc, v90, v80
	v_pk_mul_f32 v[12:13], v[64:65], v[184:185] op_sel_hi:[0,1]
	v_pk_mul_f32 v[20:21], v[64:65], v[204:205] op_sel_hi:[0,1]
	v_cndmask_b32_e32 v110, v237, v110, vcc
	v_cmp_ne_u32_e32 vcc, v90, v154
	v_pk_mul_f32 v[28:29], v[64:65], v[220:221] op_sel_hi:[0,1]
	v_pk_mul_f32 v[114:115], v[64:65], v[246:247] op_sel_hi:[0,1]
	v_cndmask_b32_e32 v111, v237, v111, vcc
	v_cmp_ne_u32_e32 vcc, v90, v79
	v_pk_mul_f32 v[122:123], v[64:65], v[122:123] op_sel_hi:[0,1]
	v_pk_mul_f32 v[130:131], v[64:65], v[130:131] op_sel_hi:[0,1]
	v_cndmask_b32_e32 v24, v237, v24, vcc
	v_cmp_ne_u32_e32 vcc, v90, v151
	s_mov_b64 s[8:9], 0
	s_nop 0
	v_cndmask_b32_e32 v25, v237, v25, vcc
	v_cmp_ne_u32_e32 vcc, v90, v78
	s_nop 1
	v_cndmask_b32_e32 v140, v237, v16, vcc
	v_cmp_ne_u32_e32 vcc, v90, v148
	s_nop 1
	v_cndmask_b32_e32 v141, v237, v17, vcc
	v_cmp_ne_u32_e32 vcc, v90, v77
	s_nop 1
	v_cndmask_b32_e32 v166, v237, v8, vcc
	v_cmp_ne_u32_e32 vcc, v90, v145
	s_nop 1
	v_cndmask_b32_e32 v167, v237, v9, vcc
	v_cmp_ne_u32_e32 vcc, v90, v91
	s_nop 1
	v_cndmask_b32_e32 v132, v237, v132, vcc
	v_cmp_ne_u32_e32 vcc, v90, v142
	s_nop 1
	v_cndmask_b32_e32 v133, v237, v133, vcc
	v_cmp_gt_i32_e32 vcc, v90, v143
	s_nop 1
	v_cndmask_b32_e32 v3, v135, v3, vcc
	v_cmp_gt_i32_e32 vcc, v90, v144
	s_nop 1
	v_cndmask_b32_e32 v2, v134, v2, vcc
	v_cmp_gt_i32_e32 vcc, v90, v146
	v_pk_mul_f32 v[2:3], v[42:43], v[2:3]
	s_nop 0
	v_cndmask_b32_e32 v7, v11, v7, vcc
	v_cmp_gt_i32_e32 vcc, v90, v147
	s_nop 1
	v_cndmask_b32_e32 v6, v10, v6, vcc
	v_cmp_gt_i32_e32 vcc, v90, v149
	v_pk_mul_f32 v[6:7], v[46:47], v[6:7]
	s_nop 0
	v_cndmask_b32_e32 v9, v19, v15, vcc
	v_cmp_gt_i32_e32 vcc, v90, v150
	s_nop 1
	v_cndmask_b32_e32 v8, v18, v14, vcc
	v_cmp_gt_i32_e32 vcc, v90, v152
	s_nop 1
	v_cndmask_b32_e32 v11, v27, v23, vcc
	v_cmp_gt_i32_e32 vcc, v90, v153
	s_nop 1
	v_cndmask_b32_e32 v10, v26, v22, vcc
	v_cmp_gt_i32_e32 vcc, v90, v155
	s_nop 1
	v_cndmask_b32_e32 v15, v113, v31, vcc
	v_cmp_gt_i32_e32 vcc, v90, v156
	s_nop 1
	v_cndmask_b32_e32 v14, v112, v30, vcc
	v_cmp_gt_i32_e32 vcc, v90, v158
	s_nop 1
	v_cndmask_b32_e32 v17, v121, v117, vcc
	v_cmp_gt_i32_e32 vcc, v90, v159
	s_nop 1
	v_cndmask_b32_e32 v16, v120, v116, vcc
	v_cmp_gt_i32_e32 vcc, v90, v161
	s_nop 1
	v_cndmask_b32_e32 v19, v129, v125, vcc
	v_cmp_gt_i32_e32 vcc, v90, v162
	s_nop 1
	v_cndmask_b32_e32 v18, v128, v124, vcc
	v_cmp_gt_i32_e32 vcc, v90, v164
	v_pk_mul_f32 v[26:27], v[68:69], v[18:19]
	v_pk_mul_f32 v[18:19], v[58:59], v[14:15]
	v_cndmask_b32_e32 v23, v137, v85, vcc
	v_cmp_gt_i32_e32 vcc, v90, v165
	v_pk_mul_f32 v[14:15], v[54:55], v[10:11]
	v_pk_mul_f32 v[10:11], v[50:51], v[8:9]
	v_cndmask_b32_e32 v22, v136, v84, vcc
	v_cmp_gt_i32_e32 vcc, v90, v142
	v_pk_mul_f32 v[30:31], v[72:73], v[22:23]
	v_pk_mul_f32 v[22:23], v[62:63], v[16:17]
	v_cndmask_b32_e32 v1, v133, v1, vcc
	v_cmp_gt_i32_e32 vcc, v90, v91
	s_nop 1
	v_cndmask_b32_e32 v0, v132, v0, vcc
	v_cmp_gt_i32_e32 vcc, v90, v145
	v_pk_mul_f32 v[0:1], v[40:41], v[0:1]
	s_nop 0
	v_cndmask_b32_e32 v5, v167, v5, vcc
	v_cmp_gt_i32_e32 vcc, v90, v77
	s_nop 1
	v_cndmask_b32_e32 v4, v166, v4, vcc
	v_cmp_gt_i32_e32 vcc, v90, v148
	v_pk_mul_f32 v[4:5], v[44:45], v[4:5]
	s_nop 0
	v_cndmask_b32_e32 v85, v141, v13, vcc
	v_cmp_gt_i32_e32 vcc, v90, v78
	s_nop 1
	v_cndmask_b32_e32 v84, v140, v12, vcc
	v_cmp_gt_i32_e32 vcc, v90, v151
	v_pk_mul_f32 v[8:9], v[48:49], v[84:85]
	s_nop 0
	v_cndmask_b32_e32 v13, v25, v21, vcc
	v_cmp_gt_i32_e32 vcc, v90, v79
	s_nop 1
	v_cndmask_b32_e32 v12, v24, v20, vcc
	v_cmp_gt_i32_e32 vcc, v90, v154
	v_pk_mul_f32 v[12:13], v[52:53], v[12:13]
	s_nop 0
	v_cndmask_b32_e32 v79, v111, v29, vcc
	v_cmp_gt_i32_e32 vcc, v90, v80
	s_nop 1
	v_cndmask_b32_e32 v78, v110, v28, vcc
	v_cmp_gt_i32_e32 vcc, v90, v157
	v_pk_mul_f32 v[16:17], v[56:57], v[78:79]
	s_nop 0
	v_cndmask_b32_e32 v21, v119, v115, vcc
	v_cmp_gt_i32_e32 vcc, v90, v81
	s_nop 1
	v_cndmask_b32_e32 v20, v118, v114, vcc
	v_cmp_gt_i32_e32 vcc, v90, v160
	v_pk_mul_f32 v[20:21], v[60:61], v[20:21]
	s_nop 0
	v_cndmask_b32_e32 v25, v127, v123, vcc
	v_cmp_gt_i32_e32 vcc, v90, v82
	s_nop 1
	v_cndmask_b32_e32 v24, v126, v122, vcc
	v_cmp_gt_i32_e32 vcc, v90, v163
	v_pk_mul_f32 v[24:25], v[66:67], v[24:25]
	s_nop 0
	v_cndmask_b32_e32 v29, v139, v131, vcc
	v_cmp_gt_i32_e32 vcc, v90, v83
	s_nop 1
	v_cndmask_b32_e32 v28, v138, v130, vcc
	v_pk_mul_f32 v[28:29], v[70:71], v[28:29]
.LBB0_1063:
	s_andn2_b64 vcc, exec, s[8:9]
	s_cbranch_vccnz .LBB0_1065
	s_waitcnt lgkmcnt(0)
	v_add_u32_e32 v28, 0x12200, v94
	ds_read_b128 v[80:83], v28
	ds_read_b128 v[112:115], v28 offset:64
	ds_read_b128 v[120:123], v28 offset:128
	ds_read_b128 v[148:151], v28 offset:192
	ds_read_b128 v[152:155], v28 offset:256
	ds_read_b128 v[156:159], v28 offset:320
	ds_read_b128 v[160:163], v28 offset:384
	ds_read_b128 v[164:167], v28 offset:448
	s_nop 0
	s_waitcnt lgkmcnt(7)
	v_pk_mul_f32 v[2:3], v[74:75], v[82:83] op_sel_hi:[0,1]
	s_nop 0
	s_waitcnt lgkmcnt(6)
	v_pk_mul_f32 v[6:7], v[74:75], v[114:115] op_sel_hi:[0,1]
	s_nop 0
	s_waitcnt lgkmcnt(5)
	v_pk_mul_f32 v[10:11], v[74:75], v[122:123] op_sel_hi:[0,1]
	s_nop 0
	s_waitcnt lgkmcnt(4)
	v_pk_mul_f32 v[14:15], v[74:75], v[150:151] op_sel_hi:[0,1]
	s_nop 0
	s_waitcnt lgkmcnt(3)
	v_pk_mul_f32 v[18:19], v[74:75], v[154:155] op_sel_hi:[0,1]
	s_nop 0
	s_waitcnt lgkmcnt(2)
	v_pk_mul_f32 v[22:23], v[74:75], v[158:159] op_sel_hi:[0,1]
	s_nop 0
	s_waitcnt lgkmcnt(1)
	v_pk_mul_f32 v[26:27], v[74:75], v[162:163] op_sel_hi:[0,1]
	s_nop 0
	s_waitcnt lgkmcnt(0)
	v_pk_mul_f32 v[30:31], v[74:75], v[166:167] op_sel_hi:[0,1]
	v_pk_mul_f32 v[0:1], v[74:75], v[80:81] op_sel_hi:[0,1]
	v_pk_mul_f32 v[4:5], v[74:75], v[112:113] op_sel_hi:[0,1]
	v_pk_mul_f32 v[8:9], v[74:75], v[120:121] op_sel_hi:[0,1]
	v_pk_mul_f32 v[12:13], v[74:75], v[148:149] op_sel_hi:[0,1]
	v_pk_mul_f32 v[16:17], v[74:75], v[152:153] op_sel_hi:[0,1]
	v_pk_mul_f32 v[20:21], v[74:75], v[156:157] op_sel_hi:[0,1]
	v_pk_mul_f32 v[24:25], v[74:75], v[160:161] op_sel_hi:[0,1]
	v_pk_mul_f32 v[28:29], v[74:75], v[164:165] op_sel_hi:[0,1]
	v_pk_mul_f32 v[28:29], v[70:71], v[28:29]
	v_pk_mul_f32 v[24:25], v[66:67], v[24:25]
	v_pk_mul_f32 v[20:21], v[60:61], v[20:21]
	v_pk_mul_f32 v[16:17], v[56:57], v[16:17]
	v_pk_mul_f32 v[12:13], v[52:53], v[12:13]
	v_pk_mul_f32 v[8:9], v[48:49], v[8:9]
	v_pk_mul_f32 v[4:5], v[44:45], v[4:5]
	v_pk_mul_f32 v[0:1], v[40:41], v[0:1]
	v_pk_mul_f32 v[30:31], v[72:73], v[30:31]
	v_pk_mul_f32 v[26:27], v[68:69], v[26:27]
	v_pk_mul_f32 v[22:23], v[62:63], v[22:23]
	v_pk_mul_f32 v[18:19], v[58:59], v[18:19]
	v_pk_mul_f32 v[14:15], v[54:55], v[14:15]
	v_pk_mul_f32 v[10:11], v[50:51], v[10:11]
	v_pk_mul_f32 v[6:7], v[46:47], v[6:7]
	v_pk_mul_f32 v[2:3], v[42:43], v[2:3]

.LBB0_1066:
	s_andn2_b64 vcc, exec, s[8:9]
	v_add_u32_e32 v110, 0x12000, v94
	s_cbranch_vccnz .LBB0_1068
	s_waitcnt lgkmcnt(0)
	ds_read_b128 v[80:83], v110
	ds_read_b128 v[112:115], v110 offset:64
	ds_read_b128 v[120:123], v110 offset:128
	ds_read_b128 v[148:151], v110 offset:192
	ds_read_b128 v[152:155], v110 offset:256
	ds_read_b128 v[156:159], v110 offset:320
	ds_read_b128 v[160:163], v110 offset:384
	ds_read_b128 v[164:167], v110 offset:448
	s_nop 0
	s_waitcnt lgkmcnt(7)
	v_pk_mul_f32 v[2:3], v[64:65], v[82:83] op_sel_hi:[0,1]
	s_nop 0
	s_waitcnt lgkmcnt(6)
	v_pk_mul_f32 v[6:7], v[64:65], v[114:115] op_sel_hi:[0,1]
	s_nop 0
	s_waitcnt lgkmcnt(5)
	v_pk_mul_f32 v[10:11], v[64:65], v[122:123] op_sel_hi:[0,1]
	s_nop 0
	s_waitcnt lgkmcnt(4)
	v_pk_mul_f32 v[14:15], v[64:65], v[150:151] op_sel_hi:[0,1]
	s_nop 0
	s_waitcnt lgkmcnt(3)
	v_pk_mul_f32 v[18:19], v[64:65], v[154:155] op_sel_hi:[0,1]
	s_nop 0
	s_waitcnt lgkmcnt(2)
	v_pk_mul_f32 v[22:23], v[64:65], v[158:159] op_sel_hi:[0,1]
	s_nop 0
	s_waitcnt lgkmcnt(1)
	v_pk_mul_f32 v[26:27], v[64:65], v[162:163] op_sel_hi:[0,1]
	s_nop 0
	s_waitcnt lgkmcnt(0)
	v_pk_mul_f32 v[30:31], v[64:65], v[166:167] op_sel_hi:[0,1]
	v_pk_mul_f32 v[0:1], v[64:65], v[80:81] op_sel_hi:[0,1]
	v_pk_mul_f32 v[4:5], v[64:65], v[112:113] op_sel_hi:[0,1]
	v_pk_mul_f32 v[8:9], v[64:65], v[120:121] op_sel_hi:[0,1]
	v_pk_mul_f32 v[12:13], v[64:65], v[148:149] op_sel_hi:[0,1]
	v_pk_mul_f32 v[16:17], v[64:65], v[152:153] op_sel_hi:[0,1]
	v_pk_mul_f32 v[20:21], v[64:65], v[156:157] op_sel_hi:[0,1]
	v_pk_mul_f32 v[24:25], v[64:65], v[160:161] op_sel_hi:[0,1]
	v_pk_mul_f32 v[28:29], v[64:65], v[164:165] op_sel_hi:[0,1]
	v_pk_mul_f32 v[28:29], v[70:71], v[28:29]
	v_pk_mul_f32 v[24:25], v[66:67], v[24:25]
	v_pk_mul_f32 v[20:21], v[60:61], v[20:21]
	v_pk_mul_f32 v[16:17], v[56:57], v[16:17]
	v_pk_mul_f32 v[12:13], v[52:53], v[12:13]
	v_pk_mul_f32 v[8:9], v[48:49], v[8:9]
	v_pk_mul_f32 v[4:5], v[44:45], v[4:5]
	v_pk_mul_f32 v[0:1], v[40:41], v[0:1]
	v_pk_mul_f32 v[30:31], v[72:73], v[30:31]
	v_pk_mul_f32 v[26:27], v[68:69], v[26:27]
	v_pk_mul_f32 v[22:23], v[62:63], v[22:23]
	v_pk_mul_f32 v[18:19], v[58:59], v[18:19]
	v_pk_mul_f32 v[14:15], v[54:55], v[14:15]
	v_pk_mul_f32 v[10:11], v[50:51], v[10:11]
	v_pk_mul_f32 v[6:7], v[46:47], v[6:7]
	v_pk_mul_f32 v[2:3], v[42:43], v[2:3]
.LBB0_1068:
	s_waitcnt lgkmcnt(0)
	v_lshrrev_b32_e32 v40, 2, v75
	v_or_b32_e32 v40, v91, v40
	v_lshlrev_b32_e32 v41, 3, v75
	v_and_b32_e32 v41, 24, v41
	v_mul_u32_u24_e32 v40, 0x90, v40
	v_add3_u32 v64, 0, v41, v40
	ds_read_b64_tr_b16 v[62:63], v64 offset:20736
	ds_read_b64_tr_b16 v[60:61], v64 offset:18432
	ds_read_b64_tr_b16 v[68:69], v64 offset:18464
	ds_read_b64_tr_b16 v[70:71], v64 offset:20768
	ds_read_b64_tr_b16 v[80:81], v64 offset:18496
	ds_read_b64_tr_b16 v[82:83], v64 offset:20800
	ds_read_b64_tr_b16 v[112:113], v64 offset:18528
	ds_read_b64_tr_b16 v[114:115], v64 offset:20832
	v_cvt_pk_bf16_f32 v42, v4, v5
	v_cvt_pk_bf16_f32 v8, v8, v9
	v_cvt_pk_bf16_f32 v9, v10, v11
	v_cvt_pk_bf16_f32 v10, v12, v13
	v_cvt_pk_bf16_f32 v11, v14, v15
	v_cvt_pk_bf16_f32 v4, v16, v17
	v_cvt_pk_bf16_f32 v5, v18, v19
	s_nop 0
	s_nop 0
	s_nop 0
	s_nop 0
	v_cvt_pk_bf16_f32 v40, v0, v1
	v_cvt_pk_bf16_f32 v41, v2, v3
	v_cvt_pk_bf16_f32 v43, v6, v7
	v_cvt_pk_bf16_f32 v6, v20, v21
	v_cvt_pk_bf16_f32 v7, v22, v23
	v_cvt_pk_bf16_f32 v0, v24, v25
	v_cvt_pk_bf16_f32 v1, v26, v27
	v_cvt_pk_bf16_f32 v2, v28, v29
	v_cvt_pk_bf16_f32 v3, v30, v31
	s_nop 0
	s_nop 0
	s_nop 0
	s_nop 0
	ds_read_b64_tr_b16 v[120:121], v64 offset:23040
	ds_read_b64_tr_b16 v[122:123], v64 offset:25344
	s_nop 0
	s_waitcnt lgkmcnt(8)
	v_mfma_f32_16x16x32_bf16 v[12:15], v[60:63], v[40:43], 0
	v_mul_u32_u24_e32 v56, 0x90, v75
	v_readfirstlane_b32 s11, v92
	s_mov_b64 s[8:9], -1
	s_nop 0
	s_waitcnt lgkmcnt(0)
	v_mfma_f32_16x16x32_bf16 v[12:15], v[120:123], v[8:11], v[12:15]
	ds_read_b64_tr_b16 v[60:61], v64 offset:23072
	ds_read_b64_tr_b16 v[62:63], v64 offset:25376
	s_cmpk_lt_i32 s11, 0x100
	v_mfma_f32_16x16x32_bf16 v[16:19], v[68:71], v[40:43], 0
	ds_read_b64_tr_b16 v[68:69], v64 offset:23104
	ds_read_b64_tr_b16 v[70:71], v64 offset:25408
	s_nop 0
	s_waitcnt lgkmcnt(2)
	v_mfma_f32_16x16x32_bf16 v[16:19], v[60:63], v[8:11], v[16:19]
	s_nop 0
	s_nop 0
	ds_read_b64_tr_b16 v[60:61], v64 offset:27648
	ds_read_b64_tr_b16 v[62:63], v64 offset:29952
	v_mfma_f32_16x16x32_bf16 v[20:23], v[80:83], v[40:43], 0
	ds_read_b64_tr_b16 v[80:81], v64 offset:27680
	ds_read_b64_tr_b16 v[82:83], v64 offset:29984
	s_nop 0
	s_waitcnt lgkmcnt(4)
	v_mfma_f32_16x16x32_bf16 v[20:23], v[68:71], v[8:11], v[20:23]
	ds_read_b64_tr_b16 v[68:69], v64 offset:27712
	ds_read_b64_tr_b16 v[70:71], v64 offset:30016
	ds_read_b64_tr_b16 v[28:29], v64 offset:23136
	ds_read_b64_tr_b16 v[30:31], v64 offset:25440
	v_mfma_f32_16x16x32_bf16 v[24:27], v[112:115], v[40:43], 0
	ds_read_b64_tr_b16 v[112:113], v64 offset:32256
	ds_read_b64_tr_b16 v[114:115], v64 offset:34560
	s_nop 0
	s_waitcnt lgkmcnt(2)
	v_mfma_f32_16x16x32_bf16 v[8:11], v[28:31], v[8:11], v[24:27]
	s_nop 5
	s_nop 0
	s_nop 0
	s_nop 0
	v_mfma_f32_16x16x32_bf16 v[12:15], v[60:63], v[4:7], v[12:15]
	s_nop 0
	s_nop 0
	ds_read_b64_tr_b16 v[60:61], v64 offset:32288
	ds_read_b64_tr_b16 v[62:63], v64 offset:34592
	s_nop 0
	v_mfma_f32_16x16x32_bf16 v[16:19], v[80:83], v[4:7], v[16:19]
	s_nop 0
	s_nop 0
	ds_read_b64_tr_b16 v[80:81], v64 offset:32320
	ds_read_b64_tr_b16 v[82:83], v64 offset:34624
	s_nop 0
	v_mfma_f32_16x16x32_bf16 v[20:23], v[68:71], v[4:7], v[20:23]
	ds_read_b64_tr_b16 v[24:25], v64 offset:27744
	ds_read_b64_tr_b16 v[26:27], v64 offset:30048
	s_nop 0
	s_waitcnt lgkmcnt(0)
	v_mfma_f32_16x16x32_bf16 v[4:7], v[24:27], v[4:7], v[8:11]
	s_nop 2
	s_nop 0
	s_nop 0
	s_nop 0
	v_mfma_f32_16x16x32_bf16 v[48:51], v[112:115], v[0:3], v[12:15]
	s_nop 0
	s_nop 0
	s_nop 0
	v_mfma_f32_16x16x32_bf16 v[52:55], v[60:63], v[0:3], v[16:19]
	s_nop 0
	s_nop 0
	s_nop 0
	v_add_u32_e32 v16, v94, v56
	s_nop 0
	v_mfma_f32_16x16x32_bf16 v[44:47], v[80:83], v[0:3], v[20:23]
	ds_read_b64_tr_b16 v[8:9], v64 offset:32352
	ds_read_b64_tr_b16 v[10:11], v64 offset:34656
	s_nop 0
	s_waitcnt lgkmcnt(0)
	s_barrier
	s_waitcnt lgkmcnt(0)
	ds_read_b128 v[112:115], v16 offset:41472
	ds_read_b128 v[120:123], v16 offset:41536
	ds_read_b128 v[148:151], v16 offset:36864
	ds_read_b128 v[152:155], v16 offset:36928
	ds_read_b128 v[156:159], v16 offset:39168
	ds_read_b128 v[160:163], v16 offset:43776
	ds_read_b128 v[164:167], v16 offset:43840
	ds_read_b128 v[168:171], v16 offset:46080
	v_mfma_f32_16x16x32_bf16 v[40:43], v[8:11], v[0:3], v[4:7]
	v_add_u32_e32 v8, 0xffffff80, v90
	v_cvt_f32_i32_e32 v8, v8
	s_nop 0
	s_nop 0
	s_nop 0
	s_waitcnt lgkmcnt(7)
	v_mfma_f32_16x16x32_bf16 v[0:3], v[112:115], v[32:35], 0
	ds_read_b128 v[112:115], v16 offset:46144
	v_mul_f32_e32 v17, v76, v8
	s_nop 0
	s_nop 0
	s_nop 0
	s_waitcnt lgkmcnt(6)
	v_mfma_f32_16x16x32_bf16 v[8:11], v[148:151], v[32:35], 0
	ds_read_b128 v[148:151], v16 offset:48384
	s_nop 0
	s_waitcnt lgkmcnt(6)
	v_mfma_f32_16x16x32_bf16 v[56:59], v[152:155], v[36:39], v[8:11]
	ds_read_b128 v[152:155], v16 offset:48448
	s_nop 5
	s_nop 0
	ds_read_b128 v[12:15], v16 offset:39232
	v_mfma_f32_16x16x32_bf16 v[66:69], v[120:123], v[36:39], v[0:3]
	ds_read_b128 v[120:123], v16 offset:50688
	s_nop 2
	s_nop 0
	s_nop 0
	s_nop 0
	s_waitcnt lgkmcnt(7)
	v_mfma_f32_16x16x32_bf16 v[0:3], v[160:163], v[32:35], 0
	ds_read_b128 v[160:163], v16 offset:50752
	s_nop 0
	s_waitcnt lgkmcnt(7)
	v_mfma_f32_16x16x32_bf16 v[70:73], v[164:167], v[36:39], v[0:3]
	ds_read_b128 v[164:167], v16 offset:52992
	s_nop 5
	s_nop 0
	s_nop 0
	s_nop 0
	s_waitcnt lgkmcnt(7)
	v_mfma_f32_16x16x32_bf16 v[0:3], v[168:171], v[32:35], 0
	s_nop 0
	s_waitcnt lgkmcnt(6)
	v_mfma_f32_16x16x32_bf16 v[74:77], v[112:115], v[36:39], v[0:3]
	s_nop 5
	s_nop 0
	s_nop 0
	s_nop 0
	s_waitcnt lgkmcnt(5)
	v_mfma_f32_16x16x32_bf16 v[0:3], v[148:151], v[32:35], 0
	s_nop 0
	s_waitcnt lgkmcnt(4)
	v_mfma_f32_16x16x32_bf16 v[78:81], v[152:155], v[36:39], v[0:3]
	s_nop 5
	s_nop 0
	s_nop 0
	s_nop 0
	s_waitcnt lgkmcnt(2)
	v_mfma_f32_16x16x32_bf16 v[0:3], v[120:123], v[32:35], 0
	s_nop 0
	s_waitcnt lgkmcnt(1)
	v_mfma_f32_16x16x32_bf16 v[82:85], v[160:163], v[36:39], v[0:3]
	s_nop 5
	s_nop 0
	ds_read_b128 v[4:7], v16 offset:53056
	v_mfma_f32_16x16x32_bf16 v[8:11], v[156:159], v[32:35], 0
	s_nop 0
	s_waitcnt lgkmcnt(1)
	v_mfma_f32_16x16x32_bf16 v[0:3], v[164:167], v[32:35], 0
	v_mfma_f32_16x16x32_bf16 v[60:63], v[12:15], v[36:39], v[8:11]
	s_nop 0
	s_waitcnt lgkmcnt(0)
	v_mfma_f32_16x16x32_bf16 v[32:35], v[4:7], v[36:39], v[0:3]
	v_exp_f32_e32 v36, v17
	s_cbranch_scc0 .LBB0_1074
	s_nop 2
	v_sub_u32_e32 v0, 0x80, v90
	v_cvt_f32_i32_e32 v0, v0
	s_cmpk_lt_i32 s11, 0x71
	v_add_u32_e32 v37, 0x12200, v94
	v_mul_f32_e32 v0, v93, v0
	v_exp_f32_e32 v38, v0
	s_cbranch_scc1 .LBB0_1071
	s_waitcnt lgkmcnt(0)
	ds_read_b128 v[160:163], v95
	ds_read_b128 v[164:167], v98
	ds_read_b128 v[168:171], v96
	ds_read_b128 v[172:175], v100
	ds_read_b128 v[176:179], v97
	ds_read_b128 v[184:187], v102
	ds_read_b128 v[200:203], v99
	ds_read_b128 v[204:207], v104
	ds_read_b128 v[216:219], v101
	ds_read_b128 v[220:223], v106
	ds_read_b128 v[224:227], v103
	ds_read_b128 v[240:243], v107
	ds_read_b128 v[244:247], v105
	ds_read_b128 v[248:251], v108
	ds_read_b128 v[120:123], v37
	ds_read_b128 v[124:127], v109
	v_or_b32_e32 v39, 0x81, v91
	v_or_b32_e32 v157, 0xf2, v91
	v_or_b32_e32 v156, 0xf3, v91
	s_nop 0
	s_waitcnt lgkmcnt(2)
	v_pk_mul_f32 v[108:109], v[36:37], v[250:251] op_sel_hi:[0,1]
	s_nop 0
	s_waitcnt lgkmcnt(1)
	v_pk_mul_f32 v[118:119], v[38:39], v[122:123] op_sel_hi:[0,1]
	s_nop 0
	s_waitcnt lgkmcnt(0)
	v_pk_mul_f32 v[122:123], v[38:39], v[126:127] op_sel_hi:[0,1]
	v_cmp_ne_u32_e32 vcc, v90, v157
	v_or_b32_e32 v153, 0xe2, v91
	v_or_b32_e32 v152, 0xe3, v91
	v_cndmask_b32_e32 v122, v237, v122, vcc
	v_cmp_ne_u32_e32 vcc, v90, v156
	v_pk_mul_f32 v[106:107], v[38:39], v[246:247] op_sel_hi:[0,1]
	v_or_b32_e32 v149, 0xd2, v91
	v_cndmask_b32_e32 v123, v237, v123, vcc
	v_cmp_ne_u32_e32 vcc, v90, v153
	v_or_b32_e32 v148, 0xd3, v91
	v_pk_mul_f32 v[102:103], v[38:39], v[226:227] op_sel_hi:[0,1]
	v_cndmask_b32_e32 v106, v237, v106, vcc
	v_cmp_ne_u32_e32 vcc, v90, v152
	v_or_b32_e32 v145, 0xc2, v91
	v_or_b32_e32 v144, 0xc3, v91
	v_cndmask_b32_e32 v107, v237, v107, vcc
	v_cmp_ne_u32_e32 vcc, v90, v149
	v_pk_mul_f32 v[94:95], v[38:39], v[218:219] op_sel_hi:[0,1]
	v_or_b32_e32 v141, 0xb2, v91
	v_cndmask_b32_e32 v102, v237, v102, vcc
	v_cmp_ne_u32_e32 vcc, v90, v148
	v_or_b32_e32 v140, 0xb3, v91
	v_pk_mul_f32 v[26:27], v[38:39], v[202:203] op_sel_hi:[0,1]
	v_cndmask_b32_e32 v103, v237, v103, vcc
	v_cmp_ne_u32_e32 vcc, v90, v145
	v_or_b32_e32 v137, 0xa2, v91
	v_or_b32_e32 v136, 0xa3, v91
	v_cndmask_b32_e32 v94, v237, v94, vcc
	v_cmp_ne_u32_e32 vcc, v90, v144
	v_pk_mul_f32 v[18:19], v[38:39], v[178:179] op_sel_hi:[0,1]
	v_or_b32_e32 v133, 0x92, v91
	v_cndmask_b32_e32 v95, v237, v95, vcc
	v_cmp_ne_u32_e32 vcc, v90, v141
	v_or_b32_e32 v132, 0x93, v91
	v_pk_mul_f32 v[10:11], v[38:39], v[170:171] op_sel_hi:[0,1]
	v_cndmask_b32_e32 v26, v237, v26, vcc
	v_cmp_ne_u32_e32 vcc, v90, v140
	v_or_b32_e32 v111, 0x80, v91
	v_pk_mul_f32 v[120:121], v[38:39], v[120:121] op_sel_hi:[0,1]
	v_cndmask_b32_e32 v27, v237, v27, vcc
	v_cmp_ne_u32_e32 vcc, v90, v137
	v_or_b32_e32 v129, 0x82, v91
	v_or_b32_e32 v128, 0x83, v91
	v_cndmask_b32_e32 v18, v237, v18, vcc
	v_cmp_ne_u32_e32 vcc, v90, v136
	v_or_b32_e32 v155, 0xf0, v91
	v_or_b32_e32 v154, 0xf1, v91
	v_cndmask_b32_e32 v19, v237, v19, vcc
	v_cmp_ne_u32_e32 vcc, v90, v133
	v_pk_mul_f32 v[124:125], v[38:39], v[124:125] op_sel_hi:[0,1]
	v_or_b32_e32 v151, 0xe0, v91
	v_cndmask_b32_e32 v10, v237, v10, vcc
	v_cmp_ne_u32_e32 vcc, v90, v132
	v_or_b32_e32 v150, 0xe1, v91
	v_pk_mul_f32 v[104:105], v[38:39], v[244:245] op_sel_hi:[0,1]
	v_cndmask_b32_e32 v11, v237, v11, vcc
	v_cmp_ne_u32_e32 vcc, v90, v111
	v_or_b32_e32 v147, 0xd0, v91
	v_or_b32_e32 v146, 0xd1, v91
	v_cndmask_b32_e32 v120, v237, v120, vcc
	v_cmp_ne_u32_e32 vcc, v90, v39
	v_pk_mul_f32 v[100:101], v[38:39], v[224:225] op_sel_hi:[0,1]
	v_or_b32_e32 v143, 0xc0, v91
	v_cndmask_b32_e32 v121, v237, v121, vcc
	v_cmp_ne_u32_e32 vcc, v90, v129
	v_or_b32_e32 v142, 0xc1, v91
	v_pk_mul_f32 v[92:93], v[38:39], v[216:217] op_sel_hi:[0,1]
	v_cndmask_b32_e32 v118, v237, v118, vcc
	v_cmp_ne_u32_e32 vcc, v90, v128
	v_or_b32_e32 v139, 0xb0, v91
	v_or_b32_e32 v138, 0xb1, v91
	v_cndmask_b32_e32 v119, v237, v119, vcc
	v_cmp_ne_u32_e32 vcc, v90, v155
	v_pk_mul_f32 v[24:25], v[38:39], v[200:201] op_sel_hi:[0,1]
	v_or_b32_e32 v135, 0xa0, v91
	v_cndmask_b32_e32 v124, v237, v124, vcc
	v_cmp_ne_u32_e32 vcc, v90, v154
	v_or_b32_e32 v134, 0xa1, v91
	v_pk_mul_f32 v[16:17], v[38:39], v[176:177] op_sel_hi:[0,1]
	v_cndmask_b32_e32 v125, v237, v125, vcc
	v_cmp_ne_u32_e32 vcc, v90, v151
	v_or_b32_e32 v131, 0x90, v91
	v_or_b32_e32 v130, 0x91, v91
	v_cndmask_b32_e32 v104, v237, v104, vcc
	v_cmp_ne_u32_e32 vcc, v90, v150
	v_pk_mul_f32 v[8:9], v[38:39], v[168:169] op_sel_hi:[0,1]
	v_pk_mul_f32 v[2:3], v[36:37], v[162:163] op_sel_hi:[0,1]
	v_cndmask_b32_e32 v105, v237, v105, vcc
	v_cmp_ne_u32_e32 vcc, v90, v147
	v_pk_mul_f32 v[0:1], v[36:37], v[160:161] op_sel_hi:[0,1]
	v_pk_mul_f32 v[4:5], v[36:37], v[164:165] op_sel_hi:[0,1]
	v_cndmask_b32_e32 v100, v237, v100, vcc
	v_cmp_ne_u32_e32 vcc, v90, v146
	v_pk_mul_f32 v[6:7], v[36:37], v[166:167] op_sel_hi:[0,1]
	v_pk_mul_f32 v[12:13], v[36:37], v[172:173] op_sel_hi:[0,1]
	v_cndmask_b32_e32 v101, v237, v101, vcc
	v_cmp_ne_u32_e32 vcc, v90, v143
	v_pk_mul_f32 v[14:15], v[36:37], v[174:175] op_sel_hi:[0,1]
	v_pk_mul_f32 v[20:21], v[36:37], v[184:185] op_sel_hi:[0,1]
	v_cndmask_b32_e32 v92, v237, v92, vcc
	v_cmp_ne_u32_e32 vcc, v90, v142
	v_pk_mul_f32 v[22:23], v[36:37], v[186:187] op_sel_hi:[0,1]
	v_pk_mul_f32 v[28:29], v[36:37], v[204:205] op_sel_hi:[0,1]
	v_cndmask_b32_e32 v93, v237, v93, vcc
	v_cmp_ne_u32_e32 vcc, v90, v139
	v_pk_mul_f32 v[30:31], v[36:37], v[206:207] op_sel_hi:[0,1]
	v_pk_mul_f32 v[96:97], v[36:37], v[220:221] op_sel_hi:[0,1]
	v_cndmask_b32_e32 v24, v237, v24, vcc
	v_cmp_ne_u32_e32 vcc, v90, v138
	v_pk_mul_f32 v[98:99], v[36:37], v[222:223] op_sel_hi:[0,1]
	v_pk_mul_f32 v[112:113], v[36:37], v[240:241] op_sel_hi:[0,1]
	v_cndmask_b32_e32 v25, v237, v25, vcc
	v_cmp_ne_u32_e32 vcc, v90, v135
	v_pk_mul_f32 v[114:115], v[36:37], v[242:243] op_sel_hi:[0,1]
	v_pk_mul_f32 v[116:117], v[36:37], v[248:249] op_sel_hi:[0,1]
	v_cndmask_b32_e32 v16, v237, v16, vcc
	v_cmp_ne_u32_e32 vcc, v90, v134
	s_mov_b64 s[8:9], 0
	s_nop 0
	v_cndmask_b32_e32 v17, v237, v17, vcc
	v_cmp_ne_u32_e32 vcc, v90, v131
	s_nop 1
	v_cndmask_b32_e32 v8, v237, v8, vcc
	v_cmp_ne_u32_e32 vcc, v90, v130
	s_nop 1
	v_cndmask_b32_e32 v9, v237, v9, vcc
	v_cmp_gt_i32_e32 vcc, v90, v128
	s_nop 1
	v_cndmask_b32_e32 v3, v119, v3, vcc
	v_cmp_gt_i32_e32 vcc, v90, v129
	s_nop 1
	v_cndmask_b32_e32 v2, v118, v2, vcc
	v_cmp_gt_i32_e32 vcc, v90, v39
	v_pk_mul_f32 v[2:3], v[58:59], v[2:3]
	s_nop 0
	v_cndmask_b32_e32 v1, v121, v1, vcc
	v_cmp_gt_i32_e32 vcc, v90, v111
	s_nop 1
	v_cndmask_b32_e32 v0, v120, v0, vcc
	v_cmp_gt_i32_e32 vcc, v90, v130
	v_pk_mul_f32 v[0:1], v[56:57], v[0:1]
	s_nop 0
	v_cndmask_b32_e32 v5, v9, v5, vcc
	v_cmp_gt_i32_e32 vcc, v90, v131
	s_nop 1
	v_cndmask_b32_e32 v4, v8, v4, vcc
	v_cmp_gt_i32_e32 vcc, v90, v132
	v_pk_mul_f32 v[4:5], v[60:61], v[4:5]
	s_nop 0
	v_cndmask_b32_e32 v7, v11, v7, vcc
	v_cmp_gt_i32_e32 vcc, v90, v133
	s_nop 1
	v_cndmask_b32_e32 v6, v10, v6, vcc
	v_cmp_gt_i32_e32 vcc, v90, v134
	v_pk_mul_f32 v[6:7], v[62:63], v[6:7]
	s_nop 0
	v_cndmask_b32_e32 v9, v17, v13, vcc
	v_cmp_gt_i32_e32 vcc, v90, v135
	s_nop 1
	v_cndmask_b32_e32 v8, v16, v12, vcc
	v_cmp_gt_i32_e32 vcc, v90, v136
	v_pk_mul_f32 v[8:9], v[66:67], v[8:9]
	s_nop 0
	v_cndmask_b32_e32 v11, v19, v15, vcc
	v_cmp_gt_i32_e32 vcc, v90, v137
	s_nop 1
	v_cndmask_b32_e32 v10, v18, v14, vcc
	v_cmp_gt_i32_e32 vcc, v90, v138
	v_pk_mul_f32 v[10:11], v[68:69], v[10:11]
	s_nop 0
	v_cndmask_b32_e32 v13, v25, v21, vcc
	v_cmp_gt_i32_e32 vcc, v90, v139
	s_nop 1
	v_cndmask_b32_e32 v12, v24, v20, vcc
	v_cmp_gt_i32_e32 vcc, v90, v140
	v_pk_mul_f32 v[12:13], v[70:71], v[12:13]
	s_nop 0
	v_cndmask_b32_e32 v15, v27, v23, vcc
	v_cmp_gt_i32_e32 vcc, v90, v141
	s_nop 1
	v_cndmask_b32_e32 v14, v26, v22, vcc
	v_cmp_gt_i32_e32 vcc, v90, v142
	v_pk_mul_f32 v[14:15], v[72:73], v[14:15]
	s_nop 0
	v_cndmask_b32_e32 v17, v93, v29, vcc
	v_cmp_gt_i32_e32 vcc, v90, v143
	s_nop 1
	v_cndmask_b32_e32 v16, v92, v28, vcc
	v_cmp_gt_i32_e32 vcc, v90, v144
	v_pk_mul_f32 v[16:17], v[74:75], v[16:17]
	s_nop 0
	v_cndmask_b32_e32 v19, v95, v31, vcc
	v_cmp_gt_i32_e32 vcc, v90, v145
	s_nop 1
	v_cndmask_b32_e32 v18, v94, v30, vcc
	v_cmp_gt_i32_e32 vcc, v90, v146
	v_pk_mul_f32 v[18:19], v[76:77], v[18:19]
	s_nop 0
	v_cndmask_b32_e32 v21, v101, v97, vcc
	v_cmp_gt_i32_e32 vcc, v90, v147
	s_nop 1
	v_cndmask_b32_e32 v20, v100, v96, vcc
	v_cmp_gt_i32_e32 vcc, v90, v148
	v_pk_mul_f32 v[20:21], v[78:79], v[20:21]
	s_nop 0
	v_cndmask_b32_e32 v23, v103, v99, vcc
	v_cmp_gt_i32_e32 vcc, v90, v149
	s_nop 1
	v_cndmask_b32_e32 v22, v102, v98, vcc
	v_cmp_gt_i32_e32 vcc, v90, v150
	v_pk_mul_f32 v[22:23], v[80:81], v[22:23]
	s_nop 0
	v_cndmask_b32_e32 v25, v105, v113, vcc
	v_cmp_gt_i32_e32 vcc, v90, v151
	s_nop 1
	v_cndmask_b32_e32 v24, v104, v112, vcc
	v_cmp_gt_i32_e32 vcc, v90, v152
	v_pk_mul_f32 v[24:25], v[82:83], v[24:25]
	s_nop 0
	v_cndmask_b32_e32 v27, v107, v115, vcc
	v_cmp_gt_i32_e32 vcc, v90, v153
	s_nop 1
	v_cndmask_b32_e32 v26, v106, v114, vcc
	v_cmp_gt_i32_e32 vcc, v90, v154
	v_pk_mul_f32 v[26:27], v[84:85], v[26:27]
	s_nop 0
	v_cndmask_b32_e32 v29, v125, v117, vcc
	v_cmp_gt_i32_e32 vcc, v90, v155
	s_nop 1
	v_cndmask_b32_e32 v28, v124, v116, vcc
	v_cmp_gt_i32_e32 vcc, v90, v156
	v_pk_mul_f32 v[28:29], v[32:33], v[28:29]
	s_nop 0
	v_cndmask_b32_e32 v31, v123, v109, vcc
	v_cmp_gt_i32_e32 vcc, v90, v157
	s_nop 1
	v_cndmask_b32_e32 v30, v122, v108, vcc
	v_pk_mul_f32 v[30:31], v[34:35], v[30:31]
.LBB0_1071:
	s_andn2_b64 vcc, exec, s[8:9]
	s_cbranch_vccnz .LBB0_1073
	s_waitcnt lgkmcnt(0)
	ds_read_b128 v[92:95], v37
	ds_read_b128 v[96:99], v37 offset:64
	ds_read_b128 v[100:103], v37 offset:128
	ds_read_b128 v[104:107], v37 offset:192
	ds_read_b128 v[112:115], v37 offset:256
	ds_read_b128 v[120:123], v37 offset:320
	ds_read_b128 v[148:151], v37 offset:384
	ds_read_b128 v[152:155], v37 offset:448
	s_nop 0
	s_waitcnt lgkmcnt(7)
	v_pk_mul_f32 v[2:3], v[38:39], v[94:95] op_sel_hi:[0,1]
	s_nop 0
	s_waitcnt lgkmcnt(6)
	v_pk_mul_f32 v[6:7], v[38:39], v[98:99] op_sel_hi:[0,1]
	s_nop 0
	s_waitcnt lgkmcnt(5)
	v_pk_mul_f32 v[10:11], v[38:39], v[102:103] op_sel_hi:[0,1]
	s_nop 0
	s_waitcnt lgkmcnt(4)
	v_pk_mul_f32 v[14:15], v[38:39], v[106:107] op_sel_hi:[0,1]
	s_nop 0
	s_waitcnt lgkmcnt(3)
	v_pk_mul_f32 v[18:19], v[38:39], v[114:115] op_sel_hi:[0,1]
	s_nop 0
	s_waitcnt lgkmcnt(2)
	v_pk_mul_f32 v[22:23], v[38:39], v[122:123] op_sel_hi:[0,1]
	s_nop 0
	s_waitcnt lgkmcnt(1)
	v_pk_mul_f32 v[26:27], v[38:39], v[150:151] op_sel_hi:[0,1]
	s_nop 0
	s_waitcnt lgkmcnt(0)
	v_pk_mul_f32 v[30:31], v[38:39], v[154:155] op_sel_hi:[0,1]
	v_pk_mul_f32 v[0:1], v[38:39], v[92:93] op_sel_hi:[0,1]
	v_pk_mul_f32 v[4:5], v[38:39], v[96:97] op_sel_hi:[0,1]
	v_pk_mul_f32 v[8:9], v[38:39], v[100:101] op_sel_hi:[0,1]
	v_pk_mul_f32 v[12:13], v[38:39], v[104:105] op_sel_hi:[0,1]
	v_pk_mul_f32 v[16:17], v[38:39], v[112:113] op_sel_hi:[0,1]
	v_pk_mul_f32 v[20:21], v[38:39], v[120:121] op_sel_hi:[0,1]
	v_pk_mul_f32 v[24:25], v[38:39], v[148:149] op_sel_hi:[0,1]
	v_pk_mul_f32 v[28:29], v[38:39], v[152:153] op_sel_hi:[0,1]
	v_pk_mul_f32 v[28:29], v[32:33], v[28:29]
	v_pk_mul_f32 v[24:25], v[82:83], v[24:25]
	v_pk_mul_f32 v[20:21], v[78:79], v[20:21]
	v_pk_mul_f32 v[16:17], v[74:75], v[16:17]
	v_pk_mul_f32 v[12:13], v[70:71], v[12:13]
	v_pk_mul_f32 v[8:9], v[66:67], v[8:9]
	v_pk_mul_f32 v[4:5], v[60:61], v[4:5]
	v_pk_mul_f32 v[0:1], v[56:57], v[0:1]
	v_pk_mul_f32 v[30:31], v[34:35], v[30:31]
	v_pk_mul_f32 v[26:27], v[84:85], v[26:27]
	v_pk_mul_f32 v[22:23], v[80:81], v[22:23]
	v_pk_mul_f32 v[18:19], v[76:77], v[18:19]
	v_pk_mul_f32 v[14:15], v[72:73], v[14:15]
	v_pk_mul_f32 v[10:11], v[68:69], v[10:11]
	v_pk_mul_f32 v[6:7], v[62:63], v[6:7]
	v_pk_mul_f32 v[2:3], v[58:59], v[2:3]

.LBB0_1074:
	s_andn2_b64 vcc, exec, s[8:9]
	s_cbranch_vccnz .LBB0_1076
	s_waitcnt lgkmcnt(0)
	ds_read_b128 v[92:95], v110
	ds_read_b128 v[96:99], v110 offset:64
	ds_read_b128 v[100:103], v110 offset:128
	ds_read_b128 v[104:107], v110 offset:192
	ds_read_b128 v[112:115], v110 offset:256
	ds_read_b128 v[120:123], v110 offset:320
	ds_read_b128 v[148:151], v110 offset:384
	ds_read_b128 v[152:155], v110 offset:448
	s_nop 0
	s_nop 0
	s_nop 0
	s_nop 0
	s_nop 0
	s_nop 0
	s_nop 0
	s_nop 0
	s_nop 0
	s_nop 0
	s_waitcnt lgkmcnt(7)
	v_pk_mul_f32 v[2:3], v[36:37], v[94:95] op_sel_hi:[0,1]
	s_nop 0
	s_waitcnt lgkmcnt(6)
	v_pk_mul_f32 v[6:7], v[36:37], v[98:99] op_sel_hi:[0,1]
	s_nop 0
	s_waitcnt lgkmcnt(5)
	v_pk_mul_f32 v[10:11], v[36:37], v[102:103] op_sel_hi:[0,1]
	s_nop 0
	s_waitcnt lgkmcnt(4)
	v_pk_mul_f32 v[14:15], v[36:37], v[106:107] op_sel_hi:[0,1]
	s_nop 0
	s_waitcnt lgkmcnt(3)
	v_pk_mul_f32 v[18:19], v[36:37], v[114:115] op_sel_hi:[0,1]
	s_nop 0
	s_waitcnt lgkmcnt(2)
	v_pk_mul_f32 v[22:23], v[36:37], v[122:123] op_sel_hi:[0,1]
	s_nop 0
	s_waitcnt lgkmcnt(1)
	v_pk_mul_f32 v[26:27], v[36:37], v[150:151] op_sel_hi:[0,1]
	s_nop 0
	s_waitcnt lgkmcnt(0)
	v_pk_mul_f32 v[30:31], v[36:37], v[154:155] op_sel_hi:[0,1]
	v_pk_mul_f32 v[0:1], v[36:37], v[92:93] op_sel_hi:[0,1]
	v_pk_mul_f32 v[4:5], v[36:37], v[96:97] op_sel_hi:[0,1]
	v_pk_mul_f32 v[8:9], v[36:37], v[100:101] op_sel_hi:[0,1]
	v_pk_mul_f32 v[12:13], v[36:37], v[104:105] op_sel_hi:[0,1]
	v_pk_mul_f32 v[16:17], v[36:37], v[112:113] op_sel_hi:[0,1]
	v_pk_mul_f32 v[20:21], v[36:37], v[120:121] op_sel_hi:[0,1]
	v_pk_mul_f32 v[24:25], v[36:37], v[148:149] op_sel_hi:[0,1]
	v_pk_mul_f32 v[28:29], v[36:37], v[152:153] op_sel_hi:[0,1]
	v_pk_mul_f32 v[28:29], v[32:33], v[28:29]
	v_pk_mul_f32 v[24:25], v[82:83], v[24:25]
	v_pk_mul_f32 v[20:21], v[78:79], v[20:21]
	v_pk_mul_f32 v[16:17], v[74:75], v[16:17]
	v_pk_mul_f32 v[12:13], v[70:71], v[12:13]
	v_pk_mul_f32 v[8:9], v[66:67], v[8:9]
	v_pk_mul_f32 v[4:5], v[60:61], v[4:5]
	v_pk_mul_f32 v[0:1], v[56:57], v[0:1]
	v_pk_mul_f32 v[30:31], v[34:35], v[30:31]
	v_pk_mul_f32 v[26:27], v[84:85], v[26:27]
	v_pk_mul_f32 v[22:23], v[80:81], v[22:23]
	v_pk_mul_f32 v[18:19], v[76:77], v[18:19]
	v_pk_mul_f32 v[14:15], v[72:73], v[14:15]
	v_pk_mul_f32 v[10:11], v[68:69], v[10:11]
	v_pk_mul_f32 v[6:7], v[62:63], v[6:7]
	v_pk_mul_f32 v[2:3], v[58:59], v[2:3]
.LBB0_1076:
	s_waitcnt lgkmcnt(0)
	ds_read_b64_tr_b16 v[94:95], v64 offset:57600
	ds_read_b64_tr_b16 v[92:93], v64 offset:55296
	ds_read_b64_tr_b16 v[96:97], v64 offset:55328
	ds_read_b64_tr_b16 v[98:99], v64 offset:57632
	ds_read_b64_tr_b16 v[100:101], v64 offset:55360
	ds_read_b64_tr_b16 v[102:103], v64 offset:57664
	ds_read_b64_tr_b16 v[104:105], v64 offset:55392
	ds_read_b64_tr_b16 v[106:107], v64 offset:57696
	s_nop 3
	v_cvt_pk_bf16_f32 v34, v4, v5
	v_cvt_pk_bf16_f32 v8, v8, v9
	v_cvt_pk_bf16_f32 v9, v10, v11
	v_cvt_pk_bf16_f32 v10, v12, v13
	v_cvt_pk_bf16_f32 v11, v14, v15
	v_cvt_pk_bf16_f32 v4, v16, v17
	v_cvt_pk_bf16_f32 v5, v18, v19
	s_nop 0
	s_nop 0
	s_nop 0
	s_nop 0
	v_cvt_pk_bf16_f32 v32, v0, v1
	v_cvt_pk_bf16_f32 v33, v2, v3
	v_cvt_pk_bf16_f32 v35, v6, v7
	v_cvt_pk_bf16_f32 v6, v20, v21
	v_cvt_pk_bf16_f32 v7, v22, v23
	v_cvt_pk_bf16_f32 v0, v24, v25
	v_cvt_pk_bf16_f32 v1, v26, v27
	v_cvt_pk_bf16_f32 v2, v28, v29
	v_cvt_pk_bf16_f32 v3, v30, v31
	s_nop 0
	s_nop 0
	s_nop 0
	s_nop 0
	ds_read_b64_tr_b16 v[108:109], v64 offset:59904
	ds_read_b64_tr_b16 v[110:111], v64 offset:62208
	s_nop 0
	s_waitcnt lgkmcnt(8)
	v_mfma_f32_16x16x32_bf16 v[12:15], v[92:95], v[32:35], v[48:51]
	v_add_u32_e32 v36, 0xd800, v64
	s_lshl_b32 s12, s45, 8
	s_ashr_i32 s13, s12, 31
	s_nop 0
	s_waitcnt lgkmcnt(0)
	v_mfma_f32_16x16x32_bf16 v[12:15], v[108:111], v[8:11], v[12:15]
	ds_read_b64_tr_b16 v[92:93], v64 offset:59936
	ds_read_b64_tr_b16 v[94:95], v64 offset:62240
	s_lshl_b64 s[12:13], s[12:13], 2
	v_mfma_f32_16x16x32_bf16 v[16:19], v[96:99], v[32:35], v[52:55]
	ds_read_b64_tr_b16 v[96:97], v64 offset:59968
	ds_read_b64_tr_b16 v[98:99], v64 offset:62272
	s_nop 0
	s_waitcnt lgkmcnt(2)
	v_mfma_f32_16x16x32_bf16 v[16:19], v[92:95], v[8:11], v[16:19]
	s_nop 0
	s_nop 0
	ds_read_b64_tr_b16 v[92:93], v64 offset:60000
	ds_read_b64_tr_b16 v[94:95], v64 offset:62304
	v_mfma_f32_16x16x32_bf16 v[20:23], v[100:103], v[32:35], v[44:47]
	ds_read_b64_tr_b16 v[100:101], v64 offset:64512
	ds_read_b64_tr_b16 v[102:103], v36 offset:11520
	s_nop 0
	s_waitcnt lgkmcnt(4)
	v_mfma_f32_16x16x32_bf16 v[20:23], v[96:99], v[8:11], v[20:23]
	s_nop 0
	s_nop 0
	ds_read_b64_tr_b16 v[112:113], v36 offset:11552
	ds_read_b64_tr_b16 v[110:111], v64 offset:64544
	v_mfma_f32_16x16x32_bf16 v[24:27], v[104:107], v[32:35], v[40:43]
	ds_read_b64_tr_b16 v[96:97], v64 offset:64576
	ds_read_b64_tr_b16 v[98:99], v36 offset:11584
	s_nop 0
	s_waitcnt lgkmcnt(6)
	v_mfma_f32_16x16x32_bf16 v[8:11], v[92:95], v[8:11], v[24:27]
	ds_read_b64_tr_b16 v[92:93], v64 offset:64608
	ds_read_b64_tr_b16 v[94:95], v36 offset:11616
	s_nop 5
	s_nop 0
	s_nop 0
	s_nop 0
	s_nop 0
	s_waitcnt lgkmcnt(6)
	v_mfma_f32_16x16x32_bf16 v[12:15], v[100:103], v[4:7], v[12:15]
	s_nop 0
	ds_read_b64_tr_b16 v[100:101], v36 offset:13824
	ds_read_b64_tr_b16 v[102:103], v36 offset:16128
	s_nop 0
	s_waitcnt lgkmcnt(6)
	v_mfma_f32_16x16x32_bf16 v[16:19], v[110:113], v[4:7], v[16:19]
	s_nop 0
	s_nop 0
	ds_read_b64_tr_b16 v[104:105], v36 offset:13856
	ds_read_b64_tr_b16 v[106:107], v36 offset:16160
	s_nop 0
	s_waitcnt lgkmcnt(6)
	v_mfma_f32_16x16x32_bf16 v[24:27], v[96:99], v[4:7], v[20:23]
	ds_read_b64_tr_b16 v[96:97], v36 offset:13888
	ds_read_b64_tr_b16 v[98:99], v36 offset:16192
	s_nop 2
	s_nop 0
	s_nop 0
	v_lshlrev_b32_e32 v64, 1, v91
	v_lshl_add_u64 v[34:35], v[88:89], 0, v[64:65]
	s_nop 0
	s_waitcnt lgkmcnt(6)
	v_mfma_f32_16x16x32_bf16 v[4:7], v[92:95], v[4:7], v[8:11]
	s_nop 2
	s_nop 0
	s_nop 0
	s_nop 0
	s_waitcnt lgkmcnt(4)
	v_mfma_f32_16x16x32_bf16 v[28:31], v[100:103], v[0:3], v[12:15]
	s_nop 0
	s_nop 0
	s_nop 0
	s_waitcnt lgkmcnt(2)
	v_mfma_f32_16x16x32_bf16 v[20:23], v[104:107], v[0:3], v[16:19]
	s_nop 0
	s_nop 0
	s_nop 0
	s_waitcnt lgkmcnt(0)
	v_mfma_f32_16x16x32_bf16 v[16:19], v[96:99], v[0:3], v[24:27]
	ds_read_b64_tr_b16 v[8:9], v36 offset:13920
	ds_read_b64_tr_b16 v[10:11], v36 offset:16224
	s_nop 0
	s_waitcnt lgkmcnt(0)
	s_barrier
	v_mfma_f32_16x16x32_bf16 v[4:7], v[8:11], v[0:3], v[4:7]
	v_add_f32_e32 v0, v28, v29
	v_add_f32_e32 v1, v30, v31
	v_add_f32_e32 v0, v0, v1
	v_add_f32_e32 v1, v20, v21
	v_add_f32_e32 v2, v22, v23
	v_add_f32_e32 v0, 0, v0
	v_add_f32_e32 v1, v1, v2
	v_add_f32_e32 v0, v0, v1
	v_add_f32_e32 v1, v16, v17
	v_add_f32_e32 v2, v18, v19
	v_add_f32_e32 v1, v1, v2
	v_add_f32_e32 v0, v0, v1
	v_add_f32_e32 v1, v4, v5
	v_add_f32_e32 v2, v6, v7
	s_load_dwordx2 s[8:9], s[0:1], 0x78
	v_add_f32_e32 v1, v1, v2
	v_add_f32_e32 v0, v0, v1
	v_mov_b32_e32 v1, v0
	s_nop 1
	v_permlane16_swap_b32_e32 v0, v1
	v_add_f32_e32 v0, v0, v1
	s_waitcnt lgkmcnt(0)
	s_add_u32 s8, s8, s12
	v_mov_b32_e32 v1, v0
	s_addc_u32 s9, s9, s13
	s_lshl_b32 s11, s10, 2
	v_permlane32_swap_b32_e32 v0, v1
	s_add_u32 s8, s8, s11
	v_add_f32_e32 v0, v0, v1
	s_addc_u32 s9, s9, 0
	v_lshlrev_b32_e32 v24, 2, v91
	v_mul_f32_e32 v32, 0x3c800000, v0
	global_load_dwordx4 v[0:3], v24, s[8:9]
	global_load_dwordx2 v[36:37], v[34:35], off offset:1536
	global_load_dwordx4 v[12:15], v24, s[8:9] offset:64
	global_load_dwordx2 v[46:47], v[34:35], off offset:1568
	global_load_dwordx4 v[8:11], v24, s[8:9] offset:128
	global_load_dwordx2 v[44:45], v[34:35], off offset:1600
	s_nop 0
	global_load_dwordx4 v[24:27], v24, s[8:9] offset:192
	s_nop 0
	global_load_dwordx2 v[38:39], v[34:35], off offset:1632
	v_pk_add_f32 v[30:31], v[30:31], v[32:33] op_sel_hi:[1,0] neg_lo:[0,1] neg_hi:[0,1]
	v_pk_add_f32 v[28:29], v[28:29], v[32:33] op_sel_hi:[1,0] neg_lo:[0,1] neg_hi:[0,1]
	v_lshlrev_b64 v[34:35], 11, v[86:87]
	v_mul_f32_e32 v42, v29, v29
	v_pk_fma_f32 v[42:43], v[28:29], v[28:29], v[42:43] op_sel_hi:[1,1,0]
	v_lshl_add_u64 v[34:35], s[6:7], 0, v[34:35]
	v_pk_fma_f32 v[42:43], v[30:31], v[30:31], v[42:43]
	s_lshl_b32 s96, s10, 1
	v_lshl_add_u64 v[34:35], v[34:35], 0, s[96:97]
	s_mov_b64 s[6:7], 0xf000000
	s_waitcnt vmcnt(6)
	v_lshlrev_b32_e32 v48, 16, v36
	v_mul_f32_e32 v33, 0xbfb8aa3b, v48
	v_exp_f32_e32 v33, v33
	v_and_b32_e32 v49, 0xffff0000, v36
	v_lshlrev_b32_e32 v40, 16, v37
	v_and_b32_e32 v41, 0xffff0000, v37
	v_add_f32_e32 v33, 1.0, v33
	v_rcp_f32_e32 v36, v33
	v_mul_f32_e32 v33, 0xbfb8aa3b, v49
	v_exp_f32_e32 v33, v33
	s_waitcnt vmcnt(4)
	v_lshlrev_b32_e32 v50, 16, v47
	v_and_b32_e32 v51, 0xffff0000, v47
	v_add_f32_e32 v33, 1.0, v33
	v_rcp_f32_e32 v37, v33
	v_mul_f32_e32 v33, 0xbfb8aa3b, v40
	v_exp_f32_e32 v33, v33
	v_pk_mul_f32 v[36:37], v[36:37], v[48:49]
	v_mul_f32_e32 v48, v31, v31
	v_add_f32_e32 v33, 1.0, v33
	v_pk_add_f32 v[48:49], v[48:49], v[42:43] op_sel_hi:[0,1]
	v_rcp_f32_e32 v42, v33
	v_mul_f32_e32 v33, 0xbfb8aa3b, v41
	v_exp_f32_e32 v33, v33
	s_nop 0
	v_add_f32_e32 v33, 1.0, v33
	v_pk_add_f32 v[20:21], v[20:21], v[32:33] op_sel_hi:[1,0] neg_lo:[0,1] neg_hi:[0,1]
	v_rcp_f32_e32 v43, v33
	v_pk_fma_f32 v[48:49], v[20:21], v[20:21], v[48:49]
	v_mul_f32_e32 v52, v21, v21
	v_pk_add_f32 v[48:49], v[52:53], v[48:49] op_sel_hi:[0,1]
	v_lshlrev_b32_e32 v52, 16, v46
	v_pk_add_f32 v[22:23], v[22:23], v[32:33] op_sel_hi:[1,0] neg_lo:[0,1] neg_hi:[0,1]
	v_mul_f32_e32 v33, 0xbfb8aa3b, v52
	v_exp_f32_e32 v33, v33
	v_and_b32_e32 v53, 0xffff0000, v46
	v_pk_fma_f32 v[48:49], v[22:23], v[22:23], v[48:49]
	v_pk_mul_f32 v[42:43], v[42:43], v[40:41]
	v_add_f32_e32 v33, 1.0, v33
	v_rcp_f32_e32 v46, v33
	v_mul_f32_e32 v33, 0xbfb8aa3b, v53
	v_exp_f32_e32 v33, v33
	v_lshl_add_u64 v[40:41], v[34:35], 0, v[64:65]
	v_lshl_add_u64 v[34:35], v[40:41], 0, s[6:7]
	s_mov_b32 s6, 0xf000000
	v_add_f32_e32 v33, 1.0, v33
	v_rcp_f32_e32 v47, v33
	v_mul_f32_e32 v33, 0xbfb8aa3b, v50
	v_exp_f32_e32 v33, v33
	v_pk_mul_f32 v[46:47], v[46:47], v[52:53]
	v_mul_f32_e32 v52, v23, v23
	v_add_f32_e32 v33, 1.0, v33
	v_pk_add_f32 v[48:49], v[52:53], v[48:49] op_sel_hi:[0,1]
	v_rcp_f32_e32 v52, v33
	v_mul_f32_e32 v33, 0xbfb8aa3b, v51
	v_exp_f32_e32 v33, v33
	s_nop 0
	v_add_f32_e32 v33, 1.0, v33
	v_pk_add_f32 v[16:17], v[16:17], v[32:33] op_sel_hi:[1,0] neg_lo:[0,1] neg_hi:[0,1]
	v_rcp_f32_e32 v53, v33
	v_pk_fma_f32 v[48:49], v[16:17], v[16:17], v[48:49]
	v_mul_f32_e32 v54, v17, v17
	v_pk_add_f32 v[48:49], v[54:55], v[48:49] op_sel_hi:[0,1]
	s_waitcnt vmcnt(2)
	v_lshlrev_b32_e32 v54, 16, v44
	v_pk_add_f32 v[18:19], v[18:19], v[32:33] op_sel_hi:[1,0] neg_lo:[0,1] neg_hi:[0,1]
	v_mul_f32_e32 v33, 0xbfb8aa3b, v54
	v_exp_f32_e32 v33, v33
	v_and_b32_e32 v55, 0xffff0000, v44
	v_pk_mul_f32 v[50:51], v[52:53], v[50:51]
	v_lshlrev_b32_e32 v52, 16, v45
	v_add_f32_e32 v33, 1.0, v33
	v_rcp_f32_e32 v44, v33
	v_mul_f32_e32 v33, 0xbfb8aa3b, v55
	v_exp_f32_e32 v33, v33
	v_and_b32_e32 v53, 0xffff0000, v45
	v_pk_fma_f32 v[48:49], v[18:19], v[18:19], v[48:49]
	v_add_f32_e32 v33, 1.0, v33
	v_rcp_f32_e32 v45, v33
	v_mul_f32_e32 v33, 0xbfb8aa3b, v52
	v_exp_f32_e32 v33, v33
	v_pk_mul_f32 v[44:45], v[44:45], v[54:55]
	v_mul_f32_e32 v54, v19, v19
	v_add_f32_e32 v33, 1.0, v33
	v_pk_add_f32 v[48:49], v[54:55], v[48:49] op_sel_hi:[0,1]
	v_rcp_f32_e32 v54, v33
	v_mul_f32_e32 v33, 0xbfb8aa3b, v53
	v_exp_f32_e32 v33, v33
	s_nop 0
	v_add_f32_e32 v33, 1.0, v33
	v_rcp_f32_e32 v55, v33
	v_pk_add_f32 v[4:5], v[4:5], v[32:33] op_sel_hi:[1,0] neg_lo:[0,1] neg_hi:[0,1]
	v_pk_add_f32 v[6:7], v[6:7], v[32:33] op_sel_hi:[1,0] neg_lo:[0,1] neg_hi:[0,1]
	v_pk_fma_f32 v[32:33], v[4:5], v[4:5], v[48:49]
	v_mul_f32_e32 v48, v5, v5
	v_pk_add_f32 v[32:33], v[48:49], v[32:33] op_sel_hi:[0,1]
	s_waitcnt vmcnt(0)
	v_lshlrev_b32_e32 v48, 16, v38
	v_and_b32_e32 v49, 0xffff0000, v38
	v_pk_mul_f32 v[52:53], v[54:55], v[52:53]
	v_lshlrev_b32_e32 v54, 16, v39
	v_and_b32_e32 v55, 0xffff0000, v39
	v_mul_f32_e32 v38, 0xbfb8aa3b, v48
	v_mul_f32_e32 v39, 0xbfb8aa3b, v49
	v_exp_f32_e32 v38, v38
	v_exp_f32_e32 v39, v39
	v_pk_fma_f32 v[32:33], v[6:7], v[6:7], v[32:33]
	v_add_f32_e32 v38, 1.0, v38
	v_add_f32_e32 v39, 1.0, v39
	v_rcp_f32_e32 v38, v38
	v_rcp_f32_e32 v39, v39
	s_nop 0
	v_pk_mul_f32 v[38:39], v[38:39], v[48:49]
	v_mul_f32_e32 v48, v7, v7
	v_pk_add_f32 v[32:33], v[48:49], v[32:33] op_sel_hi:[0,1]
	v_mov_b32_e32 v33, v32
	s_nop 1
	v_permlane16_swap_b32_e32 v32, v33
	v_add_f32_e32 v32, v32, v33
	v_mov_b32_e32 v33, v32
	s_nop 1
	v_permlane32_swap_b32_e32 v32, v33
	v_add_f32_e32 v32, v32, v33
	v_fmamk_f32 v32, v32, 0x3c800000, v229
	v_cmp_gt_f32_e32 vcc, s55, v32
	v_mul_f32_e32 v33, 0x4b800000, v32
	s_nop 0
	v_cndmask_b32_e32 v32, v32, v33, vcc
	v_rsq_f32_e32 v32, v32
	s_nop 0
	v_mul_f32_e32 v33, 0x45800000, v32
	v_cndmask_b32_e32 v32, v32, v33, vcc
	v_pk_mul_f32 v[28:29], v[28:29], v[32:33] op_sel_hi:[1,0]
	s_nop 0
	v_pk_mul_f32 v[0:1], v[0:1], v[28:29]
	v_pk_mul_f32 v[28:29], v[30:31], v[32:33] op_sel_hi:[1,0]
	v_pk_mul_f32 v[0:1], v[36:37], v[0:1]
	v_pk_mul_f32 v[2:3], v[2:3], v[28:29]
	v_cvt_pk_bf16_f32 v0, v0, v1
	v_pk_mul_f32 v[2:3], v[42:43], v[2:3]
	s_nop 0
	v_cvt_pk_bf16_f32 v1, v2, v3
	v_add_co_u32_e32 v2, vcc, s6, v40
	s_nop 1
	v_addc_co_u32_e32 v3, vcc, 0, v41, vcc
	global_store_dwordx2 v[2:3], v[0:1], off
	v_pk_mul_f32 v[0:1], v[20:21], v[32:33] op_sel_hi:[1,0]
	v_pk_mul_f32 v[2:3], v[22:23], v[32:33] op_sel_hi:[1,0]
	v_pk_mul_f32 v[0:1], v[12:13], v[0:1]
	v_pk_mul_f32 v[2:3], v[14:15], v[2:3]
	v_pk_mul_f32 v[0:1], v[0:1], v[46:47]
	v_pk_mul_f32 v[2:3], v[2:3], v[50:51]
	v_cvt_pk_bf16_f32 v0, v0, v1
	v_cvt_pk_bf16_f32 v1, v2, v3
	global_store_dwordx2 v[34:35], v[0:1], off offset:32
	v_pk_mul_f32 v[0:1], v[16:17], v[32:33] op_sel_hi:[1,0]
	v_pk_mul_f32 v[2:3], v[18:19], v[32:33] op_sel_hi:[1,0]
	v_pk_mul_f32 v[0:1], v[8:9], v[0:1]
	v_pk_mul_f32 v[2:3], v[10:11], v[2:3]
	v_pk_mul_f32 v[0:1], v[0:1], v[44:45]
	v_pk_mul_f32 v[2:3], v[2:3], v[52:53]
	v_cvt_pk_bf16_f32 v0, v0, v1
	v_cvt_pk_bf16_f32 v1, v2, v3
	v_mul_f32_e32 v2, 0xbfb8aa3b, v54
	v_mul_f32_e32 v3, 0xbfb8aa3b, v55
	v_exp_f32_e32 v2, v2
	v_exp_f32_e32 v3, v3
	global_store_dwordx2 v[34:35], v[0:1], off offset:64
	v_pk_mul_f32 v[0:1], v[4:5], v[32:33] op_sel_hi:[1,0]
	v_add_f32_e32 v2, 1.0, v2
	v_add_f32_e32 v3, 1.0, v3
	v_rcp_f32_e32 v2, v2
	v_rcp_f32_e32 v3, v3
	v_pk_mul_f32 v[4:5], v[6:7], v[32:33] op_sel_hi:[1,0]
	v_pk_mul_f32 v[0:1], v[24:25], v[0:1]
	v_pk_mul_f32 v[4:5], v[26:27], v[4:5]
	v_pk_mul_f32 v[2:3], v[2:3], v[54:55]
	v_pk_mul_f32 v[0:1], v[0:1], v[38:39]
	v_pk_mul_f32 v[2:3], v[4:5], v[2:3]
	v_cvt_pk_bf16_f32 v0, v0, v1
	v_cvt_pk_bf16_f32 v1, v2, v3
	global_store_dwordx2 v[34:35], v[0:1], off offset:96

.LBB0_1100:
	s_waitcnt lgkmcnt(0)
	ds_read_b64_tr_b16 v[152:153], v97 offset:57600
	ds_read_b64_tr_b16 v[150:151], v97 offset:55296
	ds_read_b64_tr_b16 v[154:155], v97 offset:55360
	ds_read_b64_tr_b16 v[156:157], v97 offset:57664
	ds_read_b64_tr_b16 v[160:161], v97 offset:59904
	ds_read_b64_tr_b16 v[162:163], v97 offset:62208
	ds_read_b64_tr_b16 v[164:165], v97 offset:59936
	ds_read_b64_tr_b16 v[166:167], v97 offset:62240
	v_exp_f32_e32 v84, v84
	v_exp_f32_e32 v87, v87
	v_exp_f32_e32 v88, v88
	v_exp_f32_e32 v89, v89
	v_add_f32_e32 v90, 0, v84
	v_exp_f32_e32 v86, v86
	v_add_f32_e32 v90, v87, v90
	v_exp_f32_e32 v85, v85
	v_add_f32_e32 v90, v88, v90
	v_exp_f32_e32 v83, v83
	v_add_f32_e32 v90, v89, v90
	v_exp_f32_e32 v82, v82
	v_add_f32_e32 v90, v86, v90
	v_exp_f32_e32 v81, v81
	v_add_f32_e32 v90, v85, v90
	v_exp_f32_e32 v80, v80
	v_add_f32_e32 v90, v83, v90
	v_exp_f32_e32 v79, v79
	v_add_f32_e32 v90, v82, v90
	v_exp_f32_e32 v78, v78
	v_add_f32_e32 v90, v90, v81
	v_exp_f32_e32 v77, v77
	v_add_f32_e32 v90, v80, v90
	v_exp_f32_e32 v76, v76
	v_add_f32_e32 v90, v79, v90
	v_exp_f32_e32 v75, v75
	v_add_f32_e32 v90, v78, v90
	v_exp_f32_e32 v74, v74
	v_add_f32_e32 v90, v77, v90
	v_exp_f32_e32 v15, v15
	v_add_f32_e32 v90, v76, v90
	v_exp_f32_e32 v14, v14
	v_add_f32_e32 v90, v75, v90
	v_exp_f32_e32 v13, v13
	v_add_f32_e32 v90, v74, v90
	v_exp_f32_e32 v91, v11
	v_add_f32_e32 v90, v15, v90
	v_add_f32_e32 v90, v14, v90
	v_add_f32_e32 v90, v13, v90
	v_add_f32_e32 v11, v91, v90
	v_exp_f32_e32 v90, v9
	v_exp_f32_e32 v92, v7
	v_exp_f32_e32 v93, v4
	v_exp_f32_e32 v116, v0
	v_add_f32_e32 v9, v90, v11
	v_add_f32_e32 v7, v92, v9
	v_add_f32_e32 v4, v93, v7
	v_exp_f32_e32 v123, v5
	v_exp_f32_e32 v124, v6
	v_cvt_pk_bf16_f32 v5, v79, v78
	v_cvt_pk_bf16_f32 v6, v77, v76
	v_cvt_pk_bf16_f32 v7, v75, v74
	s_nop 0
	s_nop 0
	ds_read_b64_tr_b16 v[78:79], v97 offset:55328
	v_exp_f32_e32 v125, v8
	v_exp_f32_e32 v126, v10
	v_cvt_pk_bf16_f32 v8, v84, v87
	v_cvt_pk_bf16_f32 v9, v88, v89
	v_cvt_pk_bf16_f32 v10, v86, v85
	v_cvt_pk_bf16_f32 v11, v83, v82
	v_add_f32_e32 v0, v116, v4
	v_cvt_pk_bf16_f32 v4, v81, v80
	s_nop 0
	s_waitcnt lgkmcnt(7)
	v_mfma_f32_16x16x32_bf16 v[16:19], v[150:153], v[8:11], v[16:19]
	ds_read_b64_tr_b16 v[148:149], v97 offset:59968
	ds_read_b64_tr_b16 v[150:151], v97 offset:62272
	ds_read_b64_tr_b16 v[80:81], v97 offset:57632
	s_nop 0
	s_nop 0
	v_exp_f32_e32 v120, v1
	s_nop 0
	s_waitcnt lgkmcnt(8)
	v_mfma_f32_16x16x32_bf16 v[24:27], v[154:157], v[8:11], v[24:27]
	ds_read_b64_tr_b16 v[152:153], v97 offset:60000
	ds_read_b64_tr_b16 v[154:155], v97 offset:62304
	ds_read_b64_tr_b16 v[74:75], v97 offset:55392
	ds_read_b64_tr_b16 v[76:77], v97 offset:57696
	v_exp_f32_e32 v121, v2
	v_exp_f32_e32 v122, v3
	s_waitcnt lgkmcnt(4)
	v_mfma_f32_16x16x32_bf16 v[20:23], v[78:81], v[8:11], v[20:23]
	v_add_f32_e32 v0, v120, v0
	v_add_f32_e32 v0, v121, v0
	v_add_f32_e32 v0, v122, v0
	s_nop 0
	s_waitcnt lgkmcnt(0)
	v_mfma_f32_16x16x32_bf16 v[8:11], v[74:77], v[8:11], v[28:31]
	s_nop 2
	s_nop 0
	s_nop 0
	v_add_f32_e32 v0, v123, v0
	v_exp_f32_e32 v127, v12
	s_nop 0
	v_mfma_f32_16x16x32_bf16 v[16:19], v[160:163], v[4:7], v[16:19]
	s_nop 0
	s_nop 0
	ds_read_b64_tr_b16 v[156:157], v97 offset:64512
	ds_read_b64_tr_b16 v[158:159], v110 offset:11520
	v_add_f32_e32 v0, v124, v0
	v_add_f32_e32 v0, v125, v0
	s_nop 0
	v_mfma_f32_16x16x32_bf16 v[20:23], v[164:167], v[4:7], v[20:23]
	s_nop 0
	s_nop 0
	ds_read_b64_tr_b16 v[160:161], v97 offset:64576
	ds_read_b64_tr_b16 v[162:163], v110 offset:11584
	v_add_f32_e32 v0, v126, v0
	v_add_f32_e32 v0, v127, v0
	s_nop 0
	v_mfma_f32_16x16x32_bf16 v[24:27], v[148:151], v[4:7], v[24:27]
	s_nop 0
	s_nop 0
	ds_read_b64_tr_b16 v[148:149], v97 offset:64608
	ds_read_b64_tr_b16 v[150:151], v110 offset:11616
	v_add_f32_e32 v119, v118, v0
	v_cvt_pk_bf16_f32 v0, v15, v14
	s_nop 0
	v_mfma_f32_16x16x32_bf16 v[4:7], v[152:155], v[4:7], v[8:11]
	ds_read_b64_tr_b16 v[152:153], v110 offset:13824
	ds_read_b64_tr_b16 v[154:155], v110 offset:16128
	s_nop 2
	s_nop 0
	s_nop 0
	ds_read_b64_tr_b16 v[30:31], v110 offset:11552
	ds_read_b64_tr_b16 v[28:29], v97 offset:64544
	v_cvt_pk_bf16_f32 v1, v13, v91
	v_cvt_pk_bf16_f32 v2, v90, v92
	v_cvt_pk_bf16_f32 v3, v93, v116
	v_cvt_pk_bf16_f32 v12, v120, v121
	v_cvt_pk_bf16_f32 v13, v122, v123
	s_nop 0
	s_waitcnt lgkmcnt(8)
	v_mfma_f32_16x16x32_bf16 v[8:11], v[156:159], v[0:3], v[16:19]
	ds_read_b64_tr_b16 v[156:157], v110 offset:13856
	ds_read_b64_tr_b16 v[158:159], v110 offset:16160
	v_cvt_pk_bf16_f32 v14, v124, v125
	v_cvt_pk_bf16_f32 v15, v126, v127
	v_mov_b32_e32 v116, v117
	s_nop 0
	s_waitcnt lgkmcnt(2)
	v_mfma_f32_16x16x32_bf16 v[16:19], v[28:31], v[0:3], v[20:23]
	s_nop 2
	s_nop 0
	s_nop 0
	s_nop 0
	v_mfma_f32_16x16x32_bf16 v[20:23], v[160:163], v[0:3], v[24:27]
	ds_read_b64_tr_b16 v[160:161], v110 offset:13888
	ds_read_b64_tr_b16 v[162:163], v110 offset:16192
	s_nop 2
	s_nop 0
	s_nop 0
	s_nop 0
	v_mfma_f32_16x16x32_bf16 v[24:27], v[148:151], v[0:3], v[4:7]
	s_nop 0
	s_nop 0
	s_nop 0
	s_nop 0
	s_nop 0
	s_nop 0
	v_mfma_f32_16x16x32_bf16 v[0:3], v[152:155], v[12:15], v[8:11]
	s_nop 2
	s_nop 0
	s_nop 0
	s_nop 0
	s_waitcnt lgkmcnt(2)
	v_mfma_f32_16x16x32_bf16 v[4:7], v[156:159], v[12:15], v[16:19]
	s_nop 2
	ds_read_b64_tr_b16 v[16:17], v110 offset:13920
	ds_read_b64_tr_b16 v[18:19], v110 offset:16224
	s_nop 0
	s_waitcnt lgkmcnt(2)
	v_mfma_f32_16x16x32_bf16 v[8:11], v[160:163], v[12:15], v[20:23]
	s_nop 0
	s_waitcnt lgkmcnt(0)
	v_mfma_f32_16x16x32_bf16 v[12:15], v[16:19], v[12:15], v[24:27]

.LBB0_1113:
	s_cmp_lt_i32 s19, s22
	s_cselect_b64 s[10:11], -1, 0
	s_cmp_ge_i32 s19, s22
	s_mov_b64 s[12:13], -1
	v_xor_b32_e32 v74, 0x80000000, v116
	s_cbranch_scc0 .LBB0_1117
	s_waitcnt lgkmcnt(0)
	ds_read_b128 v[120:123], v115
	ds_read_b128 v[148:151], v115 offset:64
	ds_read_b128 v[152:155], v115 offset:2304
	ds_read_b128 v[156:159], v115 offset:2368
	ds_read_b128 v[160:163], v115 offset:4672
	ds_read_b128 v[164:167], v115 offset:4608
	ds_read_b128 v[168:171], v115 offset:6912
	ds_read_b128 v[172:175], v115 offset:6976
	v_mov_b32_e32 v75, v74
	v_mov_b32_e32 v76, v74
	v_mov_b32_e32 v77, v74
	s_nop 0
	s_nop 0
	s_nop 0
	s_waitcnt lgkmcnt(5)
	v_mfma_f32_16x16x32_bf16 v[24:27], v[152:155], v[66:69], v[74:77]
	v_mov_b32_e32 v117, v116
	v_mfma_f32_16x16x32_bf16 v[16:19], v[120:123], v[66:69], v[74:77]
	v_mfma_f32_16x16x32_bf16 v[90:93], v[148:151], v[70:73], v[16:19]
	s_nop 0
	s_nop 5
	s_nop 0
	s_nop 0
	s_waitcnt lgkmcnt(4)
	v_mfma_f32_16x16x32_bf16 v[86:89], v[156:159], v[70:73], v[24:27]
	s_nop 0
	s_waitcnt lgkmcnt(2)
	v_mfma_f32_16x16x32_bf16 v[16:19], v[164:167], v[66:69], v[74:77]
	s_nop 0
	s_nop 0
	v_mfma_f32_16x16x32_bf16 v[78:81], v[160:163], v[70:73], v[16:19]
	v_max3_f32 v20, v92, v90, v91
	s_nop 1
	v_max3_f32 v28, v93, v20, v86
	s_nop 0
	s_nop 0
	s_nop 0
	s_waitcnt lgkmcnt(1)
	v_mfma_f32_16x16x32_bf16 v[20:23], v[168:171], v[66:69], v[74:77]
	v_max3_f32 v24, v88, v87, v28
	v_max3_f32 v24, v78, v89, v24
	v_max3_f32 v24, v80, v79, v24
	s_nop 0
	s_waitcnt lgkmcnt(0)
	v_mfma_f32_16x16x32_bf16 v[82:85], v[172:175], v[70:73], v[20:23]
	v_mov_b32_e32 v75, v119
	s_nop 6
	v_max3_f32 v16, v82, v81, v24
	v_max3_f32 v16, v84, v83, v16
	v_max_f32_e32 v17, v85, v85
	v_max_f32_e32 v16, v17, v16
	v_cmp_lt_f32_e32 vcc, s52, v16
	v_mov_b64_e32 v[30:31], v[14:15]
	v_mov_b64_e32 v[28:29], v[12:13]
	v_mov_b64_e32 v[26:27], v[10:11]
	v_mov_b64_e32 v[24:25], v[8:9]
	v_mov_b64_e32 v[22:23], v[6:7]
	v_mov_b64_e32 v[20:21], v[4:5]
	v_mov_b64_e32 v[18:19], v[2:3]
	v_mov_b64_e32 v[16:17], v[0:1]
	s_cbranch_vccz .LBB0_1116
	v_max_f32_e32 v16, v91, v91
	v_max_f32_e32 v17, v90, v90
	v_max_f32_e32 v16, v17, v16
	v_max3_f32 v16, v16, v92, v93
	v_max3_f32 v16, v16, v86, v87
	v_max3_f32 v16, v16, v88, v89
	v_max3_f32 v16, v16, v78, v79
	v_max3_f32 v16, v16, v80, v81
	v_max3_f32 v16, v16, v82, v83
	v_max3_f32 v16, v16, v84, v85
	v_mov_b32_e32 v17, v16
	s_nop 1
	v_permlane16_swap_b32_e32 v16, v17
	v_max_f32_e32 v17, v17, v17
	v_max_f32_e32 v16, v16, v16
	v_max_f32_e32 v16, v16, v17
	v_mov_b32_e32 v17, v16
	s_nop 1
	v_permlane32_swap_b32_e32 v16, v17
	v_max_f32_e32 v17, v17, v17
	v_max_f32_e32 v16, v16, v16
	v_max_f32_e32 v16, v16, v17
	v_cmp_lt_f32_e32 vcc, s52, v16
	s_nop 1
	v_cndmask_b32_e32 v16, 0, v16, vcc
	v_exp_f32_e64 v76, -v16
	v_add_f32_e32 v117, v116, v16
	v_pk_add_f32 v[90:91], v[90:91], v[16:17] op_sel_hi:[1,0] neg_lo:[0,1] neg_hi:[0,1]
	v_pk_add_f32 v[92:93], v[92:93], v[16:17] op_sel_hi:[1,0] neg_lo:[0,1] neg_hi:[0,1]
	v_mul_f32_e32 v75, v119, v76
	v_pk_add_f32 v[86:87], v[86:87], v[16:17] op_sel_hi:[1,0] neg_lo:[0,1] neg_hi:[0,1]
	v_pk_add_f32 v[88:89], v[88:89], v[16:17] op_sel_hi:[1,0] neg_lo:[0,1] neg_hi:[0,1]
	v_pk_add_f32 v[78:79], v[78:79], v[16:17] op_sel_hi:[1,0] neg_lo:[0,1] neg_hi:[0,1]
	v_pk_add_f32 v[80:81], v[80:81], v[16:17] op_sel_hi:[1,0] neg_lo:[0,1] neg_hi:[0,1]
	v_pk_add_f32 v[82:83], v[82:83], v[16:17] op_sel_hi:[1,0] neg_lo:[0,1] neg_hi:[0,1]
	v_pk_add_f32 v[84:85], v[84:85], v[16:17] op_sel_hi:[1,0] neg_lo:[0,1] neg_hi:[0,1]
	v_pk_mul_f32 v[30:31], v[14:15], v[76:77] op_sel_hi:[1,0]
	v_pk_mul_f32 v[28:29], v[12:13], v[76:77] op_sel_hi:[1,0]
	v_pk_mul_f32 v[26:27], v[10:11], v[76:77] op_sel_hi:[1,0]
	v_pk_mul_f32 v[24:25], v[8:9], v[76:77] op_sel_hi:[1,0]
	v_pk_mul_f32 v[22:23], v[6:7], v[76:77] op_sel_hi:[1,0]
	v_pk_mul_f32 v[20:21], v[4:5], v[76:77] op_sel_hi:[1,0]
	v_pk_mul_f32 v[18:19], v[2:3], v[76:77] op_sel_hi:[1,0]
	v_pk_mul_f32 v[16:17], v[0:1], v[76:77] op_sel_hi:[1,0]
.LBB0_1116:
	s_waitcnt lgkmcnt(0)
	ds_read_b64_tr_b16 v[150:151], v97 offset:20736
	ds_read_b64_tr_b16 v[148:149], v97 offset:18432
	ds_read_b64_tr_b16 v[152:153], v97 offset:18464
	ds_read_b64_tr_b16 v[154:155], v97 offset:20768
	ds_read_b64_tr_b16 v[156:157], v97 offset:18496
	ds_read_b64_tr_b16 v[158:159], v97 offset:20800
	ds_read_b64_tr_b16 v[160:161], v97 offset:23040
	ds_read_b64_tr_b16 v[162:163], v97 offset:25344
	v_exp_f32_e32 v76, v90
	v_exp_f32_e32 v90, v91
	v_exp_f32_e32 v91, v92
	v_exp_f32_e32 v92, v93
	v_add_f32_e32 v77, 0, v76
	v_exp_f32_e32 v86, v86
	v_add_f32_e32 v77, v90, v77
	v_exp_f32_e32 v87, v87
	v_add_f32_e32 v77, v91, v77
	v_exp_f32_e32 v88, v88
	v_add_f32_e32 v77, v92, v77
	v_exp_f32_e32 v89, v89
	v_add_f32_e32 v77, v86, v77
	v_exp_f32_e32 v78, v78
	v_add_f32_e32 v77, v87, v77
	v_exp_f32_e32 v79, v79
	v_add_f32_e32 v77, v88, v77
	v_exp_f32_e32 v93, v80
	v_add_f32_e32 v77, v89, v77
	v_exp_f32_e32 v120, v81
	v_add_f32_e32 v77, v78, v77
	v_exp_f32_e32 v121, v82
	v_add_f32_e32 v77, v79, v77
	v_exp_f32_e32 v122, v83
	v_add_f32_e32 v77, v93, v77
	v_exp_f32_e32 v84, v84
	v_add_f32_e32 v77, v120, v77
	v_exp_f32_e32 v85, v85
	v_add_f32_e32 v77, v121, v77
	v_add_f32_e32 v77, v122, v77
	v_add_f32_e32 v77, v84, v77
	v_add_f32_e32 v77, v85, v77
	v_cvt_pk_bf16_f32 v80, v76, v90
	v_cvt_pk_bf16_f32 v82, v86, v87
	v_cvt_pk_bf16_f32 v83, v88, v89
	v_cvt_pk_bf16_f32 v76, v78, v79
	v_cvt_pk_bf16_f32 v79, v84, v85
	s_nop 0
	s_nop 0
	s_nop 0
	v_cvt_pk_bf16_f32 v81, v91, v92
	s_nop 0
	v_add_f32_e32 v118, v75, v77
	s_nop 0
	s_waitcnt lgkmcnt(6)
	v_mfma_f32_16x16x32_bf16 v[16:19], v[148:151], v[80:83], v[16:19]
	s_nop 0
	s_nop 0
	ds_read_b64_tr_b16 v[148:149], v97 offset:23072
	ds_read_b64_tr_b16 v[150:151], v97 offset:25376
	v_cvt_pk_bf16_f32 v77, v93, v120
	v_cvt_pk_bf16_f32 v78, v121, v122
	s_nop 0
	s_waitcnt lgkmcnt(4)
	v_mfma_f32_16x16x32_bf16 v[24:27], v[156:159], v[80:83], v[24:27]
	ds_read_b64_tr_b16 v[156:157], v97 offset:23104
	ds_read_b64_tr_b16 v[158:159], v97 offset:25408
	ds_read_b64_tr_b16 v[84:85], v97 offset:18528
	ds_read_b64_tr_b16 v[86:87], v97 offset:20832
	s_mov_b64 s[12:13], 0
	v_mfma_f32_16x16x32_bf16 v[20:23], v[152:155], v[80:83], v[20:23]
	s_nop 0
	s_waitcnt lgkmcnt(0)
	v_mfma_f32_16x16x32_bf16 v[28:31], v[84:87], v[80:83], v[28:31]
	s_nop 0
	s_nop 0
	s_nop 0
	v_mfma_f32_16x16x32_bf16 v[16:19], v[160:163], v[76:79], v[16:19]
	s_nop 0
	s_nop 0
	s_nop 0
	v_mfma_f32_16x16x32_bf16 v[20:23], v[148:151], v[76:79], v[20:23]
	s_nop 0
	s_nop 0
	s_nop 0
	v_mfma_f32_16x16x32_bf16 v[24:27], v[156:159], v[76:79], v[24:27]
	ds_read_b64_tr_b16 v[80:81], v97 offset:23136
	ds_read_b64_tr_b16 v[82:83], v97 offset:25440
	s_nop 0
	s_waitcnt lgkmcnt(0)
	v_mfma_f32_16x16x32_bf16 v[28:31], v[80:83], v[76:79], v[28:31]
.LBB0_1117:
	s_and_b64 vcc, exec, s[12:13]
	s_cbranch_vccz .LBB0_1121
	s_waitcnt lgkmcnt(0)
	ds_read_b128 v[148:151], v115
	ds_read_b128 v[152:155], v115 offset:64
	ds_read_b128 v[156:159], v115 offset:2304
	ds_read_b128 v[160:163], v115 offset:2368
	ds_read_b128 v[164:167], v115 offset:4608
	ds_read_b128 v[168:171], v115 offset:4672
	ds_read_b128 v[172:175], v115 offset:6912
	ds_read_b128 v[178:181], v115 offset:6976
	v_mov_b32_e32 v75, v74
	v_mov_b32_e32 v76, v74
	v_mov_b32_e32 v77, v74
	v_readfirstlane_b32 s12, v95
	s_add_i32 s13, s14, s12
	s_nop 0
	s_waitcnt lgkmcnt(7)
	v_mfma_f32_16x16x32_bf16 v[16:19], v[148:151], v[66:69], v[74:77]
	ds_read_b128 v[186:189], v115 offset:9216
	s_add_i32 s24, s21, s15
	s_add_i32 s13, s13, s17
	s_sub_i32 s12, s24, s12
	s_nop 0
	s_waitcnt lgkmcnt(7)
	v_mfma_f32_16x16x32_bf16 v[16:19], v[152:155], v[70:73], v[16:19]
	s_nop 0
	s_nop 0
	ds_read_b128 v[150:153], v115 offset:9280
	s_add_i32 s13, s13, 15
	s_addk_i32 s12, 0x7f
	s_nop 0
	s_waitcnt lgkmcnt(7)
	v_mfma_f32_16x16x32_bf16 v[20:23], v[156:159], v[66:69], v[74:77]
	ds_read_b128 v[154:157], v115 offset:11520
	s_max_i32 s12, s13, s12
	v_add_u32_e32 v117, s17, v111
	s_cmpk_gt_i32 s12, 0x80
	s_nop 0
	s_waitcnt lgkmcnt(7)
	v_mfma_f32_16x16x32_bf16 v[20:23], v[160:163], v[70:73], v[20:23]
	s_nop 0
	s_nop 0
	ds_read_b128 v[158:161], v115 offset:11584
	s_cselect_b64 s[12:13], -1, 0
	s_movk_i32 s24, 0x100
	s_nop 0
	s_waitcnt lgkmcnt(7)
	v_mfma_f32_16x16x32_bf16 v[24:27], v[164:167], v[66:69], v[74:77]
	ds_read_b128 v[162:165], v115 offset:13824
	s_nop 0
	s_waitcnt lgkmcnt(7)
	v_mfma_f32_16x16x32_bf16 v[24:27], v[168:171], v[70:73], v[24:27]
	s_nop 0
	s_nop 0
	ds_read_b128 v[166:169], v115 offset:13888
	s_nop 0
	s_waitcnt lgkmcnt(7)
	v_mfma_f32_16x16x32_bf16 v[28:31], v[172:175], v[66:69], v[74:77]
	ds_read_b128 v[170:173], v115 offset:16128
	s_nop 0
	s_waitcnt lgkmcnt(7)
	v_mfma_f32_16x16x32_bf16 v[28:31], v[178:181], v[70:73], v[28:31]
	s_nop 0
	s_nop 0
	ds_read_b128 v[174:177], v115 offset:16192
	s_nop 0
	s_waitcnt lgkmcnt(7)
	v_mfma_f32_16x16x32_bf16 v[78:81], v[186:189], v[66:69], v[74:77]
	s_nop 0
	s_waitcnt lgkmcnt(6)
	v_mfma_f32_16x16x32_bf16 v[90:93], v[150:153], v[70:73], v[78:81]
	s_nop 5
	s_nop 0
	s_nop 0
	s_nop 0
	s_waitcnt lgkmcnt(5)
	v_mfma_f32_16x16x32_bf16 v[78:81], v[154:157], v[66:69], v[74:77]
	s_nop 0
	s_waitcnt lgkmcnt(4)
	v_mfma_f32_16x16x32_bf16 v[120:123], v[158:161], v[70:73], v[78:81]
	s_nop 5
	s_nop 0
	s_nop 0
	s_nop 0
	s_waitcnt lgkmcnt(3)
	v_mfma_f32_16x16x32_bf16 v[78:81], v[162:165], v[66:69], v[74:77]
	s_nop 0
	s_waitcnt lgkmcnt(2)
	v_mfma_f32_16x16x32_bf16 v[124:127], v[166:169], v[70:73], v[78:81]
	s_nop 5
	s_nop 0
	s_nop 0
	s_nop 0
	s_waitcnt lgkmcnt(1)
	v_mfma_f32_16x16x32_bf16 v[74:77], v[170:173], v[66:69], v[74:77]
	s_nop 0
	s_waitcnt lgkmcnt(0)
	v_mfma_f32_16x16x32_bf16 v[128:131], v[174:177], v[70:73], v[74:77]
	s_nop 5
	v_add_u32_e32 v74, 0xffffff7f, v117
	v_cmp_gt_u32_e32 vcc, s54, v74
	s_and_b64 vcc, s[12:13], vcc
	s_nop 0
	v_cndmask_b32_e32 v84, v16, v236, vcc
	v_add_u32_e32 v16, s15, v112
	v_add_u32_e32 v16, 0x81, v16
	v_cmp_lt_u32_e32 vcc, s24, v16
	s_and_b64 vcc, s[12:13], vcc
	v_add_u32_e32 v16, 0xffffff7d, v117
	v_cndmask_b32_e32 v87, v17, v236, vcc
	v_cmp_gt_u32_e32 vcc, s54, v16
	s_and_b64 vcc, s[12:13], vcc
	v_add_u32_e32 v16, 0xffffff7c, v117
	v_cndmask_b32_e32 v88, v18, v236, vcc
	v_cmp_gt_u32_e32 vcc, s54, v16
	s_and_b64 vcc, s[12:13], vcc
	v_add_u32_e32 v16, 0xffffff6f, v117
	v_cndmask_b32_e32 v89, v19, v236, vcc
	v_cmp_gt_u32_e32 vcc, s54, v16
	s_and_b64 vcc, s[12:13], vcc
	v_add_u32_e32 v16, 0xffffff6e, v117
	v_cndmask_b32_e32 v86, v20, v236, vcc
	v_cmp_gt_u32_e32 vcc, s54, v16
	s_and_b64 vcc, s[12:13], vcc
	v_add_u32_e32 v16, 0xffffff6d, v117
	v_cndmask_b32_e32 v85, v21, v236, vcc
	v_cmp_gt_u32_e32 vcc, s54, v16
	s_and_b64 vcc, s[12:13], vcc
	v_add_u32_e32 v16, 0xffffff6c, v117
	v_cndmask_b32_e32 v83, v22, v236, vcc
	v_cmp_gt_u32_e32 vcc, s54, v16
	s_and_b64 vcc, s[12:13], vcc
	v_add_u32_e32 v16, 0xffffff5f, v117
	v_cndmask_b32_e32 v82, v23, v236, vcc
	v_cmp_gt_u32_e32 vcc, s54, v16
	s_and_b64 vcc, s[12:13], vcc
	v_add_u32_e32 v16, 0xffffff5e, v117
	v_cndmask_b32_e32 v81, v24, v236, vcc
	v_cmp_gt_u32_e32 vcc, s54, v16
	s_and_b64 vcc, s[12:13], vcc
	v_add_u32_e32 v16, 0xffffff5d, v117
	v_cndmask_b32_e32 v80, v25, v236, vcc
	v_cmp_gt_u32_e32 vcc, s54, v16
	s_and_b64 vcc, s[12:13], vcc
	v_add_u32_e32 v16, 0xffffff5c, v117
	v_cndmask_b32_e32 v79, v26, v236, vcc
	v_cmp_gt_u32_e32 vcc, s54, v16
	s_and_b64 vcc, s[12:13], vcc
	v_add_u32_e32 v16, 0xffffff4f, v117
	v_cndmask_b32_e32 v78, v27, v236, vcc
	v_cmp_gt_u32_e32 vcc, s54, v16
	s_and_b64 vcc, s[12:13], vcc
	v_add_u32_e32 v16, 0xffffff4e, v117
	v_cndmask_b32_e32 v77, v28, v236, vcc
	v_cmp_gt_u32_e32 vcc, s54, v16
	s_and_b64 vcc, s[12:13], vcc
	v_add_u32_e32 v16, 0xffffff4d, v117
	v_cndmask_b32_e32 v76, v29, v236, vcc
	v_cmp_gt_u32_e32 vcc, s54, v16
	s_and_b64 vcc, s[12:13], vcc
	v_add_u32_e32 v16, 0xffffff4c, v117
	v_cndmask_b32_e32 v75, v30, v236, vcc
	v_cmp_gt_u32_e32 vcc, s54, v16
	s_and_b64 vcc, s[12:13], vcc
	v_add_u32_e32 v16, 0xffffff3f, v117
	v_cndmask_b32_e32 v74, v31, v236, vcc
	v_cmp_gt_u32_e32 vcc, s54, v16
	s_and_b64 vcc, s[12:13], vcc
	v_add_u32_e32 v16, 0xffffff3e, v117
	v_cndmask_b32_e32 v31, v90, v236, vcc
	v_cmp_gt_u32_e32 vcc, s54, v16
	s_and_b64 vcc, s[12:13], vcc
	v_add_u32_e32 v16, 0xffffff3d, v117
	v_cndmask_b32_e32 v30, v91, v236, vcc
	v_cmp_gt_u32_e32 vcc, s54, v16
	s_and_b64 vcc, s[12:13], vcc
	v_add_u32_e32 v16, 0xffffff3c, v117
	v_cndmask_b32_e32 v29, v92, v236, vcc
	v_cmp_gt_u32_e32 vcc, s54, v16
	s_and_b64 vcc, s[12:13], vcc
	v_add_u32_e32 v16, 0xffffff2f, v117
	v_cndmask_b32_e32 v27, v93, v236, vcc
	v_cmp_gt_u32_e32 vcc, s54, v16
	s_and_b64 vcc, s[12:13], vcc
	v_add_u32_e32 v16, 0xffffff2e, v117
	v_cndmask_b32_e32 v25, v120, v236, vcc
	v_cmp_gt_u32_e32 vcc, s54, v16
	s_and_b64 vcc, s[12:13], vcc
	v_add_u32_e32 v16, 0xffffff2d, v117
	v_cndmask_b32_e32 v23, v121, v236, vcc
	v_cmp_gt_u32_e32 vcc, s54, v16
	s_and_b64 vcc, s[12:13], vcc
	v_add_u32_e32 v16, 0xffffff2c, v117
	v_cndmask_b32_e32 v20, v122, v236, vcc
	v_cmp_gt_u32_e32 vcc, s54, v16
	s_and_b64 vcc, s[12:13], vcc
	v_add_u32_e32 v17, 0xffffff1f, v117
	v_cndmask_b32_e32 v16, v123, v236, vcc
	v_cmp_gt_u32_e32 vcc, s54, v17
	s_and_b64 vcc, s[12:13], vcc
	v_add_u32_e32 v18, 0xffffff1e, v117
	v_cndmask_b32_e32 v17, v124, v236, vcc
	v_cmp_gt_u32_e32 vcc, s54, v18
	s_and_b64 vcc, s[12:13], vcc
	v_add_u32_e32 v19, 0xffffff1d, v117
	v_max3_f32 v90, v88, v84, v87
	v_cndmask_b32_e32 v18, v125, v236, vcc
	v_cmp_gt_u32_e32 vcc, s54, v19
	v_max3_f32 v90, v86, v89, v90
	s_and_b64 vcc, s[12:13], vcc
	v_add_u32_e32 v21, 0xffffff1c, v117
	v_max3_f32 v90, v83, v85, v90
	v_cndmask_b32_e32 v19, v126, v236, vcc
	v_cmp_gt_u32_e32 vcc, s54, v21
	v_max3_f32 v90, v81, v82, v90
	s_and_b64 vcc, s[12:13], vcc
	v_add_u32_e32 v22, 0xffffff0f, v117
	v_max3_f32 v90, v79, v80, v90
	v_cndmask_b32_e32 v21, v127, v236, vcc
	v_cmp_gt_u32_e32 vcc, s54, v22
	v_max3_f32 v90, v77, v78, v90
	s_and_b64 vcc, s[12:13], vcc
	v_add_u32_e32 v24, 0xffffff0e, v117
	v_max3_f32 v90, v75, v76, v90
	v_cndmask_b32_e32 v22, v128, v236, vcc
	v_cmp_gt_u32_e32 vcc, s54, v24
	v_max3_f32 v90, v31, v74, v90
	s_and_b64 vcc, s[12:13], vcc
	v_add_u32_e32 v26, 0xffffff0d, v117
	v_max3_f32 v90, v29, v30, v90
	v_cndmask_b32_e32 v24, v129, v236, vcc
	v_cmp_gt_u32_e32 vcc, s54, v26
	v_max3_f32 v90, v25, v27, v90
	s_and_b64 vcc, s[12:13], vcc
	v_add_u32_e32 v28, 0xffffff0c, v117
	v_max3_f32 v90, v20, v23, v90
	v_cndmask_b32_e32 v26, v130, v236, vcc
	v_cmp_gt_u32_e32 vcc, s54, v28
	v_max3_f32 v90, v17, v16, v90
	s_and_b64 vcc, s[12:13], vcc
	v_max3_f32 v90, v19, v18, v90
	v_cndmask_b32_e32 v28, v131, v236, vcc
	v_max3_f32 v90, v22, v21, v90
	v_max3_f32 v90, v26, v24, v90
	v_max_f32_e32 v91, v28, v28
	v_max_f32_e32 v90, v91, v90
	v_cmp_lt_f32_e32 vcc, s52, v90
	s_cbranch_vccz .LBB0_1120
	v_max_f32_e32 v90, v87, v87
	v_max_f32_e32 v91, v84, v84
	v_max_f32_e32 v90, v91, v90
	v_max3_f32 v90, v90, v88, v89
	v_max3_f32 v90, v90, v86, v85
	v_max3_f32 v90, v90, v83, v82
	v_max3_f32 v90, v90, v81, v80
	v_max3_f32 v90, v90, v79, v78
	v_max3_f32 v90, v90, v77, v76
	v_max3_f32 v90, v90, v75, v74
	v_max3_f32 v90, v90, v31, v30
	v_max3_f32 v90, v90, v29, v27
	v_max3_f32 v90, v90, v25, v23
	v_max3_f32 v90, v90, v20, v16
	v_max3_f32 v90, v90, v17, v18
	v_max3_f32 v90, v90, v19, v21
	v_max3_f32 v90, v90, v22, v24
	v_max3_f32 v90, v90, v26, v28
	v_mov_b32_e32 v91, v90
	s_nop 1
	v_permlane16_swap_b32_e32 v90, v91
	v_max_f32_e32 v91, v91, v91
	v_max_f32_e32 v90, v90, v90
	v_max_f32_e32 v90, v90, v91
	v_mov_b32_e32 v91, v90
	s_nop 1
	v_permlane32_swap_b32_e32 v90, v91
	v_max_f32_e32 v91, v91, v91
	v_max_f32_e32 v90, v90, v90
	v_max_f32_e32 v90, v90, v91
	v_cmp_lt_f32_e32 vcc, s52, v90
	s_nop 1
	v_cndmask_b32_e32 v91, 0, v90, vcc
	v_exp_f32_e64 v90, -v91
	v_add_f32_e32 v116, v116, v91
	v_sub_f32_e32 v84, v84, v91
	v_sub_f32_e32 v87, v87, v91
	v_mul_f32_e32 v119, v119, v90
	v_sub_f32_e32 v88, v88, v91
	v_sub_f32_e32 v89, v89, v91
	v_sub_f32_e32 v86, v86, v91
	v_sub_f32_e32 v85, v85, v91
	v_sub_f32_e32 v83, v83, v91
	v_sub_f32_e32 v82, v82, v91
	v_sub_f32_e32 v81, v81, v91
	v_sub_f32_e32 v80, v80, v91
	v_sub_f32_e32 v79, v79, v91
	v_sub_f32_e32 v78, v78, v91
	v_sub_f32_e32 v77, v77, v91
	v_sub_f32_e32 v76, v76, v91
	v_sub_f32_e32 v75, v75, v91
	v_sub_f32_e32 v74, v74, v91
	v_sub_f32_e32 v31, v31, v91
	v_sub_f32_e32 v30, v30, v91
	v_sub_f32_e32 v29, v29, v91
	v_sub_f32_e32 v27, v27, v91
	v_sub_f32_e32 v25, v25, v91
	v_sub_f32_e32 v23, v23, v91
	v_sub_f32_e32 v20, v20, v91
	v_sub_f32_e32 v16, v16, v91
	v_sub_f32_e32 v17, v17, v91
	v_sub_f32_e32 v18, v18, v91
	v_sub_f32_e32 v19, v19, v91
	v_sub_f32_e32 v21, v21, v91
	v_sub_f32_e32 v22, v22, v91
	v_sub_f32_e32 v24, v24, v91
	v_sub_f32_e32 v26, v26, v91
	v_sub_f32_e32 v28, v28, v91
	v_pk_mul_f32 v[14:15], v[14:15], v[90:91] op_sel_hi:[1,0]
	v_pk_mul_f32 v[12:13], v[12:13], v[90:91] op_sel_hi:[1,0]
	v_pk_mul_f32 v[10:11], v[10:11], v[90:91] op_sel_hi:[1,0]
	v_pk_mul_f32 v[8:9], v[8:9], v[90:91] op_sel_hi:[1,0]
	v_pk_mul_f32 v[6:7], v[6:7], v[90:91] op_sel_hi:[1,0]
	v_pk_mul_f32 v[4:5], v[4:5], v[90:91] op_sel_hi:[1,0]
	v_pk_mul_f32 v[2:3], v[2:3], v[90:91] op_sel_hi:[1,0]
	v_pk_mul_f32 v[0:1], v[0:1], v[90:91] op_sel_hi:[1,0]
.LBB0_1120:
	s_waitcnt lgkmcnt(0)
	ds_read_b64_tr_b16 v[152:153], v97 offset:20736
	ds_read_b64_tr_b16 v[150:151], v97 offset:18432
	ds_read_b64_tr_b16 v[154:155], v97 offset:18496
	ds_read_b64_tr_b16 v[156:157], v97 offset:20800
	ds_read_b64_tr_b16 v[160:161], v97 offset:23040
	ds_read_b64_tr_b16 v[162:163], v97 offset:25344
	ds_read_b64_tr_b16 v[164:165], v97 offset:23072
	ds_read_b64_tr_b16 v[166:167], v97 offset:25376
	v_exp_f32_e32 v84, v84
	v_exp_f32_e32 v87, v87
	v_exp_f32_e32 v88, v88
	v_exp_f32_e32 v89, v89
	v_add_f32_e32 v90, 0, v84
	v_exp_f32_e32 v86, v86
	v_add_f32_e32 v90, v87, v90
	v_exp_f32_e32 v85, v85
	v_add_f32_e32 v90, v88, v90
	v_exp_f32_e32 v83, v83
	v_add_f32_e32 v90, v89, v90
	v_exp_f32_e32 v82, v82
	v_add_f32_e32 v90, v86, v90
	v_exp_f32_e32 v81, v81
	v_add_f32_e32 v90, v85, v90
	v_exp_f32_e32 v80, v80
	v_add_f32_e32 v90, v83, v90
	v_exp_f32_e32 v79, v79
	v_add_f32_e32 v90, v82, v90
	v_exp_f32_e32 v78, v78
	v_add_f32_e32 v90, v90, v81
	v_exp_f32_e32 v77, v77
	v_add_f32_e32 v90, v80, v90
	v_exp_f32_e32 v76, v76
	v_add_f32_e32 v90, v79, v90
	v_exp_f32_e32 v75, v75
	v_add_f32_e32 v90, v78, v90
	v_exp_f32_e32 v74, v74
	v_add_f32_e32 v90, v77, v90
	v_exp_f32_e32 v31, v31
	v_add_f32_e32 v90, v76, v90
	v_exp_f32_e32 v30, v30
	v_add_f32_e32 v90, v75, v90
	v_exp_f32_e32 v29, v29
	v_add_f32_e32 v90, v74, v90
	v_exp_f32_e32 v91, v27
	v_add_f32_e32 v90, v31, v90
	v_add_f32_e32 v90, v30, v90
	v_add_f32_e32 v90, v29, v90
	v_add_f32_e32 v27, v91, v90
	v_exp_f32_e32 v90, v25
	v_exp_f32_e32 v92, v23
	v_exp_f32_e32 v93, v20
	v_exp_f32_e32 v117, v16
	v_add_f32_e32 v25, v90, v27
	v_add_f32_e32 v23, v92, v25
	v_add_f32_e32 v20, v93, v23
	v_exp_f32_e32 v123, v21
	v_exp_f32_e32 v124, v22
	v_cvt_pk_bf16_f32 v21, v79, v78
	v_cvt_pk_bf16_f32 v22, v77, v76
	v_cvt_pk_bf16_f32 v23, v75, v74
	s_nop 0
	s_nop 0
	ds_read_b64_tr_b16 v[78:79], v97 offset:18464
	v_exp_f32_e32 v125, v24
	v_exp_f32_e32 v126, v26
	v_cvt_pk_bf16_f32 v24, v84, v87
	v_cvt_pk_bf16_f32 v25, v88, v89
	v_cvt_pk_bf16_f32 v26, v86, v85
	v_cvt_pk_bf16_f32 v27, v83, v82
	v_add_f32_e32 v16, v117, v20
	v_cvt_pk_bf16_f32 v20, v81, v80
	s_nop 0
	s_waitcnt lgkmcnt(7)
	v_mfma_f32_16x16x32_bf16 v[0:3], v[150:153], v[24:27], v[0:3]
	ds_read_b64_tr_b16 v[148:149], v97 offset:23104
	ds_read_b64_tr_b16 v[150:151], v97 offset:25408
	ds_read_b64_tr_b16 v[80:81], v97 offset:20768
	s_nop 0
	s_nop 0
	v_exp_f32_e32 v120, v17
	s_nop 0
	s_waitcnt lgkmcnt(8)
	v_mfma_f32_16x16x32_bf16 v[8:11], v[154:157], v[24:27], v[8:11]
	ds_read_b64_tr_b16 v[152:153], v97 offset:23136
	ds_read_b64_tr_b16 v[154:155], v97 offset:25440
	ds_read_b64_tr_b16 v[74:75], v97 offset:18528
	ds_read_b64_tr_b16 v[76:77], v97 offset:20832
	v_exp_f32_e32 v121, v18
	v_exp_f32_e32 v122, v19
	s_waitcnt lgkmcnt(4)
	v_mfma_f32_16x16x32_bf16 v[4:7], v[78:81], v[24:27], v[4:7]
	v_add_f32_e32 v16, v120, v16
	v_add_f32_e32 v16, v121, v16
	v_add_f32_e32 v16, v122, v16
	s_nop 0
	s_waitcnt lgkmcnt(0)
	v_mfma_f32_16x16x32_bf16 v[12:15], v[74:77], v[24:27], v[12:15]
	s_nop 0
	s_nop 0
	v_add_f32_e32 v16, v123, v16
	v_exp_f32_e32 v127, v28
	s_nop 0
	v_mfma_f32_16x16x32_bf16 v[0:3], v[160:163], v[20:23], v[0:3]
	s_nop 0
	s_nop 0
	ds_read_b64_tr_b16 v[156:157], v97 offset:27648
	ds_read_b64_tr_b16 v[158:159], v97 offset:29952
	v_add_f32_e32 v16, v124, v16
	v_add_f32_e32 v16, v125, v16
	s_nop 0
	v_mfma_f32_16x16x32_bf16 v[4:7], v[164:167], v[20:23], v[4:7]
	s_nop 0
	s_nop 0
	ds_read_b64_tr_b16 v[160:161], v97 offset:27680
	ds_read_b64_tr_b16 v[162:163], v97 offset:29984
	v_add_f32_e32 v16, v126, v16
	v_add_f32_e32 v16, v127, v16
	s_nop 0
	v_mfma_f32_16x16x32_bf16 v[8:11], v[148:151], v[20:23], v[8:11]
	s_nop 0
	s_nop 0
	ds_read_b64_tr_b16 v[148:149], v97 offset:27712
	ds_read_b64_tr_b16 v[150:151], v97 offset:30016
	v_add_f32_e32 v118, v119, v16
	v_cvt_pk_bf16_f32 v16, v31, v30
	s_nop 0
	v_mfma_f32_16x16x32_bf16 v[12:15], v[152:155], v[20:23], v[12:15]
	s_nop 0
	s_nop 0
	ds_read_b64_tr_b16 v[152:153], v97 offset:27744
	ds_read_b64_tr_b16 v[154:155], v97 offset:30048
	v_cvt_pk_bf16_f32 v17, v29, v91
	v_cvt_pk_bf16_f32 v18, v90, v92
	v_cvt_pk_bf16_f32 v19, v93, v117
	v_cvt_pk_bf16_f32 v28, v120, v121
	v_cvt_pk_bf16_f32 v29, v122, v123
	s_nop 0
	s_waitcnt lgkmcnt(6)
	v_mfma_f32_16x16x32_bf16 v[0:3], v[156:159], v[16:19], v[0:3]
	s_nop 0
	s_nop 0
	ds_read_b64_tr_b16 v[156:157], v97 offset:32256
	ds_read_b64_tr_b16 v[158:159], v97 offset:34560
	v_cvt_pk_bf16_f32 v30, v124, v125
	v_cvt_pk_bf16_f32 v31, v126, v127
	s_nop 0
	s_waitcnt lgkmcnt(6)
	v_mfma_f32_16x16x32_bf16 v[4:7], v[160:163], v[16:19], v[4:7]
	s_nop 0
	s_nop 0
	ds_read_b64_tr_b16 v[160:161], v97 offset:32288
	ds_read_b64_tr_b16 v[162:163], v97 offset:34592
	v_mov_b32_e32 v117, v116
	s_nop 0
	s_waitcnt lgkmcnt(6)
	v_mfma_f32_16x16x32_bf16 v[8:11], v[148:151], v[16:19], v[8:11]
	s_nop 0
	s_nop 0
	ds_read_b64_tr_b16 v[148:149], v97 offset:32320
	ds_read_b64_tr_b16 v[150:151], v97 offset:34624
	s_nop 0
	s_waitcnt lgkmcnt(6)
	v_mfma_f32_16x16x32_bf16 v[12:15], v[152:155], v[16:19], v[12:15]
	s_nop 0
	s_nop 0
	s_nop 0
	s_waitcnt lgkmcnt(4)
	v_mfma_f32_16x16x32_bf16 v[16:19], v[156:159], v[28:31], v[0:3]
	s_nop 2
	s_nop 0
	s_nop 0
	s_nop 0
	s_waitcnt lgkmcnt(2)
	v_mfma_f32_16x16x32_bf16 v[20:23], v[160:163], v[28:31], v[4:7]
	s_nop 0
	s_nop 0
	s_nop 0
	s_waitcnt lgkmcnt(0)
	v_mfma_f32_16x16x32_bf16 v[24:27], v[148:151], v[28:31], v[8:11]
	ds_read_b64_tr_b16 v[0:1], v97 offset:32352
	ds_read_b64_tr_b16 v[2:3], v97 offset:34656
	s_nop 0
	s_waitcnt lgkmcnt(0)
	v_mfma_f32_16x16x32_bf16 v[28:31], v[0:3], v[28:31], v[12:15]

.LBB0_1133:
	s_mov_b64 s[8:9], -1
	s_cmp_ge_i32 s18, s22
	v_xor_b32_e32 v74, 0x80000000, v117
	s_cbranch_scc0 .LBB0_1138
	s_waitcnt lgkmcnt(0)
	ds_read_b128 v[8:11], v115 offset:36864
	ds_read_b128 v[120:123], v115 offset:36928
	ds_read_b128 v[148:151], v115 offset:39168
	ds_read_b128 v[152:155], v115 offset:39232
	ds_read_b128 v[156:159], v115 offset:41472
	ds_read_b128 v[160:163], v115 offset:41536
	ds_read_b128 v[164:167], v115 offset:43776
	ds_read_b128 v[168:171], v115 offset:43840
	v_mov_b32_e32 v75, v74
	v_mov_b32_e32 v76, v74
	v_mov_b32_e32 v77, v74
	s_nop 0
	s_nop 0
	s_waitcnt lgkmcnt(7)
	v_mfma_f32_16x16x32_bf16 v[0:3], v[8:11], v[66:69], v[74:77]
	s_nop 0
	s_waitcnt lgkmcnt(6)
	v_mfma_f32_16x16x32_bf16 v[90:93], v[120:123], v[70:73], v[0:3]
	s_nop 5
	s_nop 0
	s_nop 0
	s_nop 0
	s_waitcnt lgkmcnt(5)
	v_mfma_f32_16x16x32_bf16 v[0:3], v[148:151], v[66:69], v[74:77]
	s_nop 0
	s_waitcnt lgkmcnt(4)
	v_mfma_f32_16x16x32_bf16 v[86:89], v[152:155], v[70:73], v[0:3]
	s_nop 5
	s_nop 0
	s_nop 0
	s_nop 0
	s_waitcnt lgkmcnt(3)
	v_mfma_f32_16x16x32_bf16 v[0:3], v[156:159], v[66:69], v[74:77]
	s_nop 0
	s_waitcnt lgkmcnt(2)
	v_mfma_f32_16x16x32_bf16 v[78:81], v[160:163], v[70:73], v[0:3]
	s_nop 5
	s_nop 0
	s_nop 0
	s_nop 0
	s_waitcnt lgkmcnt(1)
	v_mfma_f32_16x16x32_bf16 v[0:3], v[164:167], v[66:69], v[74:77]
	s_nop 0
	s_waitcnt lgkmcnt(0)
	v_mfma_f32_16x16x32_bf16 v[82:85], v[168:171], v[70:73], v[0:3]
	s_nop 5
	v_max3_f32 v0, v92, v90, v91
	v_max3_f32 v0, v93, v0, v86
	v_max3_f32 v0, v88, v87, v0
	v_max3_f32 v0, v78, v89, v0
	v_max3_f32 v0, v80, v79, v0
	v_max3_f32 v0, v82, v81, v0
	v_max3_f32 v0, v84, v83, v0
	v_max_f32_e32 v1, v85, v85
	v_max_f32_e32 v0, v1, v0
	v_cmp_lt_f32_e32 vcc, s52, v0
	s_cbranch_vccz .LBB0_1136
	v_max_f32_e32 v0, v91, v91
	v_max_f32_e32 v1, v90, v90
	v_max_f32_e32 v0, v1, v0
	v_max3_f32 v0, v0, v92, v93
	v_max3_f32 v0, v0, v86, v87
	v_max3_f32 v0, v0, v88, v89
	v_max3_f32 v0, v0, v78, v79
	v_max3_f32 v0, v0, v80, v81
	v_max3_f32 v0, v0, v82, v83
	v_max3_f32 v0, v0, v84, v85
	v_mov_b32_e32 v1, v0
	s_nop 1
	v_permlane16_swap_b32_e32 v0, v1
	v_max_f32_e32 v1, v1, v1
	v_max_f32_e32 v0, v0, v0
	v_max_f32_e32 v0, v0, v1
	v_mov_b32_e32 v1, v0
	s_nop 1
	v_permlane32_swap_b32_e32 v0, v1
	v_max_f32_e32 v1, v1, v1
	v_max_f32_e32 v0, v0, v0
	v_max_f32_e32 v0, v0, v1
	v_cmp_lt_f32_e32 vcc, s52, v0
	s_nop 1
	v_cndmask_b32_e32 v0, 0, v0, vcc
	v_exp_f32_e64 v12, -v0
	v_add_f32_e32 v116, v117, v0
	v_pk_add_f32 v[90:91], v[90:91], v[0:1] op_sel_hi:[1,0] neg_lo:[0,1] neg_hi:[0,1]
	v_pk_add_f32 v[92:93], v[92:93], v[0:1] op_sel_hi:[1,0] neg_lo:[0,1] neg_hi:[0,1]
	v_mul_f32_e32 v75, v118, v12
	v_pk_add_f32 v[86:87], v[86:87], v[0:1] op_sel_hi:[1,0] neg_lo:[0,1] neg_hi:[0,1]
	v_pk_add_f32 v[88:89], v[88:89], v[0:1] op_sel_hi:[1,0] neg_lo:[0,1] neg_hi:[0,1]
	v_pk_add_f32 v[78:79], v[78:79], v[0:1] op_sel_hi:[1,0] neg_lo:[0,1] neg_hi:[0,1]
	v_pk_add_f32 v[80:81], v[80:81], v[0:1] op_sel_hi:[1,0] neg_lo:[0,1] neg_hi:[0,1]
	v_pk_add_f32 v[82:83], v[82:83], v[0:1] op_sel_hi:[1,0] neg_lo:[0,1] neg_hi:[0,1]
	v_pk_add_f32 v[84:85], v[84:85], v[0:1] op_sel_hi:[1,0] neg_lo:[0,1] neg_hi:[0,1]
	v_pk_mul_f32 v[10:11], v[26:27], v[12:13] op_sel_hi:[1,0]
	v_pk_mul_f32 v[8:9], v[24:25], v[12:13] op_sel_hi:[1,0]
	v_pk_mul_f32 v[6:7], v[22:23], v[12:13] op_sel_hi:[1,0]
	v_pk_mul_f32 v[4:5], v[20:21], v[12:13] op_sel_hi:[1,0]
	v_pk_mul_f32 v[2:3], v[18:19], v[12:13] op_sel_hi:[1,0]
	v_pk_mul_f32 v[0:1], v[16:17], v[12:13] op_sel_hi:[1,0]
	v_pk_mul_f32 v[14:15], v[30:31], v[12:13] op_sel_hi:[1,0]
	v_pk_mul_f32 v[12:13], v[28:29], v[12:13] op_sel_hi:[1,0]
	s_branch .LBB0_1137

.LBB0_1137:
	s_waitcnt lgkmcnt(0)
	ds_read_b64_tr_b16 v[150:151], v97 offset:57600
	ds_read_b64_tr_b16 v[148:149], v97 offset:55296
	ds_read_b64_tr_b16 v[152:153], v97 offset:55328
	ds_read_b64_tr_b16 v[154:155], v97 offset:57632
	ds_read_b64_tr_b16 v[156:157], v97 offset:55360
	ds_read_b64_tr_b16 v[158:159], v97 offset:57664
	ds_read_b64_tr_b16 v[160:161], v97 offset:59904
	ds_read_b64_tr_b16 v[162:163], v97 offset:62208
	v_exp_f32_e32 v76, v90
	v_exp_f32_e32 v90, v91
	v_exp_f32_e32 v91, v92
	v_exp_f32_e32 v92, v93
	v_add_f32_e32 v77, 0, v76
	v_exp_f32_e32 v86, v86
	v_add_f32_e32 v77, v90, v77
	v_exp_f32_e32 v87, v87
	v_add_f32_e32 v77, v91, v77
	v_exp_f32_e32 v88, v88
	v_add_f32_e32 v77, v92, v77
	v_exp_f32_e32 v89, v89
	v_add_f32_e32 v77, v86, v77
	v_exp_f32_e32 v78, v78
	v_add_f32_e32 v77, v87, v77
	v_exp_f32_e32 v79, v79
	v_add_f32_e32 v77, v88, v77
	v_exp_f32_e32 v93, v80
	v_add_f32_e32 v77, v89, v77
	v_exp_f32_e32 v120, v81
	v_add_f32_e32 v77, v78, v77
	v_exp_f32_e32 v121, v82
	v_add_f32_e32 v77, v79, v77
	v_exp_f32_e32 v122, v83
	v_add_f32_e32 v77, v93, v77
	v_exp_f32_e32 v84, v84
	v_add_f32_e32 v77, v120, v77
	v_exp_f32_e32 v85, v85
	v_add_f32_e32 v77, v121, v77
	v_add_f32_e32 v77, v122, v77
	v_add_f32_e32 v77, v84, v77
	v_add_f32_e32 v77, v85, v77
	v_cvt_pk_bf16_f32 v80, v76, v90
	v_cvt_pk_bf16_f32 v82, v86, v87
	v_cvt_pk_bf16_f32 v83, v88, v89
	v_cvt_pk_bf16_f32 v76, v78, v79
	v_cvt_pk_bf16_f32 v79, v84, v85
	s_nop 0
	s_nop 0
	s_nop 0
	v_cvt_pk_bf16_f32 v81, v91, v92
	s_nop 0
	v_add_f32_e32 v119, v75, v77
	s_nop 0
	s_waitcnt lgkmcnt(6)
	v_mfma_f32_16x16x32_bf16 v[0:3], v[148:151], v[80:83], v[0:3]
	s_nop 0
	s_nop 0
	ds_read_b64_tr_b16 v[148:149], v97 offset:59936
	ds_read_b64_tr_b16 v[150:151], v97 offset:62240
	v_cvt_pk_bf16_f32 v77, v93, v120
	v_cvt_pk_bf16_f32 v78, v121, v122
	s_nop 0
	s_waitcnt lgkmcnt(4)
	v_mfma_f32_16x16x32_bf16 v[8:11], v[156:159], v[80:83], v[8:11]
	ds_read_b64_tr_b16 v[156:157], v97 offset:59968
	ds_read_b64_tr_b16 v[158:159], v97 offset:62272
	ds_read_b64_tr_b16 v[84:85], v97 offset:55392
	ds_read_b64_tr_b16 v[86:87], v97 offset:57696
	s_mov_b64 s[8:9], 0
	v_mfma_f32_16x16x32_bf16 v[4:7], v[152:155], v[80:83], v[4:7]
	s_nop 0
	s_waitcnt lgkmcnt(0)
	v_mfma_f32_16x16x32_bf16 v[12:15], v[84:87], v[80:83], v[12:15]
	s_nop 0
	s_nop 0
	s_nop 0
	v_mfma_f32_16x16x32_bf16 v[0:3], v[160:163], v[76:79], v[0:3]
	s_nop 0
	s_nop 0
	s_nop 0
	v_mfma_f32_16x16x32_bf16 v[4:7], v[148:151], v[76:79], v[4:7]
	s_nop 0
	s_nop 0
	s_nop 0
	v_mfma_f32_16x16x32_bf16 v[8:11], v[156:159], v[76:79], v[8:11]
	ds_read_b64_tr_b16 v[80:81], v97 offset:60000
	ds_read_b64_tr_b16 v[82:83], v97 offset:62304
	s_nop 0
	s_waitcnt lgkmcnt(0)
	v_mfma_f32_16x16x32_bf16 v[12:15], v[80:83], v[76:79], v[12:15]
.LBB0_1138:
	s_and_b64 vcc, exec, s[8:9]
	s_cbranch_vccz .LBB0_1101
	s_waitcnt lgkmcnt(0)
	ds_read_b128 v[148:151], v115 offset:36864
	ds_read_b128 v[152:155], v115 offset:36928
	ds_read_b128 v[156:159], v115 offset:39168
	ds_read_b128 v[160:163], v115 offset:39232
	ds_read_b128 v[164:167], v115 offset:41472
	ds_read_b128 v[168:171], v115 offset:41536
	ds_read_b128 v[172:175], v115 offset:43776
	ds_read_b128 v[178:181], v115 offset:43840
	v_mov_b32_e32 v75, v74
	v_mov_b32_e32 v76, v74
	v_mov_b32_e32 v77, v74
	v_readfirstlane_b32 s8, v95
	s_add_i32 s9, s14, s8
	s_nop 0
	s_waitcnt lgkmcnt(7)
	v_mfma_f32_16x16x32_bf16 v[0:3], v[148:151], v[66:69], v[74:77]
	ds_read_b128 v[186:189], v115 offset:46080
	s_add_i32 s10, s21, s15
	s_add_i32 s9, s9, s17
	s_sub_i32 s8, s10, s8
	s_nop 0
	s_waitcnt lgkmcnt(7)
	v_mfma_f32_16x16x32_bf16 v[0:3], v[152:155], v[70:73], v[0:3]
	s_nop 0
	s_nop 0
	ds_read_b128 v[150:153], v115 offset:46144
	s_addk_i32 s9, 0xff8f
	s_addk_i32 s8, 0xff
	s_nop 0
	s_waitcnt lgkmcnt(7)
	v_mfma_f32_16x16x32_bf16 v[4:7], v[156:159], v[66:69], v[74:77]
	ds_read_b128 v[154:157], v115 offset:48384
	s_max_i32 s8, s9, s8
	s_cmpk_gt_i32 s8, 0x80
	v_add_u32_e32 v116, s17, v111
	s_nop 0
	s_waitcnt lgkmcnt(7)
	v_mfma_f32_16x16x32_bf16 v[4:7], v[160:163], v[70:73], v[4:7]
	s_nop 0
	s_nop 0
	ds_read_b128 v[158:161], v115 offset:48448
	s_cselect_b64 s[8:9], -1, 0
	s_movk_i32 s10, 0x100
	s_nop 0
	s_waitcnt lgkmcnt(7)
	v_mfma_f32_16x16x32_bf16 v[8:11], v[164:167], v[66:69], v[74:77]
	ds_read_b128 v[162:165], v115 offset:50688
	s_nop 0
	s_waitcnt lgkmcnt(7)
	v_mfma_f32_16x16x32_bf16 v[8:11], v[168:171], v[70:73], v[8:11]
	s_nop 0
	s_nop 0
	ds_read_b128 v[166:169], v115 offset:50752
	s_nop 0
	s_waitcnt lgkmcnt(7)
	v_mfma_f32_16x16x32_bf16 v[12:15], v[172:175], v[66:69], v[74:77]
	ds_read_b128 v[170:173], v115 offset:52992
	s_nop 0
	s_waitcnt lgkmcnt(7)
	v_mfma_f32_16x16x32_bf16 v[12:15], v[178:181], v[70:73], v[12:15]
	s_nop 0
	s_nop 0
	ds_read_b128 v[174:177], v115 offset:53056
	s_nop 0
	s_waitcnt lgkmcnt(7)
	v_mfma_f32_16x16x32_bf16 v[78:81], v[186:189], v[66:69], v[74:77]
	s_nop 0
	s_waitcnt lgkmcnt(6)
	v_mfma_f32_16x16x32_bf16 v[90:93], v[150:153], v[70:73], v[78:81]
	s_nop 5
	s_nop 0
	s_nop 0
	s_nop 0
	s_waitcnt lgkmcnt(5)
	v_mfma_f32_16x16x32_bf16 v[78:81], v[154:157], v[66:69], v[74:77]
	s_nop 0
	s_waitcnt lgkmcnt(4)
	v_mfma_f32_16x16x32_bf16 v[120:123], v[158:161], v[70:73], v[78:81]
	s_nop 5
	s_nop 0
	s_nop 0
	s_nop 0
	s_waitcnt lgkmcnt(3)
	v_mfma_f32_16x16x32_bf16 v[78:81], v[162:165], v[66:69], v[74:77]
	s_nop 0
	s_waitcnt lgkmcnt(2)
	v_mfma_f32_16x16x32_bf16 v[124:127], v[166:169], v[70:73], v[78:81]
	s_nop 5
	s_nop 0
	s_nop 0
	s_nop 0
	s_waitcnt lgkmcnt(1)
	v_mfma_f32_16x16x32_bf16 v[74:77], v[170:173], v[66:69], v[74:77]
	s_nop 0
	s_waitcnt lgkmcnt(0)
	v_mfma_f32_16x16x32_bf16 v[128:131], v[174:177], v[70:73], v[74:77]
	s_nop 5
	v_add_co_u32_e32 v74, vcc, s54, v116
	s_and_b64 vcc, s[8:9], vcc
	s_nop 0
	v_cndmask_b32_e32 v84, v0, v236, vcc
	v_add_u32_e32 v0, s15, v112
	v_add_u32_e32 v0, 0x101, v0
	v_cmp_lt_u32_e32 vcc, s10, v0
	s_and_b64 vcc, s[8:9], vcc
	v_add_u32_e32 v0, 0xfffffefd, v116
	v_cndmask_b32_e32 v87, v1, v236, vcc
	v_cmp_gt_u32_e32 vcc, s54, v0
	s_and_b64 vcc, s[8:9], vcc
	v_add_u32_e32 v0, 0xfffffefc, v116
	v_cndmask_b32_e32 v88, v2, v236, vcc
	v_cmp_gt_u32_e32 vcc, s54, v0
	s_and_b64 vcc, s[8:9], vcc
	v_add_u32_e32 v0, 0xfffffeef, v116
	v_cndmask_b32_e32 v89, v3, v236, vcc
	v_cmp_gt_u32_e32 vcc, s54, v0
	s_and_b64 vcc, s[8:9], vcc
	v_add_u32_e32 v0, 0xfffffeee, v116
	v_cndmask_b32_e32 v86, v4, v236, vcc
	v_cmp_gt_u32_e32 vcc, s54, v0
	s_and_b64 vcc, s[8:9], vcc
	v_add_u32_e32 v0, 0xfffffeed, v116
	v_cndmask_b32_e32 v85, v5, v236, vcc
	v_cmp_gt_u32_e32 vcc, s54, v0
	s_and_b64 vcc, s[8:9], vcc
	v_add_u32_e32 v0, 0xfffffeec, v116
	v_cndmask_b32_e32 v83, v6, v236, vcc
	v_cmp_gt_u32_e32 vcc, s54, v0
	s_and_b64 vcc, s[8:9], vcc
	v_add_u32_e32 v0, 0xfffffedf, v116
	v_cndmask_b32_e32 v82, v7, v236, vcc
	v_cmp_gt_u32_e32 vcc, s54, v0
	s_and_b64 vcc, s[8:9], vcc
	v_add_u32_e32 v0, 0xfffffede, v116
	v_cndmask_b32_e32 v81, v8, v236, vcc
	v_cmp_gt_u32_e32 vcc, s54, v0
	s_and_b64 vcc, s[8:9], vcc
	v_add_u32_e32 v0, 0xfffffedd, v116
	v_cndmask_b32_e32 v80, v9, v236, vcc
	v_cmp_gt_u32_e32 vcc, s54, v0
	s_and_b64 vcc, s[8:9], vcc
	v_add_u32_e32 v0, 0xfffffedc, v116
	v_cndmask_b32_e32 v79, v10, v236, vcc
	v_cmp_gt_u32_e32 vcc, s54, v0
	s_and_b64 vcc, s[8:9], vcc
	v_add_u32_e32 v0, 0xfffffecf, v116
	v_cndmask_b32_e32 v78, v11, v236, vcc
	v_cmp_gt_u32_e32 vcc, s54, v0
	s_and_b64 vcc, s[8:9], vcc
	v_add_u32_e32 v0, 0xfffffece, v116
	v_cndmask_b32_e32 v77, v12, v236, vcc
	v_cmp_gt_u32_e32 vcc, s54, v0
	s_and_b64 vcc, s[8:9], vcc
	v_add_u32_e32 v0, 0xfffffecd, v116
	v_cndmask_b32_e32 v76, v13, v236, vcc
	v_cmp_gt_u32_e32 vcc, s54, v0
	s_and_b64 vcc, s[8:9], vcc
	v_add_u32_e32 v0, 0xfffffecc, v116
	v_cndmask_b32_e32 v75, v14, v236, vcc
	v_cmp_gt_u32_e32 vcc, s54, v0
	s_and_b64 vcc, s[8:9], vcc
	v_add_u32_e32 v0, 0xfffffebf, v116
	v_cndmask_b32_e32 v74, v15, v236, vcc
	v_cmp_gt_u32_e32 vcc, s54, v0
	s_and_b64 vcc, s[8:9], vcc
	v_add_u32_e32 v0, 0xfffffebe, v116
	v_cndmask_b32_e32 v15, v90, v236, vcc
	v_cmp_gt_u32_e32 vcc, s54, v0
	s_and_b64 vcc, s[8:9], vcc
	v_add_u32_e32 v0, 0xfffffebd, v116
	v_cndmask_b32_e32 v14, v91, v236, vcc
	v_cmp_gt_u32_e32 vcc, s54, v0
	s_and_b64 vcc, s[8:9], vcc
	v_add_u32_e32 v0, 0xfffffebc, v116
	v_cndmask_b32_e32 v13, v92, v236, vcc
	v_cmp_gt_u32_e32 vcc, s54, v0
	s_and_b64 vcc, s[8:9], vcc
	v_add_u32_e32 v0, 0xfffffeaf, v116
	v_cndmask_b32_e32 v11, v93, v236, vcc
	v_cmp_gt_u32_e32 vcc, s54, v0
	s_and_b64 vcc, s[8:9], vcc
	v_add_u32_e32 v0, 0xfffffeae, v116
	v_cndmask_b32_e32 v9, v120, v236, vcc
	v_cmp_gt_u32_e32 vcc, s54, v0
	s_and_b64 vcc, s[8:9], vcc
	v_add_u32_e32 v0, 0xfffffead, v116
	v_cndmask_b32_e32 v7, v121, v236, vcc
	v_cmp_gt_u32_e32 vcc, s54, v0
	s_and_b64 vcc, s[8:9], vcc
	v_add_u32_e32 v0, 0xfffffeac, v116
	v_cndmask_b32_e32 v4, v122, v236, vcc
	v_cmp_gt_u32_e32 vcc, s54, v0
	s_and_b64 vcc, s[8:9], vcc
	v_add_u32_e32 v1, 0xfffffe9f, v116
	v_cndmask_b32_e32 v0, v123, v236, vcc
	v_cmp_gt_u32_e32 vcc, s54, v1
	s_and_b64 vcc, s[8:9], vcc
	v_add_u32_e32 v2, 0xfffffe9e, v116
	v_cndmask_b32_e32 v1, v124, v236, vcc
	v_cmp_gt_u32_e32 vcc, s54, v2
	s_and_b64 vcc, s[8:9], vcc
	v_add_u32_e32 v3, 0xfffffe9d, v116
	v_max3_f32 v90, v88, v84, v87
	v_cndmask_b32_e32 v2, v125, v236, vcc
	v_cmp_gt_u32_e32 vcc, s54, v3
	v_max3_f32 v90, v86, v89, v90
	s_and_b64 vcc, s[8:9], vcc
	v_add_u32_e32 v5, 0xfffffe9c, v116
	v_max3_f32 v90, v83, v85, v90
	v_cndmask_b32_e32 v3, v126, v236, vcc
	v_cmp_gt_u32_e32 vcc, s54, v5
	v_max3_f32 v90, v81, v82, v90
	s_and_b64 vcc, s[8:9], vcc
	v_add_u32_e32 v6, 0xfffffe8f, v116
	v_max3_f32 v90, v79, v80, v90
	v_cndmask_b32_e32 v5, v127, v236, vcc
	v_cmp_gt_u32_e32 vcc, s54, v6
	v_max3_f32 v90, v77, v78, v90
	s_and_b64 vcc, s[8:9], vcc
	v_add_u32_e32 v8, 0xfffffe8e, v116
	v_max3_f32 v90, v75, v76, v90
	v_cndmask_b32_e32 v6, v128, v236, vcc
	v_cmp_gt_u32_e32 vcc, s54, v8
	v_max3_f32 v90, v15, v74, v90
	s_and_b64 vcc, s[8:9], vcc
	v_add_u32_e32 v10, 0xfffffe8d, v116
	v_max3_f32 v90, v13, v14, v90
	v_cndmask_b32_e32 v8, v129, v236, vcc
	v_cmp_gt_u32_e32 vcc, s54, v10
	v_max3_f32 v90, v9, v11, v90
	s_and_b64 vcc, s[8:9], vcc
	v_add_u32_e32 v12, 0xfffffe8c, v116
	v_max3_f32 v90, v4, v7, v90
	v_cndmask_b32_e32 v10, v130, v236, vcc
	v_cmp_gt_u32_e32 vcc, s54, v12
	v_max3_f32 v90, v1, v0, v90
	s_and_b64 vcc, s[8:9], vcc
	v_max3_f32 v90, v3, v2, v90
	v_cndmask_b32_e32 v12, v131, v236, vcc
	v_max3_f32 v90, v6, v5, v90
	v_max3_f32 v90, v10, v8, v90
	v_max_f32_e32 v91, v12, v12
	v_max_f32_e32 v90, v91, v90
	v_cmp_lt_f32_e32 vcc, s52, v90
	s_cbranch_vccz .LBB0_1100
	v_max_f32_e32 v90, v87, v87
	v_max_f32_e32 v91, v84, v84
	v_max_f32_e32 v90, v91, v90
	v_max3_f32 v90, v90, v88, v89
	v_max3_f32 v90, v90, v86, v85
	v_max3_f32 v90, v90, v83, v82
	v_max3_f32 v90, v90, v81, v80
	v_max3_f32 v90, v90, v79, v78
	v_max3_f32 v90, v90, v77, v76
	v_max3_f32 v90, v90, v75, v74
	v_max3_f32 v90, v90, v15, v14
	v_max3_f32 v90, v90, v13, v11
	v_max3_f32 v90, v90, v9, v7
	v_max3_f32 v90, v90, v4, v0
	v_max3_f32 v90, v90, v1, v2
	v_max3_f32 v90, v90, v3, v5
	v_max3_f32 v90, v90, v6, v8
	v_max3_f32 v90, v90, v10, v12
	v_mov_b32_e32 v91, v90
	s_nop 1
	v_permlane16_swap_b32_e32 v90, v91
	v_max_f32_e32 v91, v91, v91
	v_max_f32_e32 v90, v90, v90
	v_max_f32_e32 v90, v90, v91
	v_mov_b32_e32 v91, v90
	s_nop 1
	v_permlane32_swap_b32_e32 v90, v91
	v_max_f32_e32 v91, v91, v91
	v_max_f32_e32 v90, v90, v90
	v_max_f32_e32 v90, v90, v91
	v_cmp_lt_f32_e32 vcc, s52, v90
	s_nop 1
	v_cndmask_b32_e32 v91, 0, v90, vcc
	v_exp_f32_e64 v90, -v91
	v_add_f32_e32 v117, v117, v91
	v_sub_f32_e32 v84, v84, v91
	v_sub_f32_e32 v87, v87, v91
	v_mul_f32_e32 v118, v118, v90
	v_sub_f32_e32 v88, v88, v91
	v_sub_f32_e32 v89, v89, v91
	v_sub_f32_e32 v86, v86, v91
	v_sub_f32_e32 v85, v85, v91
	v_sub_f32_e32 v83, v83, v91
	v_sub_f32_e32 v82, v82, v91
	v_sub_f32_e32 v81, v81, v91
	v_sub_f32_e32 v80, v80, v91
	v_sub_f32_e32 v79, v79, v91
	v_sub_f32_e32 v78, v78, v91
	v_sub_f32_e32 v77, v77, v91
	v_sub_f32_e32 v76, v76, v91
	v_sub_f32_e32 v75, v75, v91
	v_sub_f32_e32 v74, v74, v91
	v_sub_f32_e32 v15, v15, v91
	v_sub_f32_e32 v14, v14, v91
	v_sub_f32_e32 v13, v13, v91
	v_sub_f32_e32 v11, v11, v91
	v_sub_f32_e32 v9, v9, v91
	v_sub_f32_e32 v7, v7, v91
	v_sub_f32_e32 v4, v4, v91
	v_sub_f32_e32 v0, v0, v91
	v_sub_f32_e32 v1, v1, v91
	v_sub_f32_e32 v2, v2, v91
	v_sub_f32_e32 v3, v3, v91
	v_sub_f32_e32 v5, v5, v91
	v_sub_f32_e32 v6, v6, v91
	v_sub_f32_e32 v8, v8, v91
	v_sub_f32_e32 v10, v10, v91
	v_sub_f32_e32 v12, v12, v91
	v_pk_mul_f32 v[26:27], v[26:27], v[90:91] op_sel_hi:[1,0]
	v_pk_mul_f32 v[24:25], v[24:25], v[90:91] op_sel_hi:[1,0]
	v_pk_mul_f32 v[22:23], v[22:23], v[90:91] op_sel_hi:[1,0]
	v_pk_mul_f32 v[20:21], v[20:21], v[90:91] op_sel_hi:[1,0]
	v_pk_mul_f32 v[18:19], v[18:19], v[90:91] op_sel_hi:[1,0]
	v_pk_mul_f32 v[16:17], v[16:17], v[90:91] op_sel_hi:[1,0]
	v_pk_mul_f32 v[30:31], v[30:31], v[90:91] op_sel_hi:[1,0]
	v_pk_mul_f32 v[28:29], v[28:29], v[90:91] op_sel_hi:[1,0]
	s_branch .LBB0_1100

.LBB0_1203:
	s_waitcnt lgkmcnt(0)
	ds_read_b64_tr_b16 v[122:123], v203 offset:11520
	ds_read_b64_tr_b16 v[120:121], v202 offset:64512
	ds_read_b64_tr_b16 v[148:149], v202 offset:64576
	ds_read_b64_tr_b16 v[150:151], v203 offset:11584
	ds_read_b64_tr_b16 v[152:153], v202 offset:64608
	ds_read_b64_tr_b16 v[154:155], v203 offset:11616
	ds_read_b64_tr_b16 v[156:157], v203 offset:13824
	ds_read_b64_tr_b16 v[158:159], v203 offset:16128
	v_exp_f32_e32 v48, v48
	v_exp_f32_e32 v49, v49
	v_exp_f32_e32 v50, v50
	v_exp_f32_e32 v51, v51
	v_add_f32_e32 v67, 0, v48
	v_exp_f32_e32 v52, v52
	v_add_f32_e32 v67, v49, v67
	v_exp_f32_e32 v53, v53
	v_add_f32_e32 v67, v50, v67
	v_exp_f32_e32 v54, v54
	v_add_f32_e32 v67, v51, v67
	v_exp_f32_e32 v55, v55
	v_add_f32_e32 v67, v52, v67
	v_exp_f32_e32 v56, v56
	v_add_f32_e32 v67, v53, v67
	v_exp_f32_e32 v57, v57
	v_add_f32_e32 v67, v54, v67
	v_exp_f32_e32 v58, v58
	v_add_f32_e32 v67, v55, v67
	v_exp_f32_e32 v59, v59
	v_add_f32_e32 v67, v56, v67
	v_exp_f32_e32 v60, v60
	v_add_f32_e32 v67, v57, v67
	v_exp_f32_e32 v61, v61
	v_add_f32_e32 v67, v58, v67
	v_exp_f32_e32 v62, v62
	v_add_f32_e32 v67, v59, v67
	v_exp_f32_e32 v63, v63
	v_add_f32_e32 v67, v60, v67
	v_exp_f32_e32 v32, v32
	v_add_f32_e32 v67, v61, v67
	v_exp_f32_e32 v33, v33
	v_add_f32_e32 v67, v62, v67
	v_exp_f32_e32 v34, v34
	v_add_f32_e32 v67, v63, v67
	v_exp_f32_e32 v35, v35
	v_add_f32_e32 v210, v74, v67
	v_add_f32_e32 v67, 0, v32
	v_exp_f32_e32 v36, v36
	v_add_f32_e32 v67, v33, v67
	v_exp_f32_e32 v37, v37
	v_add_f32_e32 v67, v34, v67
	v_exp_f32_e32 v38, v38
	v_add_f32_e32 v67, v35, v67
	v_exp_f32_e32 v39, v39
	v_add_f32_e32 v67, v36, v67
	v_exp_f32_e32 v68, v40
	v_add_f32_e32 v67, v37, v67
	v_add_f32_e32 v67, v38, v67
	v_add_f32_e32 v67, v39, v67
	v_add_f32_e32 v40, v68, v67
	v_exp_f32_e32 v67, v41
	v_exp_f32_e32 v69, v42
	v_exp_f32_e32 v70, v43
	v_exp_f32_e32 v71, v44
	v_add_f32_e32 v40, v67, v40
	v_exp_f32_e32 v72, v45
	v_add_f32_e32 v40, v69, v40
	v_exp_f32_e32 v73, v46
	v_add_f32_e32 v40, v70, v40
	v_exp_f32_e32 v74, v47
	v_add_f32_e32 v40, v71, v40
	v_add_f32_e32 v40, v72, v40
	v_add_f32_e32 v40, v73, v40
	v_add_f32_e32 v40, v74, v40
	v_add_f32_e32 v209, v66, v40
	v_cvt_pk_bf16_f32 v40, v48, v49
	v_cvt_pk_bf16_f32 v41, v50, v51
	v_cvt_pk_bf16_f32 v42, v52, v53
	v_cvt_pk_bf16_f32 v43, v54, v55
	s_nop 0
	ds_read_b64_tr_b16 v[54:55], v203 offset:11552
	s_nop 0
	ds_read_b64_tr_b16 v[52:53], v202 offset:64544
	v_cvt_pk_bf16_f32 v44, v32, v33
	v_cvt_pk_bf16_f32 v45, v34, v35
	v_cvt_pk_bf16_f32 v46, v36, v37
	v_cvt_pk_bf16_f32 v47, v38, v39
	s_nop 0
	s_waitcnt lgkmcnt(8)
	v_mfma_f32_16x16x32_bf16 v[20:23], v[120:123], v[40:43], v[20:23]
	v_cvt_pk_bf16_f32 v36, v56, v57
	v_cvt_pk_bf16_f32 v37, v58, v59
	v_cvt_pk_bf16_f32 v38, v60, v61
	v_mfma_f32_16x16x32_bf16 v[48:51], v[120:123], v[44:47], v[16:19]
	ds_read_b64_tr_b16 v[120:121], v203 offset:13856
	ds_read_b64_tr_b16 v[122:123], v203 offset:16160
	s_nop 2
	s_nop 0
	s_nop 0
	v_cvt_pk_bf16_f32 v39, v62, v63
	v_cvt_pk_bf16_f32 v32, v68, v67
	s_nop 0
	s_waitcnt lgkmcnt(8)
	v_mfma_f32_16x16x32_bf16 v[12:15], v[148:151], v[40:43], v[12:15]
	v_cvt_pk_bf16_f32 v33, v69, v70
	v_cvt_pk_bf16_f32 v34, v71, v72
	v_cvt_pk_bf16_f32 v35, v73, v74
	v_mfma_f32_16x16x32_bf16 v[8:11], v[148:151], v[44:47], v[8:11]
	s_nop 0
	s_nop 0
	ds_read_b64_tr_b16 v[148:149], v203 offset:13888
	ds_read_b64_tr_b16 v[150:151], v203 offset:16192
	v_mov_b32_e32 v207, v78
	s_waitcnt lgkmcnt(4)
	v_mfma_f32_16x16x32_bf16 v[28:31], v[52:55], v[40:43], v[28:31]
	v_mfma_f32_16x16x32_bf16 v[24:27], v[52:55], v[44:47], v[24:27]
	s_nop 0
	v_mfma_f32_16x16x32_bf16 v[40:43], v[152:155], v[40:43], v[4:7]
	v_mfma_f32_16x16x32_bf16 v[44:47], v[152:155], v[44:47], v[0:3]
	ds_read_b64_tr_b16 v[152:153], v203 offset:13920
	ds_read_b64_tr_b16 v[154:155], v203 offset:16224
	s_nop 2
	s_nop 0
	s_nop 0
	s_nop 0
	s_nop 0
	s_nop 0
	v_mfma_f32_16x16x32_bf16 v[16:19], v[156:159], v[36:39], v[20:23]
	s_nop 0
	s_waitcnt lgkmcnt(4)
	v_mfma_f32_16x16x32_bf16 v[20:23], v[120:123], v[36:39], v[28:31]
	s_nop 2
	s_nop 0
	s_nop 0
	v_mfma_f32_16x16x32_bf16 v[4:7], v[120:123], v[32:35], v[24:27]
	s_nop 0
	s_waitcnt lgkmcnt(2)
	v_mfma_f32_16x16x32_bf16 v[24:27], v[148:151], v[36:39], v[12:15]
	s_nop 2
	s_nop 0
	s_nop 0
	v_mfma_f32_16x16x32_bf16 v[0:3], v[156:159], v[32:35], v[48:51]
	v_mfma_f32_16x16x32_bf16 v[8:11], v[148:151], v[32:35], v[8:11]
	s_nop 0
	s_waitcnt lgkmcnt(0)
	v_mfma_f32_16x16x32_bf16 v[28:31], v[152:155], v[36:39], v[40:43]
	v_mfma_f32_16x16x32_bf16 v[12:15], v[152:155], v[32:35], v[44:47]

.LBB0_1219:
	s_waitcnt lgkmcnt(0)
	ds_read_b64_tr_b16 v[226:227], v202 offset:20736
	ds_read_b64_tr_b16 v[224:225], v202 offset:18432
	ds_read_b64_tr_b16 v[240:241], v202 offset:18464
	ds_read_b64_tr_b16 v[242:243], v202 offset:20768
	ds_read_b64_tr_b16 v[244:245], v202 offset:18496
	ds_read_b64_tr_b16 v[246:247], v202 offset:20800
	ds_read_b64_tr_b16 v[248:249], v202 offset:18528
	ds_read_b64_tr_b16 v[250:251], v202 offset:20832
	v_exp_f32_e32 v176, v176
	v_exp_f32_e32 v177, v177
	v_exp_f32_e32 v178, v178
	v_exp_f32_e32 v179, v179
	v_add_f32_e32 v211, 0, v176
	v_exp_f32_e32 v172, v172
	v_add_f32_e32 v211, v177, v211
	v_exp_f32_e32 v173, v173
	v_add_f32_e32 v211, v178, v211
	v_exp_f32_e32 v174, v174
	v_add_f32_e32 v211, v179, v211
	v_exp_f32_e32 v175, v175
	v_add_f32_e32 v211, v172, v211
	v_exp_f32_e32 v168, v168
	v_add_f32_e32 v211, v173, v211
	v_exp_f32_e32 v169, v169
	v_add_f32_e32 v211, v174, v211
	v_exp_f32_e32 v170, v170
	v_add_f32_e32 v211, v175, v211
	v_exp_f32_e32 v171, v171
	v_add_f32_e32 v211, v168, v211
	v_exp_f32_e32 v164, v164
	v_add_f32_e32 v211, v169, v211
	v_exp_f32_e32 v165, v165
	v_add_f32_e32 v211, v170, v211
	v_exp_f32_e32 v166, v166
	v_add_f32_e32 v211, v171, v211
	v_exp_f32_e32 v167, v167
	v_add_f32_e32 v211, v164, v211
	v_exp_f32_e32 v148, v148
	v_add_f32_e32 v211, v165, v211
	v_exp_f32_e32 v149, v149
	v_add_f32_e32 v211, v166, v211
	v_exp_f32_e32 v150, v150
	v_add_f32_e32 v211, v167, v211
	v_exp_f32_e32 v151, v151
	v_add_f32_e32 v211, v208, v211
	v_add_f32_e32 v208, 0, v148
	v_exp_f32_e32 v213, v160
	v_add_f32_e32 v208, v149, v208
	v_exp_f32_e32 v214, v161
	v_add_f32_e32 v208, v150, v208
	v_exp_f32_e32 v215, v162
	v_add_f32_e32 v208, v151, v208
	v_exp_f32_e32 v163, v163
	v_add_f32_e32 v160, v213, v208
	v_exp_f32_e32 v216, v156
	v_add_f32_e32 v160, v214, v160
	v_exp_f32_e32 v217, v157
	v_add_f32_e32 v160, v215, v160
	v_exp_f32_e32 v218, v158
	v_add_f32_e32 v160, v163, v160
	v_exp_f32_e32 v219, v159
	v_add_f32_e32 v156, v216, v160
	v_exp_f32_e32 v220, v152
	v_add_f32_e32 v156, v217, v156
	v_exp_f32_e32 v221, v153
	v_add_f32_e32 v156, v218, v156
	v_exp_f32_e32 v222, v154
	v_add_f32_e32 v156, v219, v156
	v_exp_f32_e32 v223, v155
	v_add_f32_e32 v152, v220, v156
	v_add_f32_e32 v152, v221, v152
	v_add_f32_e32 v152, v222, v152
	v_add_f32_e32 v152, v223, v152
	v_add_f32_e32 v208, v212, v152
	v_cvt_pk_bf16_f32 v152, v168, v169
	v_cvt_pk_bf16_f32 v154, v164, v165
	v_cvt_pk_bf16_f32 v155, v166, v167
	s_nop 0
	s_nop 0
	s_nop 0
	v_cvt_pk_bf16_f32 v156, v176, v177
	v_cvt_pk_bf16_f32 v157, v178, v179
	v_cvt_pk_bf16_f32 v158, v172, v173
	v_cvt_pk_bf16_f32 v159, v174, v175
	v_cvt_pk_bf16_f32 v160, v148, v149
	v_cvt_pk_bf16_f32 v161, v150, v151
	v_cvt_pk_bf16_f32 v162, v213, v214
	v_cvt_pk_bf16_f32 v163, v215, v163
	v_cvt_pk_bf16_f32 v153, v170, v171
	s_nop 0
	s_waitcnt lgkmcnt(6)
	v_mfma_f32_16x16x32_bf16 v[32:35], v[224:227], v[156:159], v[32:35]
	s_nop 0
	v_cvt_pk_bf16_f32 v148, v216, v217
	v_cvt_pk_bf16_f32 v149, v218, v219
	v_mfma_f32_16x16x32_bf16 v[48:51], v[224:227], v[160:163], v[48:51]
	s_nop 0
	s_nop 0
	ds_read_b64_tr_b16 v[224:225], v202 offset:23040
	ds_read_b64_tr_b16 v[226:227], v202 offset:25344
	v_cvt_pk_bf16_f32 v150, v220, v221
	v_cvt_pk_bf16_f32 v151, v222, v223
	s_nop 0
	s_waitcnt lgkmcnt(4)
	v_mfma_f32_16x16x32_bf16 v[40:43], v[244:247], v[156:159], v[40:43]
	s_mov_b64 s[8:9], 0
	v_mfma_f32_16x16x32_bf16 v[56:59], v[244:247], v[160:163], v[56:59]
	s_nop 0
	s_nop 0
	ds_read_b64_tr_b16 v[244:245], v202 offset:23072
	ds_read_b64_tr_b16 v[246:247], v202 offset:25376
	v_mfma_f32_16x16x32_bf16 v[36:39], v[240:243], v[156:159], v[36:39]
	s_nop 0
	s_waitcnt lgkmcnt(4)
	v_mfma_f32_16x16x32_bf16 v[44:47], v[248:251], v[156:159], v[44:47]
	s_nop 0
	s_nop 0
	s_nop 0
	s_waitcnt lgkmcnt(2)
	v_mfma_f32_16x16x32_bf16 v[32:35], v[224:227], v[152:155], v[32:35]
	v_mfma_f32_16x16x32_bf16 v[48:51], v[224:227], v[148:151], v[48:51]
	s_nop 0
	s_nop 0
	ds_read_b64_tr_b16 v[224:225], v202 offset:23104
	ds_read_b64_tr_b16 v[226:227], v202 offset:25408
	v_mfma_f32_16x16x32_bf16 v[52:55], v[240:243], v[160:163], v[52:55]
	ds_read_b64_tr_b16 v[240:241], v202 offset:23136
	ds_read_b64_tr_b16 v[242:243], v202 offset:25440
	s_nop 0
	s_waitcnt lgkmcnt(4)
	v_mfma_f32_16x16x32_bf16 v[36:39], v[244:247], v[152:155], v[36:39]
	v_mfma_f32_16x16x32_bf16 v[52:55], v[244:247], v[148:151], v[52:55]
	s_nop 0
	s_nop 0
	s_nop 0
	s_waitcnt lgkmcnt(2)
	v_mfma_f32_16x16x32_bf16 v[40:43], v[224:227], v[152:155], v[40:43]
	v_mfma_f32_16x16x32_bf16 v[56:59], v[224:227], v[148:151], v[56:59]
	s_nop 0
	s_nop 0
	v_mfma_f32_16x16x32_bf16 v[60:63], v[248:251], v[160:163], v[60:63]
	s_nop 0
	s_waitcnt lgkmcnt(0)
	v_mfma_f32_16x16x32_bf16 v[44:47], v[240:243], v[152:155], v[44:47]
	v_mfma_f32_16x16x32_bf16 v[60:63], v[240:243], v[148:151], v[60:63]

.LBB0_1226:
	s_waitcnt lgkmcnt(0)
	ds_read_b64_tr_b16 v[146:147], v202 offset:20736
	ds_read_b64_tr_b16 v[144:145], v202 offset:18432
	ds_read_b64_tr_b16 v[148:149], v202 offset:18464
	ds_read_b64_tr_b16 v[152:153], v202 offset:18496
	ds_read_b64_tr_b16 v[156:157], v202 offset:18528
	ds_read_b64_tr_b16 v[150:151], v202 offset:20768
	ds_read_b64_tr_b16 v[154:155], v202 offset:20800
	ds_read_b64_tr_b16 v[158:159], v202 offset:20832
	v_exp_f32_e32 v70, v48
	v_exp_f32_e32 v71, v49
	v_exp_f32_e32 v72, v50
	v_exp_f32_e32 v73, v51
	v_exp_f32_e32 v74, v44
	v_exp_f32_e32 v75, v45
	v_exp_f32_e32 v76, v46
	v_exp_f32_e32 v77, v47
	v_exp_f32_e32 v64, v60
	v_exp_f32_e32 v67, v61
	v_exp_f32_e32 v68, v62
	v_exp_f32_e32 v127, v63
	v_exp_f32_e32 v132, v56
	v_exp_f32_e32 v133, v57
	v_exp_f32_e32 v134, v58
	v_exp_f32_e32 v135, v59
	s_nop 0
	s_nop 0
	s_nop 0
	s_nop 0
	s_nop 0
	s_nop 0
	s_nop 0
	s_nop 0
	v_exp_f32_e32 v136, v52
	v_exp_f32_e32 v137, v53
	v_exp_f32_e32 v138, v54
	v_exp_f32_e32 v139, v55
	v_cvt_pk_bf16_f32 v52, v70, v71
	v_cvt_pk_bf16_f32 v53, v72, v73
	v_cvt_pk_bf16_f32 v54, v74, v75
	v_cvt_pk_bf16_f32 v55, v76, v77
	v_exp_f32_e32 v140, v40
	v_cvt_pk_bf16_f32 v44, v64, v67
	v_cvt_pk_bf16_f32 v45, v68, v127
	v_cvt_pk_bf16_f32 v46, v132, v133
	v_cvt_pk_bf16_f32 v47, v134, v135
	v_exp_f32_e32 v141, v41
	v_exp_f32_e32 v142, v42
	v_exp_f32_e32 v143, v43
	v_exp_f32_e32 v78, v36
	v_exp_f32_e32 v120, v37
	v_exp_f32_e32 v121, v38
	v_exp_f32_e32 v122, v39
	v_exp_f32_e32 v123, v32
	v_exp_f32_e32 v124, v33
	v_exp_f32_e32 v125, v34
	v_exp_f32_e32 v126, v35
	s_nop 0
	s_waitcnt lgkmcnt(1)
	v_mfma_f32_16x16x32_bf16 v[40:43], v[152:155], v[52:55], v[8:11]
	s_nop 2
	ds_read_b64_tr_b16 v[160:161], v202 offset:23040
	ds_read_b64_tr_b16 v[162:163], v202 offset:25344
	v_cvt_pk_bf16_f32 v32, v136, v137
	v_cvt_pk_bf16_f32 v33, v138, v139
	v_mfma_f32_16x16x32_bf16 v[0:3], v[144:147], v[52:55], v[0:3]
	v_cvt_pk_bf16_f32 v34, v140, v141
	v_cvt_pk_bf16_f32 v35, v142, v143
	v_mov_b32_e32 v69, v66
	v_mfma_f32_16x16x32_bf16 v[20:23], v[148:151], v[44:47], v[20:23]
	v_mfma_f32_16x16x32_bf16 v[4:7], v[148:151], v[52:55], v[4:7]
	v_mfma_f32_16x16x32_bf16 v[36:39], v[152:155], v[44:47], v[24:27]
	ds_read_b64_tr_b16 v[148:149], v202 offset:23072
	ds_read_b64_tr_b16 v[152:153], v202 offset:23104
	s_nop 0
	s_waitcnt lgkmcnt(4)
	v_mfma_f32_16x16x32_bf16 v[52:55], v[156:159], v[52:55], v[12:15]
	s_nop 2
	s_nop 0
	s_nop 0
	ds_read_b64_tr_b16 v[164:165], v202 offset:23136
	ds_read_b64_tr_b16 v[150:151], v202 offset:25376
	ds_read_b64_tr_b16 v[154:155], v202 offset:25408
	ds_read_b64_tr_b16 v[166:167], v202 offset:25440
	v_mfma_f32_16x16x32_bf16 v[16:19], v[144:147], v[44:47], v[16:19]
	v_cvt_pk_bf16_f32 v48, v78, v120
	v_cvt_pk_bf16_f32 v49, v121, v122
	v_cvt_pk_bf16_f32 v50, v123, v124
	v_mfma_f32_16x16x32_bf16 v[44:47], v[156:159], v[44:47], v[28:31]
	v_cvt_pk_bf16_f32 v51, v125, v126
	ds_read_b128 v[144:147], v206 offset:16128
	s_nop 0
	s_waitcnt lgkmcnt(7)
	v_mfma_f32_16x16x32_bf16 v[24:27], v[160:163], v[48:51], v[0:3]
	s_nop 2
	v_add_f32_e32 v0, 0, v64
	v_mfma_f32_16x16x32_bf16 v[16:19], v[160:163], v[32:35], v[16:19]
	ds_read_b128 v[156:159], v206 offset:9216
	s_nop 0
	s_waitcnt lgkmcnt(4)
	v_mfma_f32_16x16x32_bf16 v[20:23], v[148:151], v[32:35], v[20:23]
	v_mfma_f32_16x16x32_bf16 v[28:31], v[148:151], v[48:51], v[4:7]
	ds_read_b128 v[148:151], v206 offset:9280
	ds_read_b128 v[160:163], v206 offset:11520
	s_nop 0
	s_waitcnt lgkmcnt(5)
	v_mfma_f32_16x16x32_bf16 v[8:11], v[152:155], v[32:35], v[36:39]
	s_nop 0
	v_add_f32_e32 v4, v67, v0
	v_mov_b32_e32 v67, v66
	s_nop 0
	s_waitcnt lgkmcnt(4)
	v_mfma_f32_16x16x32_bf16 v[0:3], v[164:167], v[32:35], v[44:47]
	s_nop 0
	s_nop 0
	v_mfma_f32_16x16x32_bf16 v[12:15], v[152:155], v[48:51], v[40:43]
	ds_read_b128 v[152:155], v206 offset:13824
	ds_read_b128 v[168:171], v206 offset:11584
	v_add_f32_e32 v56, v68, v4
	v_mov_b32_e32 v68, v66
	v_mfma_f32_16x16x32_bf16 v[4:7], v[164:167], v[48:51], v[52:55]
	s_nop 0
	ds_read_b128 v[164:167], v206 offset:13888
	ds_read_b128 v[172:175], v206 offset:16192
	v_xor_b32_e32 v40, 0x80000000, v79
	v_mov_b32_e32 v41, v40
	s_nop 0
	s_waitcnt lgkmcnt(5)
	v_mfma_f32_16x16x32_bf16 v[44:47], v[148:151], v[92:95], v[66:69]
	v_add_f32_e32 v36, v127, v56
	v_mov_b32_e32 v42, v40
	v_mov_b32_e32 v43, v40
	v_add_f32_e32 v52, v132, v36
	s_nop 0
	v_mfma_f32_16x16x32_bf16 v[60:63], v[156:159], v[80:83], v[40:43]
	s_nop 0
	s_nop 0
	s_waitcnt lgkmcnt(4)
	v_mfma_f32_16x16x32_bf16 v[56:59], v[160:163], v[80:83], v[40:43]
	v_add_f32_e32 v48, v133, v52
	v_add_f32_e32 v52, v134, v48
	s_nop 0
	v_add_f32_e32 v52, v135, v52
	s_nop 0
	v_add_f32_e32 v64, v136, v52
	s_nop 0
	s_waitcnt lgkmcnt(3)
	v_mfma_f32_16x16x32_bf16 v[52:55], v[152:155], v[80:83], v[40:43]
	v_add_f32_e32 v36, v137, v64
	v_add_f32_e32 v64, v138, v36
	s_nop 0
	s_waitcnt lgkmcnt(1)
	v_mfma_f32_16x16x32_bf16 v[36:39], v[164:167], v[92:95], v[66:69]
	v_add_f32_e32 v48, v139, v64
	v_add_f32_e32 v48, v140, v48
	v_add_f32_e32 v64, v141, v48
	v_mfma_f32_16x16x32_bf16 v[48:51], v[144:147], v[80:83], v[40:43]
	s_nop 2
	v_add_f32_e32 v40, v142, v64
	v_add_f32_e32 v40, v143, v40
	v_mfma_f32_16x16x32_bf16 v[32:35], v[168:171], v[92:95], v[66:69]
	v_add_f32_e32 v64, v210, v40
	s_nop 0
	s_waitcnt lgkmcnt(0)
	v_mfma_f32_16x16x32_bf16 v[40:43], v[172:175], v[92:95], v[66:69]
	s_nop 2
	v_max3_f32 v66, v62, v60, v61
	v_max3_f32 v66, v63, v66, v56
	v_max3_f32 v66, v58, v57, v66
	v_max3_f32 v66, v52, v59, v66
	v_max3_f32 v66, v54, v53, v66
	v_max3_f32 v66, v48, v55, v66
	v_max3_f32 v66, v50, v49, v66
	v_max_f32_e32 v67, v51, v51
	v_max_f32_e32 v66, v67, v66
	v_cmp_lt_f32_e32 vcc, s52, v66
	s_cbranch_vccz .LBB0_1228
	v_max_f32_e32 v66, v61, v61
	v_max_f32_e32 v67, v60, v60
	v_max_f32_e32 v66, v67, v66
	v_max3_f32 v66, v66, v62, v63
	v_max3_f32 v66, v66, v56, v57
	v_max3_f32 v66, v66, v58, v59
	v_max3_f32 v66, v66, v52, v53
	v_max3_f32 v66, v66, v54, v55
	v_max3_f32 v66, v66, v48, v49
	v_max3_f32 v66, v66, v50, v51
	v_mov_b32_e32 v67, v66
	s_nop 1
	v_permlane16_swap_b32_e32 v66, v67
	v_max_f32_e32 v67, v67, v67
	v_max_f32_e32 v66, v66, v66
	v_max_f32_e32 v66, v66, v67
	v_mov_b32_e32 v67, v66
	s_nop 1
	v_permlane32_swap_b32_e32 v66, v67
	v_max_f32_e32 v67, v67, v67
	v_max_f32_e32 v66, v66, v66
	v_max_f32_e32 v66, v66, v67
	v_cmp_lt_f32_e32 vcc, s52, v66
	s_nop 1
	v_cndmask_b32_e32 v66, 0, v66, vcc
	v_exp_f32_e64 v68, -v66
	v_add_f32_e32 v79, v79, v66
	v_pk_add_f32 v[60:61], v[60:61], v[66:67] op_sel_hi:[1,0] neg_lo:[0,1] neg_hi:[0,1]
	v_pk_add_f32 v[62:63], v[62:63], v[66:67] op_sel_hi:[1,0] neg_lo:[0,1] neg_hi:[0,1]
	v_mul_f32_e32 v64, v64, v68
	v_pk_add_f32 v[56:57], v[56:57], v[66:67] op_sel_hi:[1,0] neg_lo:[0,1] neg_hi:[0,1]
	v_pk_add_f32 v[58:59], v[58:59], v[66:67] op_sel_hi:[1,0] neg_lo:[0,1] neg_hi:[0,1]
	v_pk_add_f32 v[52:53], v[52:53], v[66:67] op_sel_hi:[1,0] neg_lo:[0,1] neg_hi:[0,1]
	v_pk_add_f32 v[54:55], v[54:55], v[66:67] op_sel_hi:[1,0] neg_lo:[0,1] neg_hi:[0,1]
	v_pk_add_f32 v[48:49], v[48:49], v[66:67] op_sel_hi:[1,0] neg_lo:[0,1] neg_hi:[0,1]
	v_pk_add_f32 v[50:51], v[50:51], v[66:67] op_sel_hi:[1,0] neg_lo:[0,1] neg_hi:[0,1]
	v_pk_mul_f32 v[2:3], v[2:3], v[68:69] op_sel_hi:[1,0]
	v_pk_mul_f32 v[0:1], v[0:1], v[68:69] op_sel_hi:[1,0]
	v_pk_mul_f32 v[10:11], v[10:11], v[68:69] op_sel_hi:[1,0]
	v_pk_mul_f32 v[8:9], v[8:9], v[68:69] op_sel_hi:[1,0]
	v_pk_mul_f32 v[22:23], v[22:23], v[68:69] op_sel_hi:[1,0]
	v_pk_mul_f32 v[20:21], v[20:21], v[68:69] op_sel_hi:[1,0]
	v_pk_mul_f32 v[18:19], v[18:19], v[68:69] op_sel_hi:[1,0]
	v_pk_mul_f32 v[16:17], v[16:17], v[68:69] op_sel_hi:[1,0]

.LBB0_1230:
	s_waitcnt lgkmcnt(0)
	ds_read_b64_tr_b16 v[122:123], v202 offset:29952
	ds_read_b64_tr_b16 v[120:121], v202 offset:27648
	ds_read_b64_tr_b16 v[124:125], v202 offset:27680
	ds_read_b64_tr_b16 v[126:127], v202 offset:29984
	ds_read_b64_tr_b16 v[128:129], v202 offset:27712
	ds_read_b64_tr_b16 v[130:131], v202 offset:30016
	ds_read_b64_tr_b16 v[132:133], v202 offset:27744
	ds_read_b64_tr_b16 v[134:135], v202 offset:30048
	v_exp_f32_e32 v60, v60
	v_exp_f32_e32 v61, v61
	v_exp_f32_e32 v62, v62
	v_exp_f32_e32 v63, v63
	v_add_f32_e32 v67, 0, v60
	v_exp_f32_e32 v56, v56
	v_add_f32_e32 v67, v61, v67
	v_exp_f32_e32 v57, v57
	v_add_f32_e32 v67, v62, v67
	v_exp_f32_e32 v58, v58
	v_add_f32_e32 v67, v63, v67
	v_exp_f32_e32 v59, v59
	v_add_f32_e32 v67, v56, v67
	v_exp_f32_e32 v52, v52
	v_add_f32_e32 v67, v57, v67
	v_exp_f32_e32 v53, v53
	v_add_f32_e32 v67, v58, v67
	v_exp_f32_e32 v54, v54
	v_add_f32_e32 v67, v59, v67
	v_exp_f32_e32 v55, v55
	v_add_f32_e32 v67, v52, v67
	v_exp_f32_e32 v48, v48
	v_add_f32_e32 v67, v53, v67
	v_exp_f32_e32 v49, v49
	v_add_f32_e32 v67, v54, v67
	v_exp_f32_e32 v50, v50
	v_add_f32_e32 v67, v55, v67
	v_exp_f32_e32 v51, v51
	v_add_f32_e32 v67, v48, v67
	v_exp_f32_e32 v44, v44
	v_add_f32_e32 v67, v49, v67
	v_exp_f32_e32 v45, v45
	v_add_f32_e32 v67, v50, v67
	v_exp_f32_e32 v46, v46
	v_add_f32_e32 v67, v51, v67
	v_exp_f32_e32 v47, v47
	v_add_f32_e32 v211, v64, v67
	v_add_f32_e32 v64, 0, v44
	v_exp_f32_e32 v67, v32
	v_add_f32_e32 v64, v45, v64
	v_add_f32_e32 v64, v46, v64
	v_add_f32_e32 v64, v47, v64
	v_add_f32_e32 v32, v67, v64
	v_exp_f32_e32 v64, v33
	v_exp_f32_e32 v68, v34
	v_exp_f32_e32 v69, v35
	v_exp_f32_e32 v70, v36
	v_add_f32_e32 v32, v64, v32
	v_exp_f32_e32 v71, v37
	v_add_f32_e32 v32, v68, v32
	v_exp_f32_e32 v72, v38
	v_add_f32_e32 v32, v69, v32
	v_exp_f32_e32 v73, v39
	v_add_f32_e32 v32, v70, v32
	v_exp_f32_e32 v40, v40
	v_add_f32_e32 v32, v71, v32
	v_exp_f32_e32 v41, v41
	v_add_f32_e32 v32, v72, v32
	v_exp_f32_e32 v42, v42
	v_add_f32_e32 v32, v73, v32
	v_exp_f32_e32 v43, v43
	v_add_f32_e32 v32, v40, v32
	v_add_f32_e32 v32, v41, v32
	v_add_f32_e32 v32, v42, v32
	v_add_f32_e32 v32, v43, v32
	v_cvt_pk_bf16_f32 v33, v62, v63
	v_cvt_pk_bf16_f32 v37, v46, v47
	v_cvt_pk_bf16_f32 v46, v48, v49
	v_cvt_pk_bf16_f32 v62, v40, v41
	v_cvt_pk_bf16_f32 v63, v42, v43
	s_nop 0
	s_nop 0
	s_nop 0
	v_add_f32_e32 v208, v66, v32
	v_cvt_pk_bf16_f32 v32, v60, v61
	v_cvt_pk_bf16_f32 v34, v56, v57
	v_cvt_pk_bf16_f32 v35, v58, v59
	v_cvt_pk_bf16_f32 v36, v44, v45
	v_cvt_pk_bf16_f32 v38, v67, v64
	v_cvt_pk_bf16_f32 v39, v68, v69
	v_cvt_pk_bf16_f32 v47, v50, v51
	s_nop 0
	s_waitcnt lgkmcnt(6)
	v_mfma_f32_16x16x32_bf16 v[16:19], v[120:123], v[32:35], v[16:19]
	s_nop 0
	v_cvt_pk_bf16_f32 v44, v52, v53
	v_cvt_pk_bf16_f32 v45, v54, v55
	v_mfma_f32_16x16x32_bf16 v[24:27], v[120:123], v[36:39], v[24:27]
	s_nop 0
	s_nop 0
	ds_read_b64_tr_b16 v[120:121], v202 offset:32256
	ds_read_b64_tr_b16 v[122:123], v202 offset:34560
	v_cvt_pk_bf16_f32 v60, v70, v71
	v_cvt_pk_bf16_f32 v61, v72, v73
	s_nop 0
	s_waitcnt lgkmcnt(4)
	v_mfma_f32_16x16x32_bf16 v[8:11], v[128:131], v[32:35], v[8:11]
	v_mov_b32_e32 v78, v207
	v_mfma_f32_16x16x32_bf16 v[12:15], v[128:131], v[36:39], v[12:15]
	s_nop 0
	s_nop 0
	ds_read_b64_tr_b16 v[128:129], v202 offset:32288
	ds_read_b64_tr_b16 v[130:131], v202 offset:34592
	v_mfma_f32_16x16x32_bf16 v[28:31], v[124:127], v[36:39], v[28:31]
	s_nop 0
	s_waitcnt lgkmcnt(4)
	v_mfma_f32_16x16x32_bf16 v[4:7], v[132:135], v[36:39], v[4:7]
	s_nop 0
	s_nop 0
	v_mfma_f32_16x16x32_bf16 v[20:23], v[124:127], v[32:35], v[20:23]
	v_mfma_f32_16x16x32_bf16 v[0:3], v[132:135], v[32:35], v[0:3]
	s_nop 0
	s_waitcnt lgkmcnt(2)
	v_mfma_f32_16x16x32_bf16 v[32:35], v[120:123], v[44:47], v[16:19]
	s_nop 2
	s_nop 0
	s_nop 0
	v_mfma_f32_16x16x32_bf16 v[48:51], v[120:123], v[60:63], v[24:27]
	s_nop 0
	s_waitcnt lgkmcnt(0)
	v_mfma_f32_16x16x32_bf16 v[36:39], v[128:131], v[44:47], v[20:23]
	v_mfma_f32_16x16x32_bf16 v[52:55], v[128:131], v[60:63], v[28:31]
	ds_read_b64_tr_b16 v[16:17], v202 offset:32320
	ds_read_b64_tr_b16 v[18:19], v202 offset:34624
	s_nop 0
	s_waitcnt lgkmcnt(0)
	v_mfma_f32_16x16x32_bf16 v[40:43], v[16:19], v[44:47], v[8:11]
	s_nop 2
	ds_read_b64_tr_b16 v[8:9], v202 offset:32352
	ds_read_b64_tr_b16 v[10:11], v202 offset:34656
	v_mfma_f32_16x16x32_bf16 v[56:59], v[16:19], v[60:63], v[12:15]
	s_nop 0
	s_waitcnt lgkmcnt(0)
	v_mfma_f32_16x16x32_bf16 v[44:47], v[8:11], v[44:47], v[0:3]
	v_mfma_f32_16x16x32_bf16 v[60:63], v[8:11], v[60:63], v[4:7]

.LBB0_1247:
	s_waitcnt lgkmcnt(0)
	ds_read_b64_tr_b16 v[242:243], v202 offset:57600
	ds_read_b64_tr_b16 v[240:241], v202 offset:55296
	ds_read_b64_tr_b16 v[244:245], v202 offset:55328
	ds_read_b64_tr_b16 v[246:247], v202 offset:57632
	ds_read_b64_tr_b16 v[248:249], v202 offset:55360
	ds_read_b64_tr_b16 v[250:251], v202 offset:57664
	v_exp_f32_e32 v176, v176
	v_exp_f32_e32 v177, v177
	v_exp_f32_e32 v178, v178
	v_exp_f32_e32 v179, v179
	v_add_f32_e32 v212, 0, v176
	v_exp_f32_e32 v168, v168
	v_add_f32_e32 v212, v177, v212
	v_exp_f32_e32 v169, v169
	v_add_f32_e32 v212, v178, v212
	v_exp_f32_e32 v170, v170
	v_add_f32_e32 v212, v179, v212
	v_exp_f32_e32 v171, v171
	v_add_f32_e32 v212, v168, v212
	v_exp_f32_e32 v172, v172
	v_add_f32_e32 v212, v169, v212
	v_exp_f32_e32 v173, v173
	v_add_f32_e32 v212, v170, v212
	v_exp_f32_e32 v174, v174
	v_exp_f32_e32 v214, v165
	v_exp_f32_e32 v165, v160
	v_add_f32_e32 v212, v171, v212
	v_exp_f32_e32 v175, v175
	v_exp_f32_e32 v215, v166
	v_exp_f32_e32 v166, v161
	v_add_f32_e32 v212, v172, v212
	v_exp_f32_e32 v213, v164
	v_exp_f32_e32 v216, v167
	v_exp_f32_e32 v167, v162
	v_add_f32_e32 v212, v173, v212
	v_add_f32_e32 v212, v174, v212
	v_add_f32_e32 v160, 0, v165
	v_add_f32_e32 v212, v175, v212
	v_add_f32_e32 v160, v166, v160
	v_add_f32_e32 v164, v213, v212
	v_add_f32_e32 v212, v167, v160
	v_exp_f32_e32 v217, v163
	v_exp_f32_e32 v218, v156
	v_exp_f32_e32 v219, v157
	v_exp_f32_e32 v220, v158
	s_nop 0
	s_nop 0
	v_exp_f32_e32 v221, v159
	v_add_f32_e32 v164, v214, v164
	v_cvt_pk_bf16_f32 v158, v168, v169
	v_cvt_pk_bf16_f32 v159, v170, v171
	s_nop 0
	s_nop 0
	v_add_f32_e32 v164, v215, v164
	v_add_f32_e32 v164, v216, v164
	v_add_f32_e32 v210, v210, v164
	v_cvt_pk_bf16_f32 v156, v176, v177
	v_cvt_pk_bf16_f32 v157, v178, v179
	v_cvt_pk_bf16_f32 v164, v165, v166
	v_cvt_pk_bf16_f32 v165, v167, v217
	v_cvt_pk_bf16_f32 v166, v218, v219
	v_cvt_pk_bf16_f32 v167, v220, v221
	s_nop 0
	s_waitcnt lgkmcnt(4)
	v_mfma_f32_16x16x32_bf16 v[0:3], v[240:243], v[156:159], v[0:3]
	v_exp_f32_e32 v176, v152
	v_exp_f32_e32 v177, v153
	v_exp_f32_e32 v178, v154
	v_mfma_f32_16x16x32_bf16 v[160:163], v[240:243], v[164:167], v[16:19]
	ds_read_b64_tr_b16 v[240:241], v202 offset:55392
	ds_read_b64_tr_b16 v[242:243], v202 offset:57696
	s_nop 2
	s_nop 0
	s_nop 0
	v_exp_f32_e32 v179, v155
	v_exp_f32_e32 v222, v148
	s_nop 0
	s_waitcnt lgkmcnt(4)
	v_mfma_f32_16x16x32_bf16 v[152:155], v[244:247], v[164:167], v[20:23]
	s_nop 2
	s_nop 0
	s_nop 0
	v_exp_f32_e32 v223, v149
	v_exp_f32_e32 v224, v150
	v_exp_f32_e32 v225, v151
	s_nop 0
	s_waitcnt lgkmcnt(2)
	v_mfma_f32_16x16x32_bf16 v[148:151], v[248:251], v[164:167], v[24:27]
	s_nop 2
	ds_read_b64_tr_b16 v[24:25], v202 offset:59904
	ds_read_b64_tr_b16 v[26:27], v202 offset:62208
	s_mov_b64 s[14:15], 0
	v_mfma_f32_16x16x32_bf16 v[4:7], v[244:247], v[156:159], v[4:7]
	ds_read_b64_tr_b16 v[244:245], v202 offset:59936
	ds_read_b64_tr_b16 v[246:247], v202 offset:62240
	v_cvt_pk_bf16_f32 v168, v172, v173
	v_cvt_pk_bf16_f32 v169, v174, v175
	v_cvt_pk_bf16_f32 v170, v213, v214
	v_mfma_f32_16x16x32_bf16 v[8:11], v[248:251], v[156:159], v[8:11]
	ds_read_b64_tr_b16 v[248:249], v202 offset:59968
	ds_read_b64_tr_b16 v[250:251], v202 offset:62272
	v_cvt_pk_bf16_f32 v171, v215, v216
	s_nop 0
	s_waitcnt lgkmcnt(6)
	v_mfma_f32_16x16x32_bf16 v[12:15], v[240:243], v[156:159], v[12:15]
	v_mfma_f32_16x16x32_bf16 v[156:159], v[240:243], v[164:167], v[28:31]
	ds_read_b64_tr_b16 v[240:241], v202 offset:60000
	ds_read_b64_tr_b16 v[242:243], v202 offset:62304
	s_nop 2
	s_nop 0
	s_nop 0
	v_cvt_pk_bf16_f32 v164, v176, v177
	v_cvt_pk_bf16_f32 v165, v178, v179
	v_cvt_pk_bf16_f32 v166, v222, v223
	v_cvt_pk_bf16_f32 v167, v224, v225
	s_nop 0
	s_waitcnt lgkmcnt(6)
	v_mfma_f32_16x16x32_bf16 v[16:19], v[24:27], v[168:171], v[0:3]
	v_mfma_f32_16x16x32_bf16 v[0:3], v[24:27], v[164:167], v[160:163]
	v_add_f32_e32 v24, v217, v212
	s_nop 1
	s_nop 0
	s_nop 0
	s_nop 0
	s_waitcnt lgkmcnt(4)
	v_mfma_f32_16x16x32_bf16 v[20:23], v[244:247], v[168:171], v[4:7]
	s_nop 2
	v_add_f32_e32 v4, v218, v24
	v_add_f32_e32 v4, v219, v4
	v_add_f32_e32 v24, v220, v4
	v_mfma_f32_16x16x32_bf16 v[4:7], v[244:247], v[164:167], v[152:155]
	v_add_f32_e32 v28, v221, v24
	s_nop 1
	s_nop 0
	s_nop 0
	s_nop 0
	s_waitcnt lgkmcnt(2)
	v_mfma_f32_16x16x32_bf16 v[24:27], v[248:251], v[168:171], v[8:11]
	s_nop 2
	v_add_f32_e32 v8, v176, v28
	v_add_f32_e32 v8, v177, v8
	v_add_f32_e32 v28, v178, v8
	v_add_f32_e32 v28, v179, v28
	v_add_f32_e32 v28, v222, v28
	v_mfma_f32_16x16x32_bf16 v[8:11], v[248:251], v[164:167], v[148:151]
	s_nop 2
	v_add_f32_e32 v148, v223, v28
	s_nop 0
	s_waitcnt lgkmcnt(0)
	v_mfma_f32_16x16x32_bf16 v[28:31], v[240:243], v[168:171], v[12:15]
	s_nop 2
	v_add_f32_e32 v12, v224, v148
	v_add_f32_e32 v12, v225, v12
	v_add_f32_e32 v209, v209, v12
	v_mfma_f32_16x16x32_bf16 v[12:15], v[240:243], v[164:167], v[156:159]

.LBB0_1254:
	s_waitcnt lgkmcnt(0)
	ds_read_b64_tr_b16 v[150:151], v202 offset:57600
	ds_read_b64_tr_b16 v[148:149], v202 offset:55296
	ds_read_b64_tr_b16 v[152:153], v202 offset:55328
	ds_read_b64_tr_b16 v[154:155], v202 offset:57632
	ds_read_b64_tr_b16 v[156:157], v202 offset:55360
	ds_read_b64_tr_b16 v[158:159], v202 offset:57664
	ds_read_b64_tr_b16 v[160:161], v202 offset:55392
	ds_read_b64_tr_b16 v[162:163], v202 offset:57696
	v_exp_f32_e32 v28, v28
	v_exp_f32_e32 v29, v29
	v_exp_f32_e32 v30, v30
	v_exp_f32_e32 v31, v31
	v_add_f32_e32 v67, 0, v28
	v_exp_f32_e32 v24, v24
	v_add_f32_e32 v67, v29, v67
	v_exp_f32_e32 v25, v25
	v_add_f32_e32 v67, v30, v67
	v_exp_f32_e32 v26, v26
	v_add_f32_e32 v67, v31, v67
	v_exp_f32_e32 v27, v27
	v_add_f32_e32 v67, v24, v67
	v_exp_f32_e32 v20, v20
	v_add_f32_e32 v67, v25, v67
	v_exp_f32_e32 v21, v21
	v_add_f32_e32 v67, v26, v67
	v_exp_f32_e32 v22, v22
	v_add_f32_e32 v67, v27, v67
	v_exp_f32_e32 v23, v23
	v_add_f32_e32 v67, v20, v67
	v_exp_f32_e32 v16, v16
	v_add_f32_e32 v67, v21, v67
	v_exp_f32_e32 v17, v17
	v_add_f32_e32 v67, v22, v67
	v_exp_f32_e32 v18, v18
	v_add_f32_e32 v67, v23, v67
	v_exp_f32_e32 v19, v19
	v_add_f32_e32 v67, v16, v67
	v_add_f32_e32 v67, v17, v67
	v_add_f32_e32 v67, v18, v67
	v_add_f32_e32 v67, v19, v67
	v_exp_f32_e32 v75, v12
	v_exp_f32_e32 v76, v13
	v_exp_f32_e32 v77, v14
	v_exp_f32_e32 v79, v15
	v_exp_f32_e32 v130, v2
	v_exp_f32_e32 v131, v3
	v_cvt_pk_bf16_f32 v2, v16, v17
	v_cvt_pk_bf16_f32 v3, v18, v19
	s_nop 0
	s_nop 0
	s_nop 0
	s_nop 0
	v_exp_f32_e32 v120, v8
	v_exp_f32_e32 v121, v9
	v_exp_f32_e32 v122, v10
	v_exp_f32_e32 v123, v11
	v_exp_f32_e32 v124, v4
	v_exp_f32_e32 v125, v5
	v_exp_f32_e32 v126, v6
	v_exp_f32_e32 v127, v7
	v_cvt_pk_bf16_f32 v4, v28, v29
	v_cvt_pk_bf16_f32 v5, v30, v31
	v_cvt_pk_bf16_f32 v6, v24, v25
	v_cvt_pk_bf16_f32 v7, v26, v27
	v_cvt_pk_bf16_f32 v8, v75, v76
	v_cvt_pk_bf16_f32 v9, v77, v79
	v_cvt_pk_bf16_f32 v10, v120, v121
	v_cvt_pk_bf16_f32 v11, v122, v123
	v_exp_f32_e32 v128, v0
	v_exp_f32_e32 v129, v1
	v_cvt_pk_bf16_f32 v0, v20, v21
	v_cvt_pk_bf16_f32 v1, v22, v23
	s_nop 0
	s_waitcnt lgkmcnt(6)
	v_mfma_f32_16x16x32_bf16 v[20:23], v[148:151], v[4:7], v[32:35]
	v_cvt_pk_bf16_f32 v70, v124, v125
	v_cvt_pk_bf16_f32 v71, v126, v127
	v_cvt_pk_bf16_f32 v72, v128, v129
	s_nop 0
	s_waitcnt lgkmcnt(4)
	v_mfma_f32_16x16x32_bf16 v[24:27], v[152:155], v[4:7], v[36:39]
	v_cvt_pk_bf16_f32 v73, v130, v131
	v_add_f32_e32 v74, v211, v67
	v_mov_b32_e32 v67, v66
	v_mfma_f32_16x16x32_bf16 v[32:35], v[152:155], v[8:11], v[52:55]
	s_nop 0
	s_nop 0
	ds_read_b64_tr_b16 v[152:153], v202 offset:59904
	ds_read_b64_tr_b16 v[154:155], v202 offset:62208
	v_mov_b32_e32 v68, v66
	v_mov_b32_e32 v69, v66
	s_nop 0
	s_waitcnt lgkmcnt(4)
	v_mfma_f32_16x16x32_bf16 v[36:39], v[156:159], v[4:7], v[40:43]
	v_mfma_f32_16x16x32_bf16 v[40:43], v[156:159], v[8:11], v[56:59]
	s_nop 0
	s_nop 0
	ds_read_b64_tr_b16 v[156:157], v202 offset:59936
	ds_read_b64_tr_b16 v[158:159], v202 offset:62240
	v_mfma_f32_16x16x32_bf16 v[12:15], v[148:151], v[8:11], v[48:51]
	ds_read_b64_tr_b16 v[148:149], v202 offset:59968
	ds_read_b64_tr_b16 v[150:151], v202 offset:62272
	s_nop 0
	s_waitcnt lgkmcnt(6)
	v_mfma_f32_16x16x32_bf16 v[4:7], v[160:163], v[4:7], v[44:47]
	v_mfma_f32_16x16x32_bf16 v[44:47], v[160:163], v[8:11], v[60:63]
	s_nop 0
	s_nop 0
	ds_read_b64_tr_b16 v[160:161], v202 offset:60000
	ds_read_b64_tr_b16 v[162:163], v202 offset:62304
	s_nop 0
	s_waitcnt lgkmcnt(6)
	v_mfma_f32_16x16x32_bf16 v[20:23], v[152:155], v[0:3], v[20:23]
	v_mfma_f32_16x16x32_bf16 v[16:19], v[152:155], v[70:73], v[12:15]
	s_nop 0
	s_nop 0
	ds_read_b128 v[152:155], v206 offset:46080
	ds_read_b128 v[164:167], v206 offset:46144
	s_nop 0
	s_waitcnt lgkmcnt(6)
	v_mfma_f32_16x16x32_bf16 v[28:31], v[156:159], v[0:3], v[24:27]
	v_mfma_f32_16x16x32_bf16 v[24:27], v[156:159], v[70:73], v[32:35]
	s_nop 0
	s_nop 0
	ds_read_b128 v[156:159], v206 offset:48384
	ds_read_b128 v[168:171], v206 offset:48448
	s_nop 0
	s_nop 0
	s_nop 0
	s_nop 0
	s_waitcnt lgkmcnt(6)
	v_mfma_f32_16x16x32_bf16 v[12:15], v[148:151], v[0:3], v[36:39]
	s_nop 0
	s_waitcnt lgkmcnt(4)
	v_mfma_f32_16x16x32_bf16 v[4:7], v[160:163], v[0:3], v[4:7]
	v_mfma_f32_16x16x32_bf16 v[0:3], v[160:163], v[70:73], v[44:47]
	s_nop 0
	s_nop 0
	ds_read_b128 v[160:163], v206 offset:50688
	ds_read_b128 v[172:175], v206 offset:50752
	s_nop 0
	v_xor_b32_e32 v44, 0x80000000, v64
	v_mov_b32_e32 v45, v44
	v_mov_b32_e32 v46, v44
	v_mov_b32_e32 v47, v44
	v_mfma_f32_16x16x32_bf16 v[8:11], v[148:151], v[70:73], v[40:43]
	ds_read_b128 v[148:151], v206 offset:52992
	s_nop 0
	s_waitcnt lgkmcnt(6)
	v_mfma_f32_16x16x32_bf16 v[48:51], v[152:155], v[80:83], v[44:47]
	s_nop 0
	s_waitcnt lgkmcnt(5)
	v_mfma_f32_16x16x32_bf16 v[32:35], v[164:167], v[92:95], v[66:69]
	s_nop 0
	s_nop 0
	s_nop 0
	s_waitcnt lgkmcnt(4)
	v_mfma_f32_16x16x32_bf16 v[52:55], v[156:159], v[80:83], v[44:47]
	s_nop 0
	s_waitcnt lgkmcnt(3)
	v_mfma_f32_16x16x32_bf16 v[36:39], v[168:171], v[92:95], v[66:69]
	s_nop 0
	s_nop 0
	s_nop 0
	s_waitcnt lgkmcnt(2)
	v_mfma_f32_16x16x32_bf16 v[56:59], v[160:163], v[80:83], v[44:47]
	s_nop 0
	s_waitcnt lgkmcnt(1)
	v_mfma_f32_16x16x32_bf16 v[40:43], v[172:175], v[92:95], v[66:69]
	s_nop 0
	ds_read_b128 v[70:73], v206 offset:53056
	s_nop 0
	s_waitcnt lgkmcnt(1)
	v_mfma_f32_16x16x32_bf16 v[60:63], v[148:151], v[80:83], v[44:47]
	s_nop 0
	s_waitcnt lgkmcnt(0)
	v_mfma_f32_16x16x32_bf16 v[44:47], v[70:73], v[92:95], v[66:69]
	s_nop 2
	v_max3_f32 v66, v50, v48, v49
	v_max3_f32 v66, v51, v66, v52
	v_max3_f32 v66, v54, v53, v66
	v_max3_f32 v66, v56, v55, v66
	v_max3_f32 v66, v58, v57, v66
	v_max3_f32 v66, v60, v59, v66
	v_max3_f32 v66, v62, v61, v66
	v_max_f32_e32 v67, v63, v63
	v_max_f32_e32 v66, v67, v66
	v_cmp_lt_f32_e32 vcc, s52, v66
	s_cbranch_vccz .LBB0_1256
	v_max_f32_e32 v66, v49, v49
	v_max_f32_e32 v67, v48, v48
	v_max_f32_e32 v66, v67, v66
	v_max3_f32 v66, v66, v50, v51
	v_max3_f32 v66, v66, v52, v53
	v_max3_f32 v66, v66, v54, v55
	v_max3_f32 v66, v66, v56, v57
	v_max3_f32 v66, v66, v58, v59
	v_max3_f32 v66, v66, v60, v61
	v_max3_f32 v66, v66, v62, v63
	v_mov_b32_e32 v67, v66
	s_nop 1
	v_permlane16_swap_b32_e32 v66, v67
	v_max_f32_e32 v67, v67, v67
	v_max_f32_e32 v66, v66, v66
	v_max_f32_e32 v66, v66, v67
	v_mov_b32_e32 v67, v66
	s_nop 1
	v_permlane32_swap_b32_e32 v66, v67
	v_max_f32_e32 v67, v67, v67
	v_max_f32_e32 v66, v66, v66
	v_max_f32_e32 v66, v66, v67
	v_cmp_lt_f32_e32 vcc, s52, v66
	s_nop 1
	v_cndmask_b32_e32 v66, 0, v66, vcc
	v_exp_f32_e64 v68, -v66
	v_add_f32_e32 v64, v64, v66
	v_pk_add_f32 v[48:49], v[48:49], v[66:67] op_sel_hi:[1,0] neg_lo:[0,1] neg_hi:[0,1]
	v_pk_add_f32 v[50:51], v[50:51], v[66:67] op_sel_hi:[1,0] neg_lo:[0,1] neg_hi:[0,1]
	v_mul_f32_e32 v74, v74, v68
	v_pk_add_f32 v[52:53], v[52:53], v[66:67] op_sel_hi:[1,0] neg_lo:[0,1] neg_hi:[0,1]
	v_pk_add_f32 v[54:55], v[54:55], v[66:67] op_sel_hi:[1,0] neg_lo:[0,1] neg_hi:[0,1]
	v_pk_add_f32 v[56:57], v[56:57], v[66:67] op_sel_hi:[1,0] neg_lo:[0,1] neg_hi:[0,1]
	v_pk_add_f32 v[58:59], v[58:59], v[66:67] op_sel_hi:[1,0] neg_lo:[0,1] neg_hi:[0,1]
	v_pk_add_f32 v[60:61], v[60:61], v[66:67] op_sel_hi:[1,0] neg_lo:[0,1] neg_hi:[0,1]
	v_pk_add_f32 v[62:63], v[62:63], v[66:67] op_sel_hi:[1,0] neg_lo:[0,1] neg_hi:[0,1]
	v_pk_mul_f32 v[6:7], v[6:7], v[68:69] op_sel_hi:[1,0]
	v_pk_mul_f32 v[4:5], v[4:5], v[68:69] op_sel_hi:[1,0]
	v_pk_mul_f32 v[14:15], v[14:15], v[68:69] op_sel_hi:[1,0]
	v_pk_mul_f32 v[12:13], v[12:13], v[68:69] op_sel_hi:[1,0]
	v_pk_mul_f32 v[30:31], v[30:31], v[68:69] op_sel_hi:[1,0]
	v_pk_mul_f32 v[28:29], v[28:29], v[68:69] op_sel_hi:[1,0]
	v_pk_mul_f32 v[22:23], v[22:23], v[68:69] op_sel_hi:[1,0]
	v_pk_mul_f32 v[20:21], v[20:21], v[68:69] op_sel_hi:[1,0]
